# attention lazy softmax rescale (threshold 8 log2 units); removed redundant NaN-canonicalizing v_max ops in PEER score sort networks
# speedup vs baseline: 1.1596x; 1.0137x over previous
; DEV f32x4 mfma16(bf16x8 a, bf16x8 b, f32x4 c) { return __builtin_amdgcn_mfma_f32_16x16x32_bf16(a, b, c, 0, 0, 0); }
; DEV void peer_top16(const bf16_t* __restrict__ pq, const bf16_t* sk  , float (&l)[16]) {
;     ...
;   f32x4 acc[8];
; #pragma unroll
;   for (int nt = 0; nt < 8; nt++) acc[nt] = (f32x4){0.f, 0.f, 0.f, 0.f};
; #pragma unroll 1
;   for (int ks = 0; ks < 4; ks++) {
;     const bf16x8 bqk = *(const bf16x8*)(pq + ks * 32 + quad * 8);
; #pragma unroll
;     for (int nt = 0; nt < 8; nt++) {
;       bf16x8 ak = *(const bf16x8*)(sk + (nt * 16 + l15) * 144 + ks * 32 + quad * 8);
;       acc[nt] = mfma16(ak, bqk, acc[nt]);
;     }
;   }
;   float hi[16];
; #pragma unroll
;   for (int nt = 0; nt < 4; nt++)
; #pragma unroll
;     for (int r = 0; r < 4; r++) {
;       l[nt * 4 + r] = __uint_as_float((__float_as_uint(acc[nt][r]) & ~127u) | (unsigned)(nt * 16 + quad * 4 + r));
;       hi[nt * 4 + r] = __uint_as_float((__float_as_uint(acc[nt + 4][r]) & ~127u) | (unsigned)((nt + 4) * 16 + quad * 4 + r));
;     }
;   sort16_desc(l);
;   sort16_desc(hi);
.LBB0_168:
	global_load_dwordx4 v[104:107], v[102:103], off
	v_add_u32_e32 v43, s0, v39
	ds_read_b128 v[108:111], v43
	s_add_i32 s0, s0, 64
	v_lshl_add_u64 v[102:103], v[102:103], 0, 64
	s_cmpk_lg_i32 s0, 0x100
	s_waitcnt vmcnt(0) lgkmcnt(0)
	v_mfma_f32_16x16x32_bf16 v[30:33], v[108:111], v[104:107], v[30:33]
	ds_read_b128 v[108:111], v43 offset:4608
	s_waitcnt lgkmcnt(0)
	v_mfma_f32_16x16x32_bf16 v[22:25], v[108:111], v[104:107], v[22:25]
	ds_read_b128 v[108:111], v43 offset:9216
	s_waitcnt lgkmcnt(0)
	v_mfma_f32_16x16x32_bf16 v[14:17], v[108:111], v[104:107], v[14:17]
	ds_read_b128 v[108:111], v43 offset:13824
	s_waitcnt lgkmcnt(0)
	v_mfma_f32_16x16x32_bf16 v[6:9], v[108:111], v[104:107], v[6:9]
	ds_read_b128 v[108:111], v43 offset:18432
	s_waitcnt lgkmcnt(0)
	v_mfma_f32_16x16x32_bf16 v[26:29], v[108:111], v[104:107], v[26:29]
	ds_read_b128 v[108:111], v43 offset:23040
	s_waitcnt lgkmcnt(0)
	v_mfma_f32_16x16x32_bf16 v[18:21], v[108:111], v[104:107], v[18:21]
	ds_read_b128 v[108:111], v43 offset:27648
	s_waitcnt lgkmcnt(0)
	v_mfma_f32_16x16x32_bf16 v[10:13], v[108:111], v[104:107], v[10:13]
	ds_read_b128 v[108:111], v43 offset:32256
	s_waitcnt lgkmcnt(0)
	v_mfma_f32_16x16x32_bf16 v[2:5], v[108:111], v[104:107], v[2:5]
	s_cbranch_scc1 .LBB0_168
	v_lshlrev_b32_e32 v0, 2, v0
	s_movk_i32 s0, 0xff80
	v_and_or_b32 v30, v30, s0, v0
	v_and_b32_e32 v27, 0xffffff80, v27
	s_movk_i32 s0, 0x41
	v_or3_b32 v27, v0, v27, s0
	v_and_b32_e32 v28, 0xffffff80, v28
	s_movk_i32 s0, 0x42
	v_or3_b32 v28, v0, v28, s0
	v_and_b32_e32 v29, 0xffffff80, v29
	s_movk_i32 s0, 0x43
	v_or3_b32 v29, v0, v29, s0
	v_and_b32_e32 v18, 0xffffff80, v18
	s_movk_i32 s0, 0x50
	v_or3_b32 v18, v0, v18, s0
	v_and_b32_e32 v19, 0xffffff80, v19
	s_movk_i32 s0, 0x51
	v_or3_b32 v19, v0, v19, s0
	v_and_b32_e32 v20, 0xffffff80, v20
	s_movk_i32 s0, 0x52
	v_or3_b32 v20, v0, v20, s0
	v_and_b32_e32 v21, 0xffffff80, v21
	s_movk_i32 s0, 0x53
	v_or3_b32 v21, v0, v21, s0
	v_and_b32_e32 v10, 0xffffff80, v10
	s_movk_i32 s0, 0x60
	v_or3_b32 v10, v0, v10, s0
	v_and_b32_e32 v11, 0xffffff80, v11
	s_movk_i32 s0, 0x61
	v_or3_b32 v11, v0, v11, s0
	v_and_b32_e32 v12, 0xffffff80, v12
	s_movk_i32 s0, 0x62
	v_or3_b32 v12, v0, v12, s0
	v_and_b32_e32 v13, 0xffffff80, v13
	s_movk_i32 s0, 0x63
	v_or3_b32 v13, v0, v13, s0
	v_and_b32_e32 v2, 0xffffff80, v2
	s_movk_i32 s0, 0x70
	v_or3_b32 v2, v0, v2, s0
	v_and_b32_e32 v3, 0xffffff80, v3
	s_movk_i32 s0, 0x71
	v_and_b32_e32 v26, 0xffffff80, v26
	v_and_b32_e32 v31, 0xffffff80, v31
	v_or3_b32 v3, v0, v3, s0
	v_and_b32_e32 v4, 0xffffff80, v4
	s_movk_i32 s0, 0x72
	v_or3_b32 v26, v0, v26, 64
	v_or3_b32 v31, v0, v31, 1
	v_and_b32_e32 v32, 0xffffff80, v32
	v_and_b32_e32 v33, 0xffffff80, v33
	v_and_b32_e32 v22, 0xffffff80, v22
	v_and_b32_e32 v23, 0xffffff80, v23
	v_and_b32_e32 v24, 0xffffff80, v24
	v_and_b32_e32 v25, 0xffffff80, v25
	v_and_b32_e32 v14, 0xffffff80, v14
	v_and_b32_e32 v15, 0xffffff80, v15
	v_and_b32_e32 v16, 0xffffff80, v16
	v_and_b32_e32 v17, 0xffffff80, v17
	v_and_b32_e32 v6, 0xffffff80, v6
	v_and_b32_e32 v7, 0xffffff80, v7
	v_and_b32_e32 v8, 0xffffff80, v8
	v_or3_b32 v4, v0, v4, s0
	v_and_b32_e32 v9, 0xffffff80, v9
	v_and_b32_e32 v5, 0xffffff80, v5
	s_movk_i32 s0, 0x73
	v_or3_b32 v32, v0, v32, 2
	v_or3_b32 v33, v0, v33, 3
	v_or3_b32 v22, v0, v22, 16
	v_or3_b32 v23, v0, v23, 17
	v_or3_b32 v24, v0, v24, 18
	v_or3_b32 v25, v0, v25, 19
	v_or3_b32 v14, v0, v14, 32
	v_or3_b32 v15, v0, v15, 33
	v_or3_b32 v16, v0, v16, 34
	v_or3_b32 v17, v0, v17, 35
	v_or3_b32 v6, v0, v6, 48
	v_or3_b32 v7, v0, v7, 49
	v_or3_b32 v8, v0, v8, 50
	v_or3_b32 v9, v0, v9, 51
	v_or3_b32 v0, v0, v5, s0
	v_max_f32_e32 v5, v31, v31
	v_max_f32_e32 v31, v30, v5
	v_min_f32_e32 v5, v30, v5
	v_max_f32_e32 v30, v32, v32
	v_max_f32_e32 v32, v33, v33
	v_max_f32_e32 v67, v26, v27
	v_min_f32_e32 v26, v26, v27
	v_max_f32_e32 v27, v28, v28
	v_max_f32_e32 v28, v29, v29
	v_max_f32_e32 v33, v32, v30
	v_min_f32_e32 v30, v32, v30
	v_max_f32_e32 v32, v22, v23
	v_min_f32_e32 v22, v22, v23
	v_max_f32_e32 v23, v24, v24
	v_max_f32_e32 v24, v25, v25
	v_max_f32_e32 v29, v28, v27
	v_min_f32_e32 v27, v28, v27
	v_max_f32_e32 v28, v18, v19
	v_min_f32_e32 v18, v18, v19
	v_max_f32_e32 v19, v20, v20
	v_max_f32_e32 v20, v21, v21
	v_max_f32_e32 v25, v24, v23
	v_min_f32_e32 v23, v24, v23
	v_max_f32_e32 v24, v14, v15
	v_min_f32_e32 v14, v14, v15
	v_max_f32_e32 v15, v16, v16
	v_max_f32_e32 v16, v17, v17
	v_max_f32_e32 v21, v20, v19
	v_min_f32_e32 v19, v20, v19
	v_max_f32_e32 v20, v10, v11
	v_min_f32_e32 v10, v10, v11
	v_max_f32_e32 v11, v12, v12
	v_max_f32_e32 v12, v13, v13
	v_max_f32_e32 v17, v16, v15
	v_min_f32_e32 v15, v16, v15
	v_max_f32_e32 v16, v6, v7
	v_min_f32_e32 v6, v6, v7
	v_max_f32_e32 v7, v8, v8
	v_max_f32_e32 v8, v9, v9
	v_max_f32_e32 v13, v12, v11
	v_min_f32_e32 v11, v12, v11
	v_max_f32_e32 v12, v2, v3
	v_min_f32_e32 v2, v2, v3
	v_max_f32_e32 v3, v4, v4
	v_max_f32_e32 v9, v8, v7
	v_min_f32_e32 v7, v8, v7
	v_max_f32_e32 v4, v0, v3
	v_min_f32_e32 v0, v0, v3
	v_max_f32_e32 v8, v31, v30
	v_min_f32_e32 v30, v31, v30
	v_max_f32_e32 v31, v5, v33
	v_min_f32_e32 v5, v5, v33
	v_max_f32_e32 v33, v23, v32
	v_min_f32_e32 v23, v23, v32
	v_max_f32_e32 v32, v25, v22
	v_min_f32_e32 v22, v25, v22
	v_max_f32_e32 v25, v24, v15
	v_min_f32_e32 v15, v24, v15
	v_max_f32_e32 v24, v14, v17
	v_min_f32_e32 v14, v14, v17
	v_max_f32_e32 v17, v7, v16
	v_min_f32_e32 v7, v7, v16
	v_max_f32_e32 v16, v9, v6
	v_min_f32_e32 v6, v9, v6
	v_max_f32_e32 v3, v67, v27
	v_min_f32_e32 v27, v67, v27
	v_max_f32_e32 v67, v26, v29
	v_min_f32_e32 v26, v26, v29
	v_max_f32_e32 v29, v19, v28
	v_min_f32_e32 v19, v19, v28
	v_max_f32_e32 v28, v21, v18
	v_min_f32_e32 v18, v21, v18
; DEV void ce(float& a, float& b) { float hi = fmaxf(a, b), lo = fminf(a, b); a = hi; b = lo; }
; DEV void sort16_desc(float (&a)[16]) {
; #pragma unroll
;   for (int k = 2; k <= 16; k <<= 1)
; #pragma unroll
;     for (int j = k >> 1; j > 0; j >>= 1)
; #pragma unroll
;       for (int i = 0; i < 16; i++) {
;         const int p = i ^ j;
;         if (p > i) { if ((i & k) == 0) ce(a[i], a[p]); else ce(a[p], a[i]); }
;       }
; }
	v_max_f32_e32 v21, v20, v11
	v_min_f32_e32 v11, v20, v11
	v_max_f32_e32 v20, v10, v13
	v_min_f32_e32 v10, v10, v13
	v_max_f32_e32 v13, v0, v12
	v_min_f32_e32 v0, v0, v12
	v_max_f32_e32 v12, v4, v2
	v_min_f32_e32 v2, v4, v2
	v_max_f32_e32 v9, v8, v31
	v_min_f32_e32 v8, v8, v31
	v_max_f32_e32 v31, v30, v5
	v_min_f32_e32 v5, v30, v5
	v_max_f32_e32 v30, v22, v23
	v_min_f32_e32 v22, v22, v23
	v_max_f32_e32 v23, v32, v33
	v_min_f32_e32 v32, v32, v33
	v_max_f32_e32 v33, v25, v24
	v_min_f32_e32 v24, v25, v24
	v_max_f32_e32 v25, v15, v14
	v_min_f32_e32 v14, v15, v14
	v_max_f32_e32 v15, v6, v7
	v_min_f32_e32 v6, v6, v7
	v_max_f32_e32 v7, v16, v17
	v_min_f32_e32 v16, v16, v17
	v_max_f32_e32 v4, v3, v67
	v_min_f32_e32 v3, v3, v67
	v_max_f32_e32 v67, v27, v26
	v_min_f32_e32 v26, v27, v26
	v_max_f32_e32 v27, v18, v19
	v_min_f32_e32 v18, v18, v19
	v_max_f32_e32 v19, v28, v29
	v_min_f32_e32 v28, v28, v29
	v_max_f32_e32 v29, v21, v20
	v_min_f32_e32 v20, v21, v20
	v_max_f32_e32 v21, v11, v10
	v_min_f32_e32 v10, v11, v10
	v_max_f32_e32 v11, v2, v0
	v_min_f32_e32 v0, v2, v0
	v_max_f32_e32 v2, v12, v13
	v_min_f32_e32 v12, v12, v13
	v_max_f32_e32 v17, v9, v22
	v_min_f32_e32 v9, v9, v22
	v_max_f32_e32 v22, v8, v30
	v_min_f32_e32 v8, v8, v30
	v_max_f32_e32 v30, v31, v32
	v_min_f32_e32 v31, v31, v32
	v_max_f32_e32 v32, v5, v23
	v_min_f32_e32 v5, v5, v23
	v_max_f32_e32 v23, v6, v33
	v_min_f32_e32 v6, v6, v33
	v_max_f32_e32 v33, v15, v24
	v_min_f32_e32 v15, v15, v24
	v_max_f32_e32 v24, v16, v25
	v_min_f32_e32 v16, v16, v25
	v_max_f32_e32 v25, v7, v14
	v_min_f32_e32 v7, v7, v14
	v_max_f32_e32 v13, v4, v18
	v_min_f32_e32 v4, v4, v18
	v_max_f32_e32 v18, v3, v27
	v_min_f32_e32 v3, v3, v27
	v_max_f32_e32 v27, v67, v28
	v_min_f32_e32 v28, v67, v28
	v_max_f32_e32 v67, v26, v19
	v_min_f32_e32 v19, v26, v19
	v_max_f32_e32 v26, v0, v29
	v_min_f32_e32 v0, v0, v29
	v_max_f32_e32 v29, v11, v20
	v_min_f32_e32 v11, v11, v20
	v_max_f32_e32 v20, v12, v21
	v_min_f32_e32 v12, v12, v21
	v_max_f32_e32 v21, v2, v10
	v_min_f32_e32 v2, v2, v10
	v_max_f32_e32 v14, v17, v30
	v_min_f32_e32 v17, v17, v30
	v_max_f32_e32 v30, v22, v32
	v_min_f32_e32 v22, v22, v32
	v_max_f32_e32 v32, v9, v31
	v_min_f32_e32 v9, v9, v31
	v_max_f32_e32 v31, v8, v5
	v_min_f32_e32 v5, v8, v5
	v_max_f32_e32 v8, v16, v6
	v_min_f32_e32 v6, v16, v6
	v_max_f32_e32 v16, v7, v15
	v_min_f32_e32 v7, v7, v15
	v_max_f32_e32 v15, v24, v23
	v_min_f32_e32 v23, v24, v23
	v_max_f32_e32 v24, v25, v33
	v_min_f32_e32 v25, v25, v33
	v_max_f32_e32 v10, v13, v27
	v_min_f32_e32 v13, v13, v27
	v_max_f32_e32 v27, v18, v67
	v_min_f32_e32 v18, v18, v67
	v_max_f32_e32 v67, v4, v28
	v_min_f32_e32 v4, v4, v28
	v_max_f32_e32 v28, v3, v19
	v_min_f32_e32 v3, v3, v19
	v_max_f32_e32 v19, v12, v0
	v_min_f32_e32 v0, v12, v0
	v_max_f32_e32 v12, v2, v11
	v_min_f32_e32 v2, v2, v11
	v_max_f32_e32 v11, v20, v26
	v_min_f32_e32 v20, v20, v26
	v_max_f32_e32 v26, v21, v29
	v_min_f32_e32 v21, v21, v29
	v_max_f32_e32 v33, v14, v30
	v_min_f32_e32 v14, v14, v30
	v_max_f32_e32 v30, v17, v22
	v_min_f32_e32 v17, v17, v22
	v_max_f32_e32 v22, v32, v31
	v_min_f32_e32 v31, v32, v31
	v_max_f32_e32 v32, v9, v5
	v_min_f32_e32 v5, v9, v5
	v_max_f32_e32 v9, v7, v6
	v_min_f32_e32 v6, v7, v6
	v_max_f32_e32 v7, v16, v8
	v_min_f32_e32 v8, v16, v8
	v_max_f32_e32 v16, v25, v23
	v_min_f32_e32 v23, v25, v23
	v_max_f32_e32 v25, v24, v15
	v_min_f32_e32 v15, v24, v15
	v_max_f32_e32 v29, v10, v27
	v_min_f32_e32 v10, v10, v27
	v_max_f32_e32 v27, v13, v18
	v_min_f32_e32 v13, v13, v18
	v_max_f32_e32 v18, v67, v28
	v_min_f32_e32 v28, v67, v28
	v_max_f32_e32 v67, v4, v3
	v_min_f32_e32 v3, v4, v3
	v_max_f32_e32 v4, v2, v0
	v_min_f32_e32 v0, v2, v0
	v_max_f32_e32 v2, v12, v19
	v_min_f32_e32 v12, v12, v19
	v_max_f32_e32 v19, v21, v20
	v_min_f32_e32 v20, v21, v20
	v_max_f32_e32 v21, v26, v11
	v_min_f32_e32 v11, v26, v11
	v_max_f32_e32 v24, v33, v6
	v_min_f32_e32 v6, v33, v6
	v_max_f32_e32 v33, v14, v9
	v_min_f32_e32 v9, v14, v9
	v_max_f32_e32 v14, v30, v8
	v_min_f32_e32 v8, v30, v8
	v_max_f32_e32 v30, v17, v7
	v_min_f32_e32 v7, v17, v7
	v_max_f32_e32 v17, v22, v23
	v_min_f32_e32 v22, v22, v23
	v_max_f32_e32 v23, v31, v16
	v_min_f32_e32 v16, v31, v16
	v_max_f32_e32 v31, v32, v15
	v_min_f32_e32 v15, v32, v15
	v_max_f32_e32 v32, v5, v25
	v_min_f32_e32 v5, v5, v25
	v_max_f32_e32 v26, v29, v0
	v_min_f32_e32 v0, v29, v0
	v_max_f32_e32 v29, v10, v4
	v_min_f32_e32 v4, v10, v4
	v_max_f32_e32 v10, v27, v12
	v_min_f32_e32 v12, v27, v12
	v_max_f32_e32 v27, v13, v2
	v_min_f32_e32 v2, v13, v2
	v_max_f32_e32 v13, v18, v20
	v_min_f32_e32 v18, v18, v20
	v_max_f32_e32 v20, v28, v19
	v_min_f32_e32 v19, v28, v19
	v_max_f32_e32 v28, v67, v11
	v_min_f32_e32 v11, v67, v11
	v_max_f32_e32 v67, v3, v21
	v_min_f32_e32 v3, v3, v21
	v_max_f32_e32 v25, v24, v17
	v_min_f32_e32 v17, v24, v17
	v_max_f32_e32 v24, v33, v23
	v_min_f32_e32 v23, v33, v23
	v_max_f32_e32 v33, v14, v31
	v_min_f32_e32 v14, v14, v31
	v_max_f32_e32 v31, v30, v32
	v_min_f32_e32 v30, v30, v32
	v_max_f32_e32 v32, v6, v22
	v_min_f32_e32 v6, v6, v22
	v_max_f32_e32 v22, v9, v16
	v_min_f32_e32 v9, v9, v16
	v_max_f32_e32 v16, v8, v15
	v_min_f32_e32 v8, v8, v15
	v_max_f32_e32 v15, v7, v5
	v_min_f32_e32 v5, v7, v5
	v_max_f32_e32 v21, v26, v13
	v_min_f32_e32 v13, v26, v13
	v_max_f32_e32 v26, v29, v20
	v_min_f32_e32 v20, v29, v20
	v_max_f32_e32 v29, v10, v28
	v_min_f32_e32 v10, v10, v28
	v_max_f32_e32 v28, v27, v67
	v_min_f32_e32 v27, v27, v67
	v_max_f32_e32 v67, v0, v18
	v_min_f32_e32 v0, v0, v18
	v_max_f32_e32 v18, v4, v19
	v_min_f32_e32 v4, v4, v19
	v_max_f32_e32 v19, v12, v11
	v_min_f32_e32 v11, v12, v11
	v_max_f32_e32 v12, v2, v3
	v_min_f32_e32 v2, v2, v3
; DEV void merge_xor(float (&l)[16], int mask) {
;   float t[16];
; #pragma unroll
;   for (int i = 0; i < 16; i++) t[i] = __shfl_xor(l[15 - i], mask);
; #pragma unroll
;   for (int i = 0; i < 16; i++) l[i] = fmaxf(l[i], t[i]);
;   bitonic16(l);
; DEV void peer_top16(const bf16_t* __restrict__ pq, const bf16_t* sk  , float (&l)[16]) {
;     ...
;   sort16_desc(l);
;   sort16_desc(hi);
; #pragma unroll
;   for (int i = 0; i < 16; i++) l[i] = fmaxf(l[i], hi[15 - i]);
;   bitonic16(l);
;   merge_xor(l, 16);
;   merge_xor(l, 32);
	v_max_f32_e32 v7, v25, v33
	v_min_f32_e32 v25, v25, v33
	v_max_f32_e32 v33, v24, v31
	v_min_f32_e32 v24, v24, v31
	v_max_f32_e32 v31, v17, v14
	v_min_f32_e32 v14, v17, v14
	v_max_f32_e32 v17, v23, v30
	v_min_f32_e32 v23, v23, v30
	v_max_f32_e32 v30, v32, v16
	v_min_f32_e32 v16, v32, v16
	v_max_f32_e32 v32, v22, v15
	v_min_f32_e32 v15, v22, v15
	v_max_f32_e32 v22, v6, v8
	v_min_f32_e32 v6, v6, v8
	v_max_f32_e32 v8, v9, v5
	v_min_f32_e32 v5, v9, v5
	v_max_f32_e32 v3, v21, v29
	v_min_f32_e32 v21, v21, v29
	v_max_f32_e32 v29, v26, v28
	v_min_f32_e32 v26, v26, v28
	v_max_f32_e32 v28, v13, v10
	v_min_f32_e32 v10, v13, v10
	v_max_f32_e32 v13, v20, v27
	v_min_f32_e32 v20, v20, v27
	v_max_f32_e32 v27, v67, v19
	v_min_f32_e32 v19, v67, v19
	v_max_f32_e32 v67, v18, v12
	v_min_f32_e32 v12, v18, v12
	v_max_f32_e32 v18, v0, v11
	v_min_f32_e32 v0, v0, v11
	v_max_f32_e32 v11, v4, v2
	v_min_f32_e32 v2, v4, v2
	v_min_f32_e32 v9, v7, v33
	v_min_f32_e32 v39, v25, v24
	v_min_f32_e32 v43, v31, v17
	v_min_f32_e32 v47, v14, v23
	v_min_f32_e32 v51, v30, v32
	v_min_f32_e32 v55, v16, v15
	v_min_f32_e32 v59, v22, v8
	v_min_f32_e32 v63, v6, v5
	v_min_f32_e32 v4, v3, v29
	v_min_f32_e32 v71, v21, v26
	v_min_f32_e32 v75, v28, v13
	v_min_f32_e32 v79, v10, v20
	v_min_f32_e32 v83, v27, v67
	v_min_f32_e32 v87, v19, v12
	v_min_f32_e32 v91, v18, v11
	v_min_f32_e32 v95, v0, v2
	v_max3_f32 v7, v7, v33, v95
	v_max3_f32 v0, v9, v0, v2
	v_max3_f32 v2, v25, v24, v91
	v_max3_f32 v9, v39, v18, v11
	v_max3_f32 v11, v31, v17, v87
	v_max3_f32 v12, v43, v19, v12
	v_max3_f32 v14, v14, v23, v83
	v_max3_f32 v17, v47, v27, v67
	v_max3_f32 v18, v30, v32, v79
	v_max3_f32 v10, v51, v10, v20
	v_max3_f32 v15, v16, v15, v75
	v_max3_f32 v13, v55, v28, v13
	v_max3_f32 v8, v22, v8, v71
	v_max3_f32 v16, v59, v21, v26
	v_max3_f32 v4, v6, v5, v4
	v_max3_f32 v3, v63, v3, v29
	v_max_f32_e32 v5, v7, v18
	v_min_f32_e32 v6, v7, v18
	v_max_f32_e32 v7, v0, v10
	v_min_f32_e32 v0, v0, v10
	v_max_f32_e32 v10, v2, v15
	v_min_f32_e32 v2, v2, v15
	v_max_f32_e32 v15, v9, v13
	v_min_f32_e32 v9, v9, v13
	v_max_f32_e32 v13, v11, v8
	v_min_f32_e32 v8, v11, v8
	v_max_f32_e32 v11, v12, v16
	v_min_f32_e32 v12, v12, v16
	v_max_f32_e32 v16, v14, v4
	v_min_f32_e32 v4, v14, v4
	v_max_f32_e32 v14, v17, v3
	v_min_f32_e32 v3, v17, v3
	v_max_f32_e32 v17, v5, v13
	v_min_f32_e32 v5, v5, v13
	v_max_f32_e32 v13, v7, v11
	v_min_f32_e32 v7, v7, v11
	v_max_f32_e32 v11, v10, v16
	v_min_f32_e32 v10, v10, v16
	v_max_f32_e32 v16, v15, v14
	v_min_f32_e32 v14, v15, v14
	v_max_f32_e32 v15, v6, v8
	v_min_f32_e32 v6, v6, v8
	v_max_f32_e32 v8, v0, v12
	v_min_f32_e32 v0, v0, v12
	v_max_f32_e32 v12, v2, v4
	v_min_f32_e32 v2, v2, v4
	v_max_f32_e32 v4, v9, v3
	v_min_f32_e32 v3, v9, v3
	v_max_f32_e32 v9, v17, v11
	v_min_f32_e32 v11, v17, v11
	v_max_f32_e32 v17, v13, v16
	v_min_f32_e32 v13, v13, v16
	v_max_f32_e32 v16, v5, v10
	v_min_f32_e32 v5, v5, v10
	v_max_f32_e32 v10, v7, v14
	v_min_f32_e32 v7, v7, v14
	v_max_f32_e32 v14, v15, v12
	v_min_f32_e32 v12, v15, v12
	v_max_f32_e32 v15, v8, v4
	v_min_f32_e32 v4, v8, v4
	v_max_f32_e32 v8, v6, v2
	v_min_f32_e32 v2, v6, v2
	v_max_f32_e32 v6, v0, v3
	v_min_f32_e32 v0, v0, v3
	v_max_f32_e32 v3, v9, v17
	v_min_f32_e32 v9, v9, v17
	v_max_f32_e32 v17, v11, v13
	v_min_f32_e32 v11, v11, v13
	v_max_f32_e32 v13, v16, v10
	v_min_f32_e32 v10, v16, v10
	v_max_f32_e32 v16, v5, v7
	v_min_f32_e32 v5, v5, v7
	v_max_f32_e32 v7, v14, v15
	v_min_f32_e32 v14, v14, v15
	v_max_f32_e32 v15, v12, v4
	v_min_f32_e32 v4, v12, v4
	v_max_f32_e32 v12, v8, v6
	v_min_f32_e32 v6, v8, v6
	v_max_f32_e32 v8, v2, v0
	v_min_f32_e32 v0, v2, v0
	v_mbcnt_hi_u32_b32 v2, -1, v215
	v_and_b32_e32 v19, 64, v2
	v_xor_b32_e32 v18, 16, v2
	v_add_u32_e32 v19, 64, v19
	v_cmp_lt_i32_e32 vcc, v18, v19
	s_add_u32 s14, s12, s14
	s_addc_u32 s15, s13, s15
	v_cndmask_b32_e32 v18, v2, v18, vcc
	v_lshlrev_b32_e32 v95, 2, v18
	ds_bpermute_b32 v18, v95, v0
	ds_bpermute_b32 v20, v95, v8
	ds_bpermute_b32 v21, v95, v6
	ds_bpermute_b32 v22, v95, v12
	ds_bpermute_b32 v23, v95, v4
	ds_bpermute_b32 v24, v95, v15
	s_waitcnt lgkmcnt(5)
	ds_bpermute_b32 v25, v95, v14
	ds_bpermute_b32 v39, v95, v3
	v_max_f32_e32 v3, v3, v18
	s_waitcnt lgkmcnt(6)
	ds_bpermute_b32 v26, v95, v7
	ds_bpermute_b32 v33, v95, v9
	v_max_f32_e32 v9, v9, v20
	s_waitcnt lgkmcnt(7)
	ds_bpermute_b32 v27, v95, v5
	ds_bpermute_b32 v32, v95, v17
	v_max_f32_e32 v17, v17, v21
	s_waitcnt lgkmcnt(8)
	ds_bpermute_b32 v28, v95, v16
	ds_bpermute_b32 v31, v95, v11
	v_max_f32_e32 v11, v11, v22
	s_waitcnt lgkmcnt(9)
	ds_bpermute_b32 v29, v95, v10
	ds_bpermute_b32 v30, v95, v13
	v_max_f32_e32 v13, v13, v23
	s_waitcnt lgkmcnt(10)
	v_max_f32_e32 v10, v10, v24
	s_waitcnt lgkmcnt(9)
	v_max_f32_e32 v16, v16, v25
	s_waitcnt lgkmcnt(7)
	v_max_f32_e32 v5, v5, v26
	s_waitcnt lgkmcnt(5)
	v_max_f32_e32 v7, v7, v27
	s_waitcnt lgkmcnt(3)
	v_max_f32_e32 v14, v14, v28
	s_waitcnt lgkmcnt(1)
	v_max_f32_e32 v15, v15, v29
	s_waitcnt lgkmcnt(0)
; DEV int tidx() { int t = threadIdx.x; asm volatile("" : "+v"(t)); return t; }
; DEV f32x4 mfma16(bf16x8 a, bf16x8 b, f32x4 c) { return __builtin_amdgcn_mfma_f32_16x16x32_bf16(a, b, c, 0, 0, 0); }
; DEV void merge_xor(float (&l)[16], int mask) {
;   float t[16];
; #pragma unroll
;   for (int i = 0; i < 16; i++) t[i] = __shfl_xor(l[15 - i], mask);
; #pragma unroll
;   for (int i = 0; i < 16; i++) l[i] = fmaxf(l[i], t[i]);
;   bitonic16(l);
; }
; DEV void peer_top16(const bf16_t* __restrict__ pq, const bf16_t* sk  , float (&l)[16]) {
;   const int lane = tidx() & 63, l15 = lane & 15, quad = lane >> 4;
;   f32x4 acc[8];
; #pragma unroll
;   for (int nt = 0; nt < 8; nt++) acc[nt] = (f32x4){0.f, 0.f, 0.f, 0.f};
; #pragma unroll 1
;   for (int ks = 0; ks < 4; ks++) {
;     const bf16x8 bqk = *(const bf16x8*)(pq + ks * 32 + quad * 8);
; #pragma unroll
;     for (int nt = 0; nt < 8; nt++) {
;       bf16x8 ak = *(const bf16x8*)(sk + (nt * 16 + l15) * 144 + ks * 32 + quad * 8);
;       acc[nt] = mfma16(ak, bqk, acc[nt]);
;     }
;   }
	v_max_f32_e32 v4, v4, v30
	v_max_f32_e32 v12, v12, v31
	v_max_f32_e32 v6, v6, v32
	v_max_f32_e32 v8, v8, v33
	v_max_f32_e32 v0, v0, v39
	v_max_f32_e32 v18, v3, v7
	v_min_f32_e32 v3, v3, v7
	v_max_f32_e32 v7, v9, v14
	v_min_f32_e32 v9, v9, v14
	v_max_f32_e32 v14, v17, v15
	v_min_f32_e32 v15, v17, v15
	v_max_f32_e32 v17, v11, v4
	v_min_f32_e32 v4, v11, v4
	v_max_f32_e32 v11, v13, v12
	v_min_f32_e32 v12, v13, v12
	v_max_f32_e32 v13, v10, v6
	v_min_f32_e32 v6, v10, v6
	v_max_f32_e32 v10, v16, v8
	v_min_f32_e32 v8, v16, v8
	v_max_f32_e32 v16, v5, v0
	v_min_f32_e32 v0, v5, v0
	v_max_f32_e32 v5, v18, v11
	v_min_f32_e32 v11, v18, v11
	v_max_f32_e32 v18, v7, v13
	v_min_f32_e32 v7, v7, v13
	v_max_f32_e32 v13, v14, v10
	v_min_f32_e32 v10, v14, v10
	v_max_f32_e32 v14, v17, v16
	v_min_f32_e32 v16, v17, v16
	v_max_f32_e32 v17, v3, v12
	v_min_f32_e32 v3, v3, v12
	v_max_f32_e32 v12, v9, v6
	v_min_f32_e32 v6, v9, v6
	v_max_f32_e32 v9, v15, v8
	v_min_f32_e32 v8, v15, v8
	v_max_f32_e32 v15, v4, v0
	v_min_f32_e32 v0, v4, v0
	v_max_f32_e32 v4, v5, v13
	v_min_f32_e32 v5, v5, v13
	v_max_f32_e32 v13, v18, v14
	v_min_f32_e32 v14, v18, v14
	v_max_f32_e32 v18, v11, v10
	v_min_f32_e32 v10, v11, v10
	v_max_f32_e32 v11, v7, v16
	v_min_f32_e32 v7, v7, v16
	v_max_f32_e32 v16, v17, v9
	v_min_f32_e32 v9, v17, v9
	v_max_f32_e32 v17, v12, v15
	v_min_f32_e32 v12, v12, v15
	v_max_f32_e32 v15, v3, v8
	v_min_f32_e32 v3, v3, v8
	v_max_f32_e32 v8, v6, v0
	v_min_f32_e32 v0, v6, v0
	v_max_f32_e32 v43, v3, v0
	v_min_f32_e32 v39, v3, v0
	v_xor_b32_e32 v0, 32, v2
	v_cmp_lt_i32_e32 vcc, v0, v19
	v_max_f32_e32 v109, v4, v13
	v_min_f32_e32 v107, v4, v13
	v_cndmask_b32_e32 v0, v2, v0, vcc
	v_max_f32_e32 v105, v5, v14
	v_min_f32_e32 v103, v5, v14
	v_max_f32_e32 v87, v18, v11
	v_min_f32_e32 v79, v18, v11
	v_max_f32_e32 v75, v10, v7
	v_min_f32_e32 v71, v10, v7
	v_max_f32_e32 v67, v16, v17
	v_min_f32_e32 v63, v16, v17
	v_max_f32_e32 v59, v9, v12
	v_min_f32_e32 v55, v9, v12
	v_max_f32_e32 v51, v15, v8
	v_min_f32_e32 v47, v15, v8
	v_lshlrev_b32_e32 v99, 2, v0
	v_mov_b32_e32 v0, v195
	ds_bpermute_b32 v121, v99, v39
	ds_bpermute_b32 v120, v99, v43
	ds_bpermute_b32 v119, v99, v47
	ds_bpermute_b32 v118, v99, v51
	ds_bpermute_b32 v116, v99, v55
	ds_bpermute_b32 v115, v99, v59
	ds_bpermute_b32 v114, v99, v63
	ds_bpermute_b32 v113, v99, v67
	ds_bpermute_b32 v112, v99, v71
	ds_bpermute_b32 v111, v99, v75
	ds_bpermute_b32 v110, v99, v79
	ds_bpermute_b32 v108, v99, v87
	ds_bpermute_b32 v106, v99, v103
	ds_bpermute_b32 v104, v99, v105
	ds_bpermute_b32 v91, v99, v107
	ds_bpermute_b32 v83, v99, v109
	s_mov_b32 s0, 0
	v_bfe_u32 v102, v0, 4, 2
	v_and_b32_e32 v2, 15, v0
	v_lshlrev_b32_e32 v0, 4, v102
	v_mad_u32_u24 v122, v2, s20, v0
	v_lshl_add_u64 v[2:3], v[100:101], 0, v[0:1]
	v_lshl_add_u64 v[100:101], s[14:15], 0, v[2:3]
	v_mov_b32_e32 v2, 0
	v_mov_b32_e32 v3, v2
	v_mov_b32_e32 v4, v2
	v_mov_b32_e32 v5, v2
	v_mov_b32_e32 v10, v2
	v_mov_b32_e32 v11, v2
	v_mov_b32_e32 v12, v2
	v_mov_b32_e32 v13, v2
	v_mov_b32_e32 v18, v2
	v_mov_b32_e32 v19, v2
	v_mov_b32_e32 v20, v2
	v_mov_b32_e32 v21, v2
	v_mov_b32_e32 v26, v2
	v_mov_b32_e32 v27, v2
	v_mov_b32_e32 v28, v2
	v_mov_b32_e32 v29, v2
	v_mov_b32_e32 v6, v2
	v_mov_b32_e32 v7, v2
	v_mov_b32_e32 v8, v2
	v_mov_b32_e32 v9, v2
	v_mov_b32_e32 v14, v2
	v_mov_b32_e32 v15, v2
	v_mov_b32_e32 v16, v2
	v_mov_b32_e32 v17, v2
	v_mov_b32_e32 v22, v2
	v_mov_b32_e32 v23, v2
	v_mov_b32_e32 v24, v2
	v_mov_b32_e32 v25, v2
	v_mov_b32_e32 v30, v2
	v_mov_b32_e32 v31, v2
	v_mov_b32_e32 v32, v2
	v_mov_b32_e32 v33, v2
.LBB0_170:
	global_load_dwordx4 v[124:127], v[100:101], off
	v_add_u32_e32 v0, s0, v122
	ds_read_b128 v[128:131], v0 offset:36864
	s_add_i32 s0, s0, 64
	v_lshl_add_u64 v[100:101], v[100:101], 0, 64
	s_cmpk_lg_i32 s0, 0x100
	s_waitcnt vmcnt(0) lgkmcnt(0)
	v_mfma_f32_16x16x32_bf16 v[30:33], v[128:131], v[124:127], v[30:33]
	ds_read_b128 v[128:131], v0 offset:41472
	s_waitcnt lgkmcnt(0)
	v_mfma_f32_16x16x32_bf16 v[22:25], v[128:131], v[124:127], v[22:25]
	ds_read_b128 v[128:131], v0 offset:46080
	s_waitcnt lgkmcnt(0)
	v_mfma_f32_16x16x32_bf16 v[14:17], v[128:131], v[124:127], v[14:17]
	ds_read_b128 v[128:131], v0 offset:50688
	s_waitcnt lgkmcnt(0)
	v_mfma_f32_16x16x32_bf16 v[6:9], v[128:131], v[124:127], v[6:9]
	ds_read_b128 v[128:131], v0 offset:55296
	s_waitcnt lgkmcnt(0)
	v_mfma_f32_16x16x32_bf16 v[26:29], v[128:131], v[124:127], v[26:29]
	ds_read_b128 v[128:131], v0 offset:59904
	s_waitcnt lgkmcnt(0)
	v_mfma_f32_16x16x32_bf16 v[18:21], v[128:131], v[124:127], v[18:21]
	ds_read_b128 v[128:131], v0 offset:64512
	v_add_u32_e32 v0, 0x10e00, v0
	s_waitcnt lgkmcnt(0)
	v_mfma_f32_16x16x32_bf16 v[10:13], v[128:131], v[124:127], v[10:13]
	ds_read_b128 v[128:131], v0
	s_waitcnt lgkmcnt(0)
	v_mfma_f32_16x16x32_bf16 v[2:5], v[128:131], v[124:127], v[2:5]
	s_cbranch_scc1 .LBB0_170
; DEV int tidx() { int t = threadIdx.x; asm volatile("" : "+v"(t)); return t; }
; DEV f32x4 mfma16(bf16x8 a, bf16x8 b, f32x4 c) { return __builtin_amdgcn_mfma_f32_16x16x32_bf16(a, b, c, 0, 0, 0); }
; DEV void merge_xor(float (&l)[16], int mask) {
;   float t[16];
; #pragma unroll
;   for (int i = 0; i < 16; i++) t[i] = __shfl_xor(l[15 - i], mask);
; #pragma unroll
;   for (int i = 0; i < 16; i++) l[i] = fmaxf(l[i], t[i]);
;   bitonic16(l);
; }
; DEV void peer_top16(const bf16_t* __restrict__ pq, const bf16_t* sk  , float (&l)[16]) {
;   const int lane = tidx() & 63, l15 = lane & 15, quad = lane >> 4;
;   f32x4 acc[8];
; #pragma unroll
;   for (int nt = 0; nt < 8; nt++) acc[nt] = (f32x4){0.f, 0.f, 0.f, 0.f};
; #pragma unroll 1
;   for (int ks = 0; ks < 4; ks++) {
;     const bf16x8 bqk = *(const bf16x8*)(pq + ks * 32 + quad * 8);
; #pragma unroll
;     for (int nt = 0; nt < 8; nt++) {
;       bf16x8 ak = *(const bf16x8*)(sk + (nt * 16 + l15) * 144 + ks * 32 + quad * 8);
;       acc[nt] = mfma16(ak, bqk, acc[nt]);
;     }
;   }
;   float hi[16];
; #pragma unroll
;   for (int nt = 0; nt < 4; nt++)
; #pragma unroll
;     for (int r = 0; r < 4; r++) {
;       l[nt * 4 + r] = __uint_as_float((__float_as_uint(acc[nt][r]) & ~127u) | (unsigned)(nt * 16 + quad * 4 + r));
;       hi[nt * 4 + r] = __uint_as_float((__float_as_uint(acc[nt + 4][r]) & ~127u) | (unsigned)((nt + 4) * 16 + quad * 4 + r));
;     }
;   sort16_desc(l);
;   sort16_desc(hi);
	v_max_f32_e32 v0, v109, v121
	v_max_f32_e32 v100, v107, v120
	v_max_f32_e32 v101, v105, v119
	v_max_f32_e32 v103, v103, v118
	v_max_f32_e32 v87, v87, v116
	v_max_f32_e32 v79, v79, v115
	v_max_f32_e32 v75, v75, v114
	v_max_f32_e32 v71, v71, v113
	v_max_f32_e32 v67, v67, v112
	v_max_f32_e32 v63, v63, v111
	v_max_f32_e32 v59, v59, v110
	v_max_f32_e32 v55, v55, v108
	v_max_f32_e32 v51, v51, v106
	v_max_f32_e32 v47, v47, v104
	v_max_f32_e32 v43, v43, v91
	v_max_f32_e32 v39, v39, v83
	v_max_f32_e32 v83, v0, v67
	v_min_f32_e32 v0, v0, v67
	v_max_f32_e32 v67, v100, v63
	v_min_f32_e32 v63, v100, v63
	v_max_f32_e32 v91, v101, v59
	v_min_f32_e32 v59, v101, v59
	v_max_f32_e32 v100, v103, v55
	v_min_f32_e32 v55, v103, v55
	v_max_f32_e32 v101, v87, v51
	v_min_f32_e32 v51, v87, v51
	v_max_f32_e32 v87, v79, v47
	v_min_f32_e32 v47, v79, v47
	v_max_f32_e32 v79, v75, v43
	v_min_f32_e32 v43, v75, v43
	v_max_f32_e32 v75, v71, v39
	v_min_f32_e32 v39, v71, v39
	v_max_f32_e32 v71, v83, v101
	v_min_f32_e32 v101, v83, v101
	v_max_f32_e32 v103, v67, v87
	v_min_f32_e32 v67, v67, v87
	v_max_f32_e32 v87, v91, v79
	v_min_f32_e32 v79, v91, v79
	v_max_f32_e32 v91, v100, v75
	v_min_f32_e32 v75, v100, v75
	v_max_f32_e32 v100, v0, v51
	v_min_f32_e32 v0, v0, v51
	v_max_f32_e32 v51, v63, v47
	v_max_f32_e32 v105, v59, v43
	v_min_f32_e32 v43, v59, v43
	v_max_f32_e32 v59, v55, v39
	v_min_f32_e32 v107, v101, v79
	v_min_f32_e32 v108, v67, v75
	v_min_f32_e32 v110, v51, v59
	v_max_f32_e32 v79, v101, v79
	v_max_f32_e32 v67, v67, v75
	v_max_f32_e32 v101, v100, v105
	v_max_f32_e32 v51, v51, v59
	v_min_f32_e32 v75, v79, v67
	v_min_f32_e32 v59, v101, v51
	v_max_f32_e32 v79, v79, v67
	v_max_f32_e32 v67, v101, v51
	v_lshlrev_b32_e32 v101, 2, v102
	s_movk_i32 s0, 0xff80
	v_and_or_b32 v30, v30, s0, v101
	v_and_b32_e32 v27, 0xffffff80, v27
	s_movk_i32 s0, 0x41
	v_or3_b32 v27, v101, v27, s0
	v_and_b32_e32 v28, 0xffffff80, v28
	s_movk_i32 s0, 0x42
	v_or3_b32 v28, v101, v28, s0
	v_and_b32_e32 v29, 0xffffff80, v29
	s_movk_i32 s0, 0x43
	v_or3_b32 v29, v101, v29, s0
	v_and_b32_e32 v18, 0xffffff80, v18
	s_movk_i32 s0, 0x50
	v_or3_b32 v18, v101, v18, s0
	v_and_b32_e32 v19, 0xffffff80, v19
	s_movk_i32 s0, 0x51
	v_or3_b32 v19, v101, v19, s0
	v_and_b32_e32 v20, 0xffffff80, v20
	s_movk_i32 s0, 0x52
	v_or3_b32 v20, v101, v20, s0
	v_and_b32_e32 v21, 0xffffff80, v21
	s_movk_i32 s0, 0x53
	v_or3_b32 v21, v101, v21, s0
	v_and_b32_e32 v10, 0xffffff80, v10
	s_movk_i32 s0, 0x60
	v_or3_b32 v10, v101, v10, s0
	v_and_b32_e32 v11, 0xffffff80, v11
	s_movk_i32 s0, 0x61
	v_or3_b32 v11, v101, v11, s0
	v_and_b32_e32 v12, 0xffffff80, v12
	s_movk_i32 s0, 0x62
	v_or3_b32 v12, v101, v12, s0
	v_and_b32_e32 v13, 0xffffff80, v13
	s_movk_i32 s0, 0x63
	v_or3_b32 v13, v101, v13, s0
	v_and_b32_e32 v2, 0xffffff80, v2
	s_movk_i32 s0, 0x70
	v_and_b32_e32 v26, 0xffffff80, v26
	v_and_b32_e32 v31, 0xffffff80, v31
	v_or3_b32 v2, v101, v2, s0
	v_and_b32_e32 v3, 0xffffff80, v3
	s_movk_i32 s0, 0x71
	v_or3_b32 v26, v101, v26, 64
	v_or3_b32 v31, v101, v31, 1
	v_and_b32_e32 v32, 0xffffff80, v32
	v_and_b32_e32 v33, 0xffffff80, v33
	v_and_b32_e32 v22, 0xffffff80, v22
	v_and_b32_e32 v23, 0xffffff80, v23
	v_or3_b32 v3, v101, v3, s0
	v_and_b32_e32 v4, 0xffffff80, v4
	s_movk_i32 s0, 0x72
	v_min_f32_e32 v39, v55, v39
	v_min_f32_e32 v55, v71, v87
	v_min_f32_e32 v106, v103, v91
	v_min_f32_e32 v109, v100, v105
	v_max_f32_e32 v71, v71, v87
	v_max_f32_e32 v87, v103, v91
	v_or3_b32 v32, v101, v32, 2
	v_or3_b32 v33, v101, v33, 3
	v_or3_b32 v22, v101, v22, 16
	v_or3_b32 v23, v101, v23, 17
	v_and_b32_e32 v24, 0xffffff80, v24
	v_and_b32_e32 v25, 0xffffff80, v25
	v_and_b32_e32 v14, 0xffffff80, v14
	v_and_b32_e32 v15, 0xffffff80, v15
	v_and_b32_e32 v16, 0xffffff80, v16
	v_and_b32_e32 v17, 0xffffff80, v17
	v_and_b32_e32 v6, 0xffffff80, v6
	v_and_b32_e32 v7, 0xffffff80, v7
	v_and_b32_e32 v8, 0xffffff80, v8
	v_or3_b32 v4, v101, v4, s0
	v_and_b32_e32 v9, 0xffffff80, v9
	v_and_b32_e32 v5, 0xffffff80, v5
	s_movk_i32 s0, 0x73
	v_min_f32_e32 v104, v63, v47
	v_min_f32_e32 v83, v55, v106
	v_min_f32_e32 v47, v109, v110
	v_min_f32_e32 v91, v71, v87
	v_max_f32_e32 v100, v71, v87
	v_max_f32_e32 v87, v55, v106
	v_max_f32_e32 v55, v109, v110
	v_or3_b32 v24, v101, v24, 18
	v_or3_b32 v25, v101, v25, 19
	v_or3_b32 v14, v101, v14, 32
	v_or3_b32 v15, v101, v15, 33
	v_or3_b32 v16, v101, v16, 34
	v_or3_b32 v17, v101, v17, 35
	v_or3_b32 v6, v101, v6, 48
	v_or3_b32 v7, v101, v7, 49
	v_or3_b32 v8, v101, v8, 50
	v_or3_b32 v9, v101, v9, 51
	v_or3_b32 v5, v101, v5, s0
	v_max_f32_e32 v101, v30, v31
	v_min_f32_e32 v30, v30, v31
	v_max_f32_e32 v31, v32, v32
	v_max_f32_e32 v32, v33, v33
	v_max_f32_e32 v109, v26, v27
	v_min_f32_e32 v26, v26, v27
	v_max_f32_e32 v27, v28, v28
	v_max_f32_e32 v28, v29, v29
	v_max_f32_e32 v33, v32, v31
	v_min_f32_e32 v31, v32, v31
	v_max_f32_e32 v32, v22, v23
	v_min_f32_e32 v22, v22, v23
	v_max_f32_e32 v23, v24, v24
	v_max_f32_e32 v24, v25, v25
	v_max_f32_e32 v29, v28, v27
	v_min_f32_e32 v27, v28, v27
	v_max_f32_e32 v28, v18, v19
	v_min_f32_e32 v18, v18, v19
	v_max_f32_e32 v19, v20, v20
	v_max_f32_e32 v20, v21, v21
	v_max_f32_e32 v25, v24, v23
	v_min_f32_e32 v23, v24, v23
	v_max_f32_e32 v24, v14, v15
	v_min_f32_e32 v14, v14, v15
	v_max_f32_e32 v15, v16, v16
	v_max_f32_e32 v16, v17, v17
	v_max_f32_e32 v21, v20, v19
	v_min_f32_e32 v19, v20, v19
	v_max_f32_e32 v20, v10, v11
	v_min_f32_e32 v10, v10, v11
	v_max_f32_e32 v11, v12, v12
	v_max_f32_e32 v12, v13, v13
	v_max_f32_e32 v17, v16, v15
	v_min_f32_e32 v15, v16, v15
	v_max_f32_e32 v16, v6, v7
	v_min_f32_e32 v6, v6, v7
	v_max_f32_e32 v7, v8, v8
	v_max_f32_e32 v8, v9, v9
	v_max_f32_e32 v13, v12, v11
	v_min_f32_e32 v11, v12, v11
; DEV void ce(float& a, float& b) { float hi = fmaxf(a, b), lo = fminf(a, b); a = hi; b = lo; }
; DEV void sort16_desc(float (&a)[16]) {
; #pragma unroll
;   for (int k = 2; k <= 16; k <<= 1)
; #pragma unroll
;     for (int j = k >> 1; j > 0; j >>= 1)
; #pragma unroll
;       for (int i = 0; i < 16; i++) {
;         const int p = i ^ j;
;         if (p > i) { if ((i & k) == 0) ce(a[i], a[p]); else ce(a[p], a[i]); }
;       }
; }
	v_max_f32_e32 v12, v2, v3
	v_min_f32_e32 v2, v2, v3
	v_max_f32_e32 v3, v4, v4
	v_max_f32_e32 v4, v5, v5
	v_max_f32_e32 v9, v8, v7
	v_min_f32_e32 v7, v8, v7
	v_max_f32_e32 v5, v4, v3
	v_min_f32_e32 v3, v4, v3
	v_max_f32_e32 v8, v101, v31
	v_min_f32_e32 v31, v101, v31
	v_max_f32_e32 v101, v30, v33
	v_min_f32_e32 v30, v30, v33
	v_max_f32_e32 v33, v23, v32
	v_min_f32_e32 v23, v23, v32
	v_max_f32_e32 v32, v25, v22
	v_min_f32_e32 v22, v25, v22
	v_max_f32_e32 v25, v24, v15
	v_min_f32_e32 v15, v24, v15
	v_max_f32_e32 v24, v14, v17
	v_min_f32_e32 v14, v14, v17
	v_max_f32_e32 v17, v7, v16
	v_min_f32_e32 v7, v7, v16
	v_max_f32_e32 v16, v9, v6
	v_min_f32_e32 v6, v9, v6
	v_max_f32_e32 v4, v109, v27
	v_min_f32_e32 v27, v109, v27
	v_max_f32_e32 v109, v26, v29
	v_min_f32_e32 v26, v26, v29
	v_max_f32_e32 v29, v19, v28
	v_min_f32_e32 v19, v19, v28
	v_max_f32_e32 v28, v21, v18
	v_min_f32_e32 v18, v21, v18
	v_max_f32_e32 v21, v20, v11
	v_min_f32_e32 v11, v20, v11
	v_max_f32_e32 v20, v10, v13
	v_min_f32_e32 v10, v10, v13
	v_max_f32_e32 v13, v3, v12
	v_min_f32_e32 v3, v3, v12
	v_max_f32_e32 v12, v5, v2
	v_min_f32_e32 v2, v5, v2
	v_max_f32_e32 v9, v8, v101
	v_min_f32_e32 v8, v8, v101
	v_max_f32_e32 v101, v31, v30
	v_min_f32_e32 v30, v31, v30
	v_max_f32_e32 v31, v22, v23
	v_min_f32_e32 v22, v22, v23
	v_max_f32_e32 v23, v32, v33
	v_min_f32_e32 v32, v32, v33
	v_max_f32_e32 v33, v25, v24
	v_min_f32_e32 v24, v25, v24
	v_max_f32_e32 v25, v15, v14
	v_min_f32_e32 v14, v15, v14
	v_max_f32_e32 v15, v6, v7
	v_min_f32_e32 v6, v6, v7
	v_max_f32_e32 v7, v16, v17
	v_min_f32_e32 v16, v16, v17
	v_max_f32_e32 v5, v4, v109
	v_min_f32_e32 v4, v4, v109
	v_max_f32_e32 v109, v27, v26
	v_min_f32_e32 v26, v27, v26
	v_max_f32_e32 v27, v18, v19
	v_min_f32_e32 v18, v18, v19
	v_max_f32_e32 v19, v28, v29
	v_min_f32_e32 v28, v28, v29
	v_max_f32_e32 v29, v21, v20
	v_min_f32_e32 v20, v21, v20
	v_max_f32_e32 v21, v11, v10
	v_min_f32_e32 v10, v11, v10
	v_max_f32_e32 v11, v2, v3
	v_min_f32_e32 v2, v2, v3
	v_max_f32_e32 v3, v12, v13
	v_min_f32_e32 v12, v12, v13
	v_max_f32_e32 v17, v9, v22
	v_min_f32_e32 v9, v9, v22
	v_max_f32_e32 v22, v8, v31
	v_min_f32_e32 v8, v8, v31
	v_max_f32_e32 v31, v101, v32
	v_min_f32_e32 v32, v101, v32
	v_max_f32_e32 v101, v30, v23
	v_min_f32_e32 v23, v30, v23
	v_max_f32_e32 v30, v6, v33
	v_min_f32_e32 v6, v6, v33
	v_max_f32_e32 v33, v15, v24
	v_min_f32_e32 v15, v15, v24
	v_max_f32_e32 v24, v16, v25
	v_min_f32_e32 v16, v16, v25
	v_max_f32_e32 v25, v7, v14
	v_min_f32_e32 v7, v7, v14
	v_max_f32_e32 v13, v5, v18
	v_min_f32_e32 v5, v5, v18
	v_max_f32_e32 v18, v4, v27
	v_min_f32_e32 v4, v4, v27
	v_max_f32_e32 v27, v109, v28
	v_min_f32_e32 v28, v109, v28
	v_max_f32_e32 v109, v26, v19
	v_min_f32_e32 v19, v26, v19
	v_max_f32_e32 v26, v2, v29
	v_min_f32_e32 v2, v2, v29
	v_max_f32_e32 v29, v11, v20
	v_min_f32_e32 v11, v11, v20
	v_max_f32_e32 v20, v12, v21
	v_min_f32_e32 v12, v12, v21
	v_max_f32_e32 v21, v3, v10
	v_min_f32_e32 v3, v3, v10
	v_max_f32_e32 v14, v17, v31
	v_min_f32_e32 v17, v17, v31
	v_max_f32_e32 v31, v22, v101
	v_min_f32_e32 v22, v22, v101
	v_max_f32_e32 v101, v9, v32
	v_min_f32_e32 v9, v9, v32
	v_max_f32_e32 v32, v8, v23
	v_min_f32_e32 v8, v8, v23
	v_max_f32_e32 v23, v16, v6
	v_min_f32_e32 v6, v16, v6
	v_max_f32_e32 v16, v7, v15
	v_min_f32_e32 v7, v7, v15
	v_max_f32_e32 v15, v24, v30
	v_min_f32_e32 v24, v24, v30
	v_max_f32_e32 v30, v25, v33
	v_min_f32_e32 v25, v25, v33
	v_max_f32_e32 v10, v13, v27
	v_min_f32_e32 v13, v13, v27
	v_max_f32_e32 v27, v18, v109
	v_min_f32_e32 v18, v18, v109
	v_max_f32_e32 v109, v5, v28
	v_min_f32_e32 v5, v5, v28
	v_max_f32_e32 v28, v4, v19
	v_min_f32_e32 v4, v4, v19
	v_max_f32_e32 v19, v12, v2
	v_min_f32_e32 v2, v12, v2
	v_max_f32_e32 v12, v3, v11
	v_min_f32_e32 v3, v3, v11
	v_max_f32_e32 v11, v20, v26
	v_min_f32_e32 v20, v20, v26
	v_max_f32_e32 v26, v21, v29
	v_min_f32_e32 v21, v21, v29
	v_max_f32_e32 v33, v14, v31
	v_min_f32_e32 v14, v14, v31
	v_max_f32_e32 v31, v17, v22
	v_min_f32_e32 v17, v17, v22
	v_max_f32_e32 v22, v101, v32
	v_min_f32_e32 v32, v101, v32
	v_max_f32_e32 v101, v9, v8
	v_min_f32_e32 v8, v9, v8
	v_max_f32_e32 v9, v7, v6
	v_min_f32_e32 v6, v7, v6
	v_max_f32_e32 v7, v16, v23
	v_min_f32_e32 v16, v16, v23
	v_max_f32_e32 v23, v25, v24
	v_min_f32_e32 v24, v25, v24
	v_max_f32_e32 v25, v30, v15
	v_min_f32_e32 v15, v30, v15
	v_max_f32_e32 v29, v10, v27
	v_min_f32_e32 v10, v10, v27
	v_max_f32_e32 v27, v13, v18
	v_min_f32_e32 v13, v13, v18
	v_max_f32_e32 v18, v109, v28
	v_min_f32_e32 v28, v109, v28
	v_max_f32_e32 v109, v5, v4
	v_min_f32_e32 v4, v5, v4
	v_max_f32_e32 v5, v3, v2
	v_min_f32_e32 v2, v3, v2
	v_max_f32_e32 v3, v12, v19
	v_min_f32_e32 v12, v12, v19
	v_max_f32_e32 v19, v21, v20
	v_min_f32_e32 v20, v21, v20
	v_max_f32_e32 v21, v26, v11
	v_min_f32_e32 v11, v26, v11
	v_max_f32_e32 v30, v33, v6
	v_min_f32_e32 v6, v33, v6
	v_max_f32_e32 v33, v14, v9
	v_min_f32_e32 v9, v14, v9
	v_max_f32_e32 v14, v31, v16
	v_min_f32_e32 v16, v31, v16
	v_max_f32_e32 v31, v17, v7
	v_min_f32_e32 v7, v17, v7
	v_max_f32_e32 v17, v22, v24
	v_min_f32_e32 v22, v22, v24
	v_max_f32_e32 v24, v32, v23
	v_min_f32_e32 v23, v32, v23
	v_max_f32_e32 v32, v101, v15
	v_min_f32_e32 v15, v101, v15
	v_max_f32_e32 v101, v8, v25
	v_min_f32_e32 v8, v8, v25
	v_max_f32_e32 v26, v29, v2
	v_min_f32_e32 v2, v29, v2
	v_max_f32_e32 v29, v10, v5
	v_min_f32_e32 v5, v10, v5
	v_max_f32_e32 v10, v27, v12
	v_min_f32_e32 v12, v27, v12
	v_max_f32_e32 v27, v13, v3
	v_min_f32_e32 v3, v13, v3
	v_max_f32_e32 v13, v18, v20
	v_min_f32_e32 v18, v18, v20
	v_max_f32_e32 v20, v28, v19
	v_min_f32_e32 v19, v28, v19
	v_max_f32_e32 v28, v109, v11
	v_min_f32_e32 v11, v109, v11
	v_max_f32_e32 v109, v4, v21
; DEV void peer_top16(const bf16_t* __restrict__ pq, const bf16_t* sk  , float (&l)[16]) {
;     ...
;   sort16_desc(l);
;   sort16_desc(hi);
; #pragma unroll
;   for (int i = 0; i < 16; i++) l[i] = fmaxf(l[i], hi[15 - i]);
;   bitonic16(l);
;   merge_xor(l, 16);
;   merge_xor(l, 32);
	v_min_f32_e32 v4, v4, v21
	v_max_f32_e32 v25, v30, v17
	v_min_f32_e32 v17, v30, v17
	v_max_f32_e32 v30, v33, v24
	v_min_f32_e32 v24, v33, v24
	v_max_f32_e32 v33, v14, v32
	v_min_f32_e32 v14, v14, v32
	v_max_f32_e32 v32, v31, v101
	v_min_f32_e32 v31, v31, v101
	v_max_f32_e32 v101, v6, v22
	v_min_f32_e32 v6, v6, v22
	v_max_f32_e32 v22, v9, v23
	v_min_f32_e32 v9, v9, v23
	v_max_f32_e32 v23, v16, v15
	v_min_f32_e32 v15, v16, v15
	v_max_f32_e32 v16, v7, v8
	v_min_f32_e32 v7, v7, v8
	v_max_f32_e32 v21, v26, v13
	v_min_f32_e32 v13, v26, v13
	v_max_f32_e32 v26, v29, v20
	v_min_f32_e32 v20, v29, v20
	v_max_f32_e32 v29, v10, v28
	v_min_f32_e32 v10, v10, v28
	v_max_f32_e32 v28, v27, v109
	v_min_f32_e32 v27, v27, v109
	v_max_f32_e32 v109, v2, v18
	v_min_f32_e32 v2, v2, v18
	v_max_f32_e32 v18, v5, v19
	v_min_f32_e32 v5, v5, v19
	v_max_f32_e32 v19, v12, v11
	v_min_f32_e32 v11, v12, v11
	v_max_f32_e32 v12, v3, v4
	v_min_f32_e32 v3, v3, v4
	v_max_f32_e32 v111, v0, v43
	v_min_f32_e32 v112, v104, v39
	v_max_f32_e32 v103, v104, v39
	v_min_f32_e32 v0, v0, v43
	v_max_f32_e32 v8, v25, v33
	v_min_f32_e32 v25, v25, v33
	v_max_f32_e32 v33, v30, v32
	v_min_f32_e32 v30, v30, v32
	v_max_f32_e32 v32, v17, v14
	v_min_f32_e32 v14, v17, v14
	v_max_f32_e32 v17, v24, v31
	v_min_f32_e32 v24, v24, v31
	v_max_f32_e32 v31, v101, v23
	v_min_f32_e32 v23, v101, v23
	v_max_f32_e32 v101, v22, v16
	v_min_f32_e32 v16, v22, v16
	v_max_f32_e32 v22, v6, v15
	v_min_f32_e32 v6, v6, v15
	v_max_f32_e32 v15, v9, v7
	v_min_f32_e32 v7, v9, v7
	v_max_f32_e32 v4, v21, v29
	v_min_f32_e32 v21, v21, v29
	v_max_f32_e32 v29, v26, v28
	v_min_f32_e32 v26, v26, v28
	v_max_f32_e32 v28, v13, v10
	v_min_f32_e32 v10, v13, v10
	v_max_f32_e32 v13, v20, v27
	v_min_f32_e32 v20, v20, v27
	v_max_f32_e32 v27, v109, v19
	v_min_f32_e32 v19, v109, v19
	v_max_f32_e32 v109, v18, v12
	v_min_f32_e32 v12, v18, v12
	v_max_f32_e32 v18, v2, v11
	v_min_f32_e32 v2, v2, v11
	v_max_f32_e32 v11, v5, v3
	v_min_f32_e32 v3, v5, v3
	v_min_f32_e32 v63, v107, v108
	v_min_f32_e32 v39, v111, v103
	v_max_f32_e32 v71, v107, v108
	v_max_f32_e32 v51, v111, v103
	v_max_f32_e32 v43, v0, v112
	v_min_f32_e32 v0, v0, v112
	v_min_f32_e32 v9, v8, v33
	v_min_f32_e32 v102, v25, v30
	v_min_f32_e32 v103, v32, v17
	v_min_f32_e32 v104, v14, v24
	v_min_f32_e32 v105, v31, v101
	v_min_f32_e32 v106, v23, v16
	v_min_f32_e32 v107, v22, v15
	v_min_f32_e32 v108, v6, v7
	v_min_f32_e32 v5, v4, v29
	v_min_f32_e32 v110, v21, v26
	v_min_f32_e32 v111, v28, v13
	v_min_f32_e32 v112, v10, v20
	v_min_f32_e32 v113, v27, v109
	v_min_f32_e32 v114, v19, v12
	v_min_f32_e32 v115, v18, v11
	v_min_f32_e32 v116, v2, v3
	v_max3_f32 v8, v8, v33, v116
	v_max3_f32 v2, v9, v2, v3
	v_max3_f32 v3, v25, v30, v115
	v_max3_f32 v9, v102, v18, v11
	v_max3_f32 v11, v32, v17, v114
	v_max3_f32 v12, v103, v19, v12
	v_max3_f32 v14, v14, v24, v113
	v_max3_f32 v17, v104, v27, v109
	v_max3_f32 v18, v31, v101, v112
	v_max3_f32 v10, v105, v10, v20
	v_max3_f32 v16, v23, v16, v111
	v_max3_f32 v13, v106, v28, v13
	v_max3_f32 v15, v22, v15, v110
	v_max3_f32 v19, v107, v21, v26
	v_max3_f32 v5, v6, v7, v5
	v_max3_f32 v4, v108, v4, v29
	v_max_f32_e32 v6, v8, v18
	v_min_f32_e32 v7, v8, v18
	v_max_f32_e32 v8, v2, v10
	v_min_f32_e32 v2, v2, v10
	v_max_f32_e32 v10, v3, v16
	v_min_f32_e32 v3, v3, v16
	v_max_f32_e32 v16, v9, v13
	v_min_f32_e32 v9, v9, v13
	v_max_f32_e32 v13, v11, v15
	v_min_f32_e32 v11, v11, v15
	v_max_f32_e32 v15, v12, v19
	v_min_f32_e32 v12, v12, v19
	v_max_f32_e32 v18, v14, v5
	v_min_f32_e32 v5, v14, v5
	v_max_f32_e32 v14, v17, v4
	v_min_f32_e32 v4, v17, v4
	v_max_f32_e32 v17, v6, v13
	v_min_f32_e32 v6, v6, v13
	v_max_f32_e32 v13, v8, v15
	v_min_f32_e32 v8, v8, v15
	v_max_f32_e32 v15, v10, v18
	v_min_f32_e32 v10, v10, v18
	v_max_f32_e32 v18, v16, v14
	v_min_f32_e32 v14, v16, v14
	v_max_f32_e32 v16, v7, v11
	v_min_f32_e32 v7, v7, v11
	v_max_f32_e32 v11, v2, v12
	v_min_f32_e32 v2, v2, v12
	v_max_f32_e32 v12, v3, v5
	v_min_f32_e32 v3, v3, v5
	v_max_f32_e32 v5, v9, v4
	v_min_f32_e32 v4, v9, v4
	v_max_f32_e32 v9, v17, v15
	v_min_f32_e32 v15, v17, v15
	v_max_f32_e32 v17, v13, v18
	v_min_f32_e32 v13, v13, v18
	v_max_f32_e32 v18, v6, v10
	v_min_f32_e32 v6, v6, v10
	v_max_f32_e32 v10, v8, v14
	v_min_f32_e32 v8, v8, v14
	v_max_f32_e32 v14, v16, v12
	v_min_f32_e32 v12, v16, v12
	v_max_f32_e32 v16, v11, v5
	v_min_f32_e32 v5, v11, v5
	v_max_f32_e32 v11, v7, v3
	v_min_f32_e32 v3, v7, v3
	v_max_f32_e32 v7, v2, v4
	v_min_f32_e32 v2, v2, v4
	v_max_f32_e32 v4, v9, v17
	v_min_f32_e32 v9, v9, v17
	v_max_f32_e32 v17, v15, v13
	v_min_f32_e32 v13, v15, v13
	v_max_f32_e32 v15, v18, v10
	v_min_f32_e32 v10, v18, v10
	v_max_f32_e32 v18, v6, v8
	v_min_f32_e32 v6, v6, v8
	v_max_f32_e32 v8, v14, v16
	v_min_f32_e32 v14, v14, v16
	v_max_f32_e32 v16, v12, v5
	v_min_f32_e32 v5, v12, v5
	v_max_f32_e32 v12, v11, v7
	v_min_f32_e32 v7, v11, v7
	v_max_f32_e32 v11, v3, v2
	v_min_f32_e32 v2, v3, v2
	ds_bpermute_b32 v3, v95, v2
	ds_bpermute_b32 v19, v95, v11
	ds_bpermute_b32 v20, v95, v7
	ds_bpermute_b32 v21, v95, v12
	ds_bpermute_b32 v22, v95, v5
	ds_bpermute_b32 v23, v95, v16
	s_waitcnt lgkmcnt(5)
	ds_bpermute_b32 v24, v95, v14
	ds_bpermute_b32 v33, v95, v4
	v_max_f32_e32 v3, v4, v3
	s_waitcnt lgkmcnt(6)
	ds_bpermute_b32 v25, v95, v8
	ds_bpermute_b32 v32, v95, v9
	v_max_f32_e32 v4, v9, v19
	s_waitcnt lgkmcnt(7)
	ds_bpermute_b32 v26, v95, v6
	ds_bpermute_b32 v31, v95, v17
	v_max_f32_e32 v9, v17, v20
	s_waitcnt lgkmcnt(8)
	ds_bpermute_b32 v27, v95, v18
	ds_bpermute_b32 v30, v95, v13
	v_max_f32_e32 v13, v13, v21
	s_waitcnt lgkmcnt(9)
	ds_bpermute_b32 v28, v95, v10
	ds_bpermute_b32 v29, v95, v15
	v_max_f32_e32 v15, v15, v22
	s_waitcnt lgkmcnt(10)
; DEV int tidx() { int t = threadIdx.x; asm volatile("" : "+v"(t)); return t; }
; DEV f32x4 mfma16(bf16x8 a, bf16x8 b, f32x4 c) { return __builtin_amdgcn_mfma_f32_16x16x32_bf16(a, b, c, 0, 0, 0); }
; DEV void merge_xor(float (&l)[16], int mask) {
;   float t[16];
; #pragma unroll
;   for (int i = 0; i < 16; i++) t[i] = __shfl_xor(l[15 - i], mask);
; #pragma unroll
;   for (int i = 0; i < 16; i++) l[i] = fmaxf(l[i], t[i]);
;   bitonic16(l);
; }
; DEV void peer_top16(const bf16_t* __restrict__ pq, const bf16_t* sk  , float (&l)[16]) {
;   const int lane = tidx() & 63, l15 = lane & 15, quad = lane >> 4;
;   f32x4 acc[8];
; #pragma unroll
;   for (int nt = 0; nt < 8; nt++) acc[nt] = (f32x4){0.f, 0.f, 0.f, 0.f};
; #pragma unroll 1
;   for (int ks = 0; ks < 4; ks++) {
;     const bf16x8 bqk = *(const bf16x8*)(pq + ks * 32 + quad * 8);
; #pragma unroll
;     for (int nt = 0; nt < 8; nt++) {
;       bf16x8 ak = *(const bf16x8*)(sk + (nt * 16 + l15) * 144 + ks * 32 + quad * 8);
;       acc[nt] = mfma16(ak, bqk, acc[nt]);
;     }
;   }
;   float hi[16];
; #pragma unroll
;   for (int nt = 0; nt < 4; nt++)
; #pragma unroll
;     for (int r = 0; r < 4; r++) {
;       l[nt * 4 + r] = __uint_as_float((__float_as_uint(acc[nt][r]) & ~127u) | (unsigned)(nt * 16 + quad * 4 + r));
;       hi[nt * 4 + r] = __uint_as_float((__float_as_uint(acc[nt + 4][r]) & ~127u) | (unsigned)((nt + 4) * 16 + quad * 4 + r));
;     }
;   sort16_desc(l);
;   sort16_desc(hi);
; #pragma unroll
;   for (int i = 0; i < 16; i++) l[i] = fmaxf(l[i], hi[15 - i]);
;   bitonic16(l);
;   merge_xor(l, 16);
;   merge_xor(l, 32);
; }
; DEV void phase_peer_score(const Params& p, int layer, int M, char* smem) {
;     ...
;     unsigned char* tab = (unsigned char*)smem + 73728 + (w * 16 + l15) * 32;
; #pragma unroll
;     for (int i = 0; i < 16; i++) { tab[i] = (unsigned char)(__float_as_uint(L0[i]) & 127u); tab[16 + i] = (unsigned char)(__float_as_uint(L1[i]) & 127u); }
	v_max_f32_e32 v10, v10, v23
	s_waitcnt lgkmcnt(9)
	v_max_f32_e32 v17, v18, v24
	s_waitcnt lgkmcnt(7)
	v_max_f32_e32 v6, v6, v25
	s_waitcnt lgkmcnt(5)
	v_max_f32_e32 v8, v8, v26
	s_waitcnt lgkmcnt(3)
	v_max_f32_e32 v14, v14, v27
	s_waitcnt lgkmcnt(1)
	v_max_f32_e32 v16, v16, v28
	s_waitcnt lgkmcnt(0)
	v_max_f32_e32 v5, v5, v29
	v_max_f32_e32 v12, v12, v30
	v_max_f32_e32 v7, v7, v31
	v_max_f32_e32 v11, v11, v32
	v_max_f32_e32 v2, v2, v33
	v_max_f32_e32 v18, v3, v8
	v_min_f32_e32 v3, v3, v8
	v_max_f32_e32 v8, v4, v14
	v_min_f32_e32 v4, v4, v14
	v_max_f32_e32 v14, v9, v16
	v_min_f32_e32 v9, v9, v16
	v_max_f32_e32 v16, v13, v5
	v_min_f32_e32 v5, v13, v5
	v_max_f32_e32 v13, v15, v12
	v_min_f32_e32 v12, v15, v12
	v_max_f32_e32 v15, v10, v7
	v_min_f32_e32 v7, v10, v7
	v_max_f32_e32 v10, v17, v11
	v_min_f32_e32 v11, v17, v11
	v_max_f32_e32 v17, v6, v2
	v_min_f32_e32 v2, v6, v2
	v_max_f32_e32 v6, v18, v13
	v_min_f32_e32 v13, v18, v13
	v_max_f32_e32 v18, v8, v15
	v_min_f32_e32 v8, v8, v15
	v_max_f32_e32 v15, v14, v10
	v_min_f32_e32 v10, v14, v10
	v_max_f32_e32 v14, v16, v17
	v_min_f32_e32 v16, v16, v17
	v_max_f32_e32 v17, v3, v12
	v_min_f32_e32 v3, v3, v12
	v_max_f32_e32 v12, v4, v7
	v_min_f32_e32 v4, v4, v7
	v_max_f32_e32 v7, v9, v11
	v_min_f32_e32 v9, v9, v11
	v_max_f32_e32 v11, v5, v2
	v_min_f32_e32 v2, v5, v2
	v_max_f32_e32 v5, v6, v15
	v_min_f32_e32 v6, v6, v15
	v_max_f32_e32 v15, v18, v14
	v_min_f32_e32 v14, v18, v14
	v_max_f32_e32 v18, v13, v10
	v_min_f32_e32 v10, v13, v10
	v_max_f32_e32 v13, v8, v16
	v_min_f32_e32 v8, v8, v16
	v_max_f32_e32 v16, v17, v7
	v_min_f32_e32 v7, v17, v7
	v_max_f32_e32 v17, v12, v11
	v_min_f32_e32 v11, v12, v11
	v_max_f32_e32 v12, v3, v9
	v_min_f32_e32 v3, v3, v9
	v_max_f32_e32 v9, v4, v2
	v_min_f32_e32 v2, v4, v2
	v_max_f32_e32 v4, v5, v15
	v_min_f32_e32 v5, v5, v15
	v_max_f32_e32 v15, v6, v14
	v_min_f32_e32 v6, v6, v14
	v_max_f32_e32 v14, v18, v13
	v_min_f32_e32 v13, v18, v13
	v_max_f32_e32 v18, v10, v8
	v_min_f32_e32 v8, v10, v8
	v_max_f32_e32 v10, v16, v17
	v_min_f32_e32 v16, v16, v17
	v_max_f32_e32 v17, v7, v11
	v_min_f32_e32 v7, v7, v11
	v_max_f32_e32 v11, v12, v9
	v_min_f32_e32 v9, v12, v9
	v_max_f32_e32 v12, v3, v2
	v_min_f32_e32 v2, v3, v2
	ds_bpermute_b32 v3, v99, v2
	ds_bpermute_b32 v19, v99, v12
	ds_bpermute_b32 v20, v99, v9
	ds_bpermute_b32 v21, v99, v11
	ds_bpermute_b32 v22, v99, v7
	ds_bpermute_b32 v23, v99, v17
	s_waitcnt lgkmcnt(5)
	ds_bpermute_b32 v24, v99, v16
	ds_bpermute_b32 v33, v99, v4
	v_max_f32_e32 v3, v4, v3
	s_waitcnt lgkmcnt(6)
	ds_bpermute_b32 v25, v99, v10
	ds_bpermute_b32 v32, v99, v5
	v_max_f32_e32 v4, v5, v19
	s_waitcnt lgkmcnt(7)
	ds_bpermute_b32 v26, v99, v8
	ds_bpermute_b32 v31, v99, v15
	v_max_f32_e32 v5, v15, v20
	s_waitcnt lgkmcnt(8)
	ds_bpermute_b32 v27, v99, v18
	ds_bpermute_b32 v30, v99, v6
	v_max_f32_e32 v6, v6, v21
	s_waitcnt lgkmcnt(9)
	ds_bpermute_b32 v28, v99, v13
	ds_bpermute_b32 v29, v99, v14
	v_max_f32_e32 v14, v14, v22
	s_waitcnt lgkmcnt(10)
	v_max_f32_e32 v13, v13, v23
	s_waitcnt lgkmcnt(9)
	v_max_f32_e32 v15, v18, v24
	s_waitcnt lgkmcnt(7)
	v_max_f32_e32 v8, v8, v25
	s_waitcnt lgkmcnt(5)
	v_max_f32_e32 v10, v10, v26
	s_waitcnt lgkmcnt(3)
	v_max_f32_e32 v16, v16, v27
	s_waitcnt lgkmcnt(1)
	v_max_f32_e32 v17, v17, v28
	s_waitcnt lgkmcnt(0)
	v_max_f32_e32 v7, v7, v29
	v_max_f32_e32 v11, v11, v30
	v_max_f32_e32 v9, v9, v31
	v_max_f32_e32 v12, v12, v32
	v_max_f32_e32 v2, v2, v33
	v_max_f32_e32 v18, v3, v10
	v_min_f32_e32 v3, v3, v10
	v_max_f32_e32 v10, v4, v16
	v_min_f32_e32 v4, v4, v16
	v_max_f32_e32 v16, v5, v17
	v_min_f32_e32 v5, v5, v17
	v_max_f32_e32 v17, v6, v7
	v_min_f32_e32 v6, v6, v7
	v_max_f32_e32 v7, v14, v11
	v_min_f32_e32 v11, v14, v11
	v_max_f32_e32 v14, v13, v9
	v_min_f32_e32 v9, v13, v9
	v_max_f32_e32 v13, v15, v12
	v_min_f32_e32 v12, v15, v12
	v_max_f32_e32 v15, v8, v2
	v_min_f32_e32 v2, v8, v2
	v_max_f32_e32 v8, v18, v7
	v_min_f32_e32 v7, v18, v7
	v_max_f32_e32 v18, v10, v14
	v_min_f32_e32 v10, v10, v14
	v_max_f32_e32 v14, v16, v13
	v_min_f32_e32 v13, v16, v13
	v_max_f32_e32 v16, v17, v15
	v_min_f32_e32 v15, v17, v15
	v_max_f32_e32 v17, v3, v11
	v_min_f32_e32 v3, v3, v11
	v_max_f32_e32 v11, v4, v9
	v_min_f32_e32 v4, v4, v9
	v_max_f32_e32 v9, v5, v12
	v_min_f32_e32 v5, v5, v12
	v_max_f32_e32 v12, v6, v2
	v_min_f32_e32 v2, v6, v2
	v_max_f32_e32 v6, v8, v14
	v_min_f32_e32 v8, v8, v14
	v_max_f32_e32 v14, v18, v16
	v_min_f32_e32 v16, v18, v16
	v_max_f32_e32 v18, v7, v13
	v_max_f32_e32 v19, v10, v15
	s_movk_i32 s0, 0x7f
	v_min_f32_e32 v13, v7, v13
	v_min_f32_e32 v10, v10, v15
	v_max_f32_e32 v15, v17, v9
	v_min_f32_e32 v21, v17, v9
	v_max_f32_e32 v17, v11, v12
	v_min_f32_e32 v22, v11, v12
	v_max_f32_e32 v23, v3, v5
	v_min_f32_e32 v3, v3, v5
	v_max_f32_e32 v5, v4, v2
	v_min_f32_e32 v24, v4, v2
	v_max_f32_e32 v9, v18, v19
	v_min_f32_e32 v12, v18, v19
	v_and_b32_sdwa v18, v63, s0 dst_sel:BYTE_1 dst_unused:UNUSED_PAD src0_sel:DWORD src1_sel:DWORD
	v_max_f32_e32 v2, v6, v14
	v_min_f32_e32 v4, v6, v14
	v_max_f32_e32 v11, v13, v10
	v_min_f32_e32 v10, v13, v10
	v_max_f32_e32 v14, v23, v5
	v_min_f32_e32 v13, v23, v5
	v_max_f32_e32 v6, v3, v24
	v_min_f32_e32 v5, v3, v24
	v_and_b32_sdwa v3, v75, s0 dst_sel:BYTE_1 dst_unused:UNUSED_PAD src0_sel:DWORD src1_sel:DWORD
	v_bitop3_b16 v18, v71, v18, s0 bitop3:0xec
	v_bitop3_b16 v3, v79, v3, s0 bitop3:0xec
	v_lshlrev_b32_e32 v18, 16, v18
	v_or_b32_sdwa v23, v3, v18 dst_sel:DWORD dst_unused:UNUSED_PAD src0_sel:WORD_0 src1_sel:DWORD
	v_and_b32_sdwa v18, v83, s0 dst_sel:BYTE_1 dst_unused:UNUSED_PAD src0_sel:DWORD src1_sel:DWORD
	v_and_b32_sdwa v3, v91, s0 dst_sel:BYTE_1 dst_unused:UNUSED_PAD src0_sel:DWORD src1_sel:DWORD
; DEV void ce(float& a, float& b) { float hi = fmaxf(a, b), lo = fminf(a, b); a = hi; b = lo; }
; DEV void phase_peer_score(const Params& p, int layer, int M, char* smem) {
;     ...
;     for (int i = 0; i < 16; i++) R[i] = -3.0e38f;
; #pragma unroll
;     for (int i = 0; i < 16; i++)
; #pragma unroll
;       for (int j = 0; j < 16; j++)
;         if ((i + 1) * (j + 1) <= 16) {
;           float v = L0[i] + L1[j];
;           v = __uint_as_float((__float_as_uint(v) & ~255u) | (unsigned)(i * 16 + j));
; #pragma unroll
;           for (int t = 0; t < 16; t++)
;             if (t >= (i + 1) * (j + 1) - 1) ce(R[t], v);
;         }
;     unsigned char* tab = (unsigned char*)smem + 73728 + (w * 16 + l15) * 32;
; #pragma unroll
;     for (int i = 0; i < 16; i++) { tab[i] = (unsigned char)(__float_as_uint(L0[i]) & 127u); tab[16 + i] = (unsigned char)(__float_as_uint(L1[i]) & 127u); }
	v_bitop3_b16 v18, v87, v18, s0 bitop3:0xec
	v_bitop3_b16 v3, v100, v3, s0 bitop3:0xec
	v_lshlrev_b32_e32 v18, 16, v18
	v_max_f32_e32 v7, v8, v16
	v_min_f32_e32 v8, v8, v16
	v_max_f32_e32 v20, v15, v17
	v_min_f32_e32 v17, v15, v17
	v_max_f32_e32 v16, v21, v22
	v_min_f32_e32 v15, v21, v22
	v_or_b32_sdwa v22, v3, v18 dst_sel:DWORD dst_unused:UNUSED_PAD src0_sel:WORD_0 src1_sel:DWORD
	v_and_b32_sdwa v18, v10, s0 dst_sel:BYTE_1 dst_unused:UNUSED_PAD src0_sel:DWORD src1_sel:DWORD
	v_and_b32_sdwa v3, v12, s0 dst_sel:BYTE_1 dst_unused:UNUSED_PAD src0_sel:DWORD src1_sel:DWORD
	v_bitop3_b16 v18, v11, v18, s0 bitop3:0xec
	v_bitop3_b16 v3, v9, v3, s0 bitop3:0xec
	v_lshlrev_b32_e32 v18, 16, v18
	v_or_b32_sdwa v27, v3, v18 dst_sel:DWORD dst_unused:UNUSED_PAD src0_sel:WORD_0 src1_sel:DWORD
	v_and_b32_sdwa v18, v8, s0 dst_sel:BYTE_1 dst_unused:UNUSED_PAD src0_sel:DWORD src1_sel:DWORD
	v_and_b32_sdwa v3, v4, s0 dst_sel:BYTE_1 dst_unused:UNUSED_PAD src0_sel:DWORD src1_sel:DWORD
	v_bitop3_b16 v18, v7, v18, s0 bitop3:0xec
	v_bitop3_b16 v3, v2, v3, s0 bitop3:0xec
	v_lshlrev_b32_e32 v18, 16, v18
	v_or_b32_sdwa v26, v3, v18 dst_sel:DWORD dst_unused:UNUSED_PAD src0_sel:WORD_0 src1_sel:DWORD
	v_and_b32_sdwa v18, v0, s0 dst_sel:BYTE_1 dst_unused:UNUSED_PAD src0_sel:DWORD src1_sel:DWORD
	v_and_b32_sdwa v3, v39, s0 dst_sel:BYTE_1 dst_unused:UNUSED_PAD src0_sel:DWORD src1_sel:DWORD
	v_bitop3_b16 v18, v43, v18, s0 bitop3:0xec
	v_bitop3_b16 v3, v51, v3, s0 bitop3:0xec
	v_lshlrev_b32_e32 v18, 16, v18
	v_or_b32_sdwa v25, v3, v18 dst_sel:DWORD dst_unused:UNUSED_PAD src0_sel:WORD_0 src1_sel:DWORD
	v_and_b32_sdwa v18, v47, s0 dst_sel:BYTE_1 dst_unused:UNUSED_PAD src0_sel:DWORD src1_sel:DWORD
	v_and_b32_sdwa v3, v59, s0 dst_sel:BYTE_1 dst_unused:UNUSED_PAD src0_sel:DWORD src1_sel:DWORD
	v_bitop3_b16 v18, v55, v18, s0 bitop3:0xec
	v_bitop3_b16 v3, v67, v3, s0 bitop3:0xec
	v_lshlrev_b32_e32 v18, 16, v18
	v_or_b32_sdwa v24, v3, v18 dst_sel:DWORD dst_unused:UNUSED_PAD src0_sel:WORD_0 src1_sel:DWORD
	v_and_b32_sdwa v18, v5, s0 dst_sel:BYTE_1 dst_unused:UNUSED_PAD src0_sel:DWORD src1_sel:DWORD
	v_and_b32_sdwa v3, v13, s0 dst_sel:BYTE_1 dst_unused:UNUSED_PAD src0_sel:DWORD src1_sel:DWORD
	v_bitop3_b16 v18, v6, v18, s0 bitop3:0xec
	v_bitop3_b16 v3, v14, v3, s0 bitop3:0xec
	v_lshlrev_b32_e32 v18, 16, v18
	v_or_b32_sdwa v29, v3, v18 dst_sel:DWORD dst_unused:UNUSED_PAD src0_sel:WORD_0 src1_sel:DWORD
	v_and_b32_sdwa v18, v15, s0 dst_sel:BYTE_1 dst_unused:UNUSED_PAD src0_sel:DWORD src1_sel:DWORD
	v_and_b32_sdwa v3, v17, s0 dst_sel:BYTE_1 dst_unused:UNUSED_PAD src0_sel:DWORD src1_sel:DWORD
	v_bitop3_b16 v18, v16, v18, s0 bitop3:0xec
	v_bitop3_b16 v3, v20, v3, s0 bitop3:0xec
	v_lshlrev_b32_e32 v18, 16, v18
	v_or_b32_sdwa v28, v3, v18 dst_sel:DWORD dst_unused:UNUSED_PAD src0_sel:WORD_0 src1_sel:DWORD
	ds_write_b128 v138, v[22:25]
	ds_write_b128 v138, v[26:29] offset:16
	s_and_saveexec_b64 s[14:15], s[38:39]
	s_cbranch_execz .LBB0_162
	s_lshl_b32 s0, s18, 3
	v_add_f32_e32 v3, v100, v2
	s_andn2_b32 s0, s0, 63
	v_and_b32_e32 v3, 0xffffff00, v3
	v_add_u32_e32 v18, s0, v117
	v_add_f32_e32 v22, v100, v4
	s_movk_i32 s0, 0xff00
	v_min_f32_e32 v21, 0xff61b1e6, v3
	v_and_or_b32 v22, v22, s0, 1
	v_max_f32_e32 v21, 0xff61b1e6, v21
	v_add_f32_e32 v24, v100, v7
	v_min_f32_e32 v23, v21, v22
	v_and_or_b32 v24, v24, s0, 2
	v_max_f32_e32 v23, v21, v23
	v_add_f32_e32 v26, v100, v8
	v_min_f32_e32 v25, v23, v24
	v_and_or_b32 v26, v26, s0, 3
	v_max_f32_e32 v25, v23, v25
	v_add_f32_e32 v28, v100, v9
	v_min_f32_e32 v27, v25, v26
	v_and_or_b32 v28, v28, s0, 4
	v_max_f32_e32 v27, v25, v27
	v_add_f32_e32 v30, v100, v12
	v_min_f32_e32 v29, v27, v28
	v_and_or_b32 v30, v30, s0, 5
	v_max_f32_e32 v29, v27, v29
	v_add_f32_e32 v32, v100, v11
	v_min_f32_e32 v31, v29, v30
	v_and_or_b32 v32, v32, s0, 6
	v_max_f32_e32 v31, v29, v31
	v_add_f32_e32 v95, v100, v10
	v_min_f32_e32 v33, v31, v32
	v_and_or_b32 v95, v95, s0, 7
	v_max_f32_e32 v33, v31, v33
	v_add_f32_e32 v20, v100, v20
	v_min_f32_e32 v99, v33, v95
	v_and_or_b32 v20, v20, s0, 8
	v_max_f32_e32 v99, v33, v99
	v_add_f32_e32 v17, v100, v17
	v_min_f32_e32 v101, v99, v20
	v_and_or_b32 v17, v17, s0, 9
	v_max_f32_e32 v101, v99, v101
	v_add_f32_e32 v16, v100, v16
	v_min_f32_e32 v102, v101, v17
	v_and_or_b32 v16, v16, s0, 10
	v_max_f32_e32 v102, v101, v102
	v_add_f32_e32 v15, v100, v15
	v_min_f32_e32 v103, v102, v16
	v_and_or_b32 v15, v15, s0, 11
	v_max_f32_e32 v103, v102, v103
	v_add_f32_e32 v14, v100, v14
	v_min_f32_e32 v104, v103, v15
	v_and_or_b32 v14, v14, s0, 12
	v_max_f32_e32 v104, v103, v104
	v_add_f32_e32 v13, v100, v13
	v_min_f32_e32 v105, v104, v14
	v_and_or_b32 v13, v13, s0, 13
	v_max_f32_e32 v105, v104, v105
	v_add_f32_e32 v6, v100, v6
	v_min_f32_e32 v106, v105, v13
	v_and_or_b32 v6, v6, s0, 14
	v_max_f32_e32 v106, v105, v106
	v_add_f32_e32 v5, v100, v5
	v_min_f32_e32 v107, v106, v6
	v_and_or_b32 v5, v5, s0, 15
	v_max3_f32 v100, v106, v107, v5
	v_max_f32_e32 v106, v106, v6
	v_add_f32_e32 v6, v91, v2
	v_and_or_b32 v6, v6, s0, 16
	v_max_f32_e32 v5, v21, v22
	v_max_f32_e32 v23, v23, v24
	v_min_f32_e32 v21, v5, v6
	v_max_f32_e32 v25, v25, v26
	v_min_f32_e32 v22, v23, v21
	v_min_f32_e32 v24, v25, v22
	v_max_f32_e32 v22, v25, v22
	v_add_f32_e32 v25, v91, v4
	v_and_or_b32 v25, v25, s0, 17
	v_max_f32_e32 v27, v27, v28
	v_max_f32_e32 v29, v29, v30
	v_min_f32_e32 v26, v27, v24
	v_max_f32_e32 v24, v27, v24
	v_min_f32_e32 v27, v22, v25
	v_max_f32_e32 v31, v31, v32
	v_min_f32_e32 v28, v29, v26
	v_max_f32_e32 v26, v29, v26
	v_min_f32_e32 v29, v24, v27
	v_min_f32_e32 v30, v31, v28
	v_max_f32_e32 v28, v31, v28
	v_min_f32_e32 v31, v26, v29
	v_max_f32_e32 v26, v26, v29
; DEV void ce(float& a, float& b) { float hi = fmaxf(a, b), lo = fminf(a, b); a = hi; b = lo; }
; DEV void phase_peer_score(const Params& p, int layer, int M, char* smem) {
;     ...
;     for (int i = 0; i < 16; i++)
; #pragma unroll
;       for (int j = 0; j < 16; j++)
;         if ((i + 1) * (j + 1) <= 16) {
;           float v = L0[i] + L1[j];
;           v = __uint_as_float((__float_as_uint(v) & ~255u) | (unsigned)(i * 16 + j));
; #pragma unroll
;           for (int t = 0; t < 16; t++)
;             if (t >= (i + 1) * (j + 1) - 1) ce(R[t], v);
;         }
	v_add_f32_e32 v29, v91, v7
	v_max_f32_e32 v33, v33, v95
	v_and_or_b32 v29, v29, s0, 18
	v_max_f32_e32 v20, v99, v20
	v_min_f32_e32 v32, v33, v30
	v_min_f32_e32 v95, v20, v32
	v_max_f32_e32 v20, v20, v32
	v_max_f32_e32 v30, v33, v30
	v_min_f32_e32 v32, v28, v31
	v_max_f32_e32 v28, v28, v31
	v_min_f32_e32 v31, v26, v29
	v_max_f32_e32 v17, v101, v17
	v_min_f32_e32 v33, v30, v32
	v_max_f32_e32 v30, v30, v32
	v_min_f32_e32 v32, v28, v31
	v_min_f32_e32 v99, v17, v95
	v_max_f32_e32 v17, v17, v95
	v_min_f32_e32 v95, v20, v33
	v_max_f32_e32 v20, v20, v33
	v_min_f32_e32 v33, v30, v32
	v_max_f32_e32 v30, v30, v32
	v_add_f32_e32 v32, v91, v8
	v_and_or_b32 v32, v32, s0, 19
	v_max_f32_e32 v16, v102, v16
	v_max_f32_e32 v15, v103, v15
	v_min_f32_e32 v101, v16, v99
	v_max_f32_e32 v16, v16, v99
	v_min_f32_e32 v99, v17, v95
	v_max_f32_e32 v17, v17, v95
	v_min_f32_e32 v95, v20, v33
	v_max_f32_e32 v20, v20, v33
	v_min_f32_e32 v33, v30, v32
	v_max_f32_e32 v14, v104, v14
	v_min_f32_e32 v102, v15, v101
	v_max_f32_e32 v15, v15, v101
	v_min_f32_e32 v101, v16, v99
	v_max_f32_e32 v16, v16, v99
	v_min_f32_e32 v99, v17, v95
	v_max_f32_e32 v17, v17, v95
	v_min_f32_e32 v95, v20, v33
	v_min_f32_e32 v103, v14, v102
	v_max_f32_e32 v14, v14, v102
	v_min_f32_e32 v102, v15, v101
	v_max_f32_e32 v15, v15, v101
	v_min_f32_e32 v101, v16, v99
	v_max_f32_e32 v16, v16, v99
	v_min_f32_e32 v99, v17, v95
	v_max_f32_e32 v17, v17, v95
	v_add_f32_e32 v95, v91, v9
	v_max_f32_e32 v13, v105, v13
	v_and_or_b32 v95, v95, s0, 20
	v_min_f32_e32 v104, v13, v103
	v_max_f32_e32 v13, v13, v103
	v_min_f32_e32 v103, v14, v102
	v_min_f32_e32 v105, v106, v104
	v_max_f32_e32 v104, v106, v104
	v_min_f32_e32 v106, v13, v103
	v_max_f32_e32 v14, v14, v102
	v_min_f32_e32 v102, v15, v101
	v_max_f32_e32 v15, v15, v101
	v_min_f32_e32 v101, v16, v99
	v_max_f32_e32 v16, v16, v99
	v_min_f32_e32 v99, v17, v95
	v_add_f32_e32 v12, v91, v12
	v_min_f32_e32 v107, v104, v106
	v_max_f32_e32 v13, v13, v103
	v_min_f32_e32 v103, v14, v102
	v_max_f32_e32 v14, v14, v102
	v_min_f32_e32 v102, v15, v101
	v_max_f32_e32 v15, v15, v101
	v_min_f32_e32 v101, v16, v99
	v_and_or_b32 v12, v12, s0, 21
	v_max_f32_e32 v21, v23, v21
	v_add_f32_e32 v23, v87, v2
	v_max3_f32 v100, v100, v105, v107
	v_max_f32_e32 v104, v104, v106
	v_min_f32_e32 v105, v13, v103
	v_max_f32_e32 v13, v13, v103
	v_min_f32_e32 v103, v14, v102
	v_max_f32_e32 v14, v14, v102
	v_min_f32_e32 v102, v15, v101
	v_max_f32_e32 v15, v15, v101
	v_and_or_b32 v23, v23, s0, 32
	v_min_f32_e32 v106, v104, v105
	v_max_f32_e32 v104, v104, v105
	v_min_f32_e32 v105, v13, v103
	v_max_f32_e32 v13, v13, v103
	v_min_f32_e32 v103, v14, v102
	v_max_f32_e32 v14, v14, v102
	v_min_f32_e32 v101, v15, v12
	v_add_f32_e32 v11, v91, v11
	v_min_f32_e32 v107, v104, v105
	v_max_f32_e32 v104, v104, v105
	v_min_f32_e32 v105, v13, v103
	v_max_f32_e32 v13, v13, v103
	v_min_f32_e32 v102, v14, v101
	v_and_or_b32 v11, v11, s0, 22
	v_max_f32_e32 v22, v22, v25
	v_min_f32_e32 v25, v21, v23
	v_min_f32_e32 v103, v13, v102
	v_max_f32_e32 v13, v13, v102
	v_max_f32_e32 v24, v24, v27
	v_min_f32_e32 v27, v22, v25
	v_min_f32_e32 v102, v13, v11
	v_max_f32_e32 v11, v13, v11
	v_max_f32_e32 v13, v14, v101
	v_max_f32_e32 v14, v16, v99
	v_max_f32_e32 v16, v20, v33
	v_max_f32_e32 v20, v28, v31
	v_max_f32_e32 v26, v26, v29
	v_min_f32_e32 v28, v24, v27
	v_min_f32_e32 v29, v26, v28
	v_max_f32_e32 v26, v26, v28
	v_add_f32_e32 v28, v87, v4
	v_and_or_b32 v28, v28, s0, 33
	v_max_f32_e32 v12, v15, v12
	v_max_f32_e32 v15, v17, v95
	v_max_f32_e32 v17, v30, v32
	v_min_f32_e32 v30, v20, v29
	v_max_f32_e32 v20, v20, v29
	v_min_f32_e32 v29, v26, v28
	v_min_f32_e32 v31, v17, v30
	v_max_f32_e32 v17, v17, v30
	v_min_f32_e32 v30, v20, v29
	v_min_f32_e32 v32, v16, v31
	v_max_f32_e32 v16, v16, v31
	v_min_f32_e32 v31, v17, v30
	v_min_f32_e32 v33, v15, v32
	v_max_f32_e32 v15, v15, v32
	v_min_f32_e32 v32, v16, v31
	v_max_f32_e32 v16, v16, v31
	v_add_f32_e32 v31, v87, v7
	v_and_or_b32 v31, v31, s0, 34
	v_max3_f32 v100, v100, v106, v107
	v_min_f32_e32 v106, v104, v105
	v_max_f32_e32 v104, v104, v105
	v_min_f32_e32 v105, v104, v103
	v_max_f32_e32 v103, v104, v103
	v_add_f32_e32 v10, v91, v10
	v_min_f32_e32 v95, v14, v33
	v_max_f32_e32 v14, v14, v33
	v_min_f32_e32 v33, v15, v32
	v_max_f32_e32 v15, v15, v32
	v_min_f32_e32 v32, v16, v31
	v_max_f32_e32 v22, v22, v25
	v_add_f32_e32 v25, v83, v2
	v_max3_f32 v100, v100, v106, v105
	v_min_f32_e32 v104, v103, v102
	v_and_or_b32 v10, v10, s0, 23
	v_min_f32_e32 v99, v12, v95
	v_max_f32_e32 v12, v12, v95
	v_min_f32_e32 v95, v14, v33
	v_max_f32_e32 v14, v14, v33
	v_min_f32_e32 v33, v15, v32
	v_and_or_b32 v25, v25, s0, 48
	v_max3_f32 v10, v100, v104, v10
	v_min_f32_e32 v100, v13, v99
	v_max_f32_e32 v13, v13, v99
	v_min_f32_e32 v99, v12, v95
	v_max_f32_e32 v12, v12, v95
	v_min_f32_e32 v95, v14, v33
	v_min_f32_e32 v101, v11, v100
	v_max_f32_e32 v11, v11, v100
	v_min_f32_e32 v100, v13, v99
	v_max_f32_e32 v13, v13, v99
	v_min_f32_e32 v99, v12, v95
	v_max_f32_e32 v12, v12, v95
	v_add_f32_e32 v95, v87, v8
	v_max_f32_e32 v24, v24, v27
	v_min_f32_e32 v27, v22, v25
	v_and_or_b32 v95, v95, s0, 35
	v_max_f32_e32 v26, v26, v28
	v_min_f32_e32 v28, v24, v27
	v_max_f32_e32 v91, v103, v102
	v_max_f32_e32 v20, v20, v29
	v_min_f32_e32 v29, v26, v28
	v_min_f32_e32 v102, v91, v101
	v_max_f32_e32 v91, v91, v101
	v_min_f32_e32 v101, v11, v100
	v_max_f32_e32 v11, v11, v100
	v_min_f32_e32 v100, v13, v99
	v_max_f32_e32 v13, v13, v99
	v_min_f32_e32 v99, v12, v95
	v_max_f32_e32 v17, v17, v30
	v_min_f32_e32 v30, v20, v29
	v_min_f32_e32 v103, v91, v101
	v_max_f32_e32 v91, v91, v101
	v_min_f32_e32 v101, v11, v100
	v_max_f32_e32 v11, v11, v100
; DEV void ce(float& a, float& b) { float hi = fmaxf(a, b), lo = fminf(a, b); a = hi; b = lo; }
; DEV void phase_peer_score(const Params& p, int layer, int M, char* smem) {
;     ...
;     for (int i = 0; i < 16; i++)
; #pragma unroll
;       for (int j = 0; j < 16; j++)
;         if ((i + 1) * (j + 1) <= 16) {
;           float v = L0[i] + L1[j];
;           v = __uint_as_float((__float_as_uint(v) & ~255u) | (unsigned)(i * 16 + j));
; #pragma unroll
;           for (int t = 0; t < 16; t++)
;             if (t >= (i + 1) * (j + 1) - 1) ce(R[t], v);
;         }
	v_min_f32_e32 v100, v13, v99
	v_add_f32_e32 v9, v87, v9
	v_max_f32_e32 v16, v16, v31
	v_min_f32_e32 v31, v17, v30
	v_max3_f32 v10, v10, v102, v103
	v_min_f32_e32 v102, v91, v101
	v_max_f32_e32 v91, v91, v101
	v_min_f32_e32 v101, v11, v100
	v_and_or_b32 v9, v9, s0, 36
	v_max_f32_e32 v15, v15, v32
	v_min_f32_e32 v32, v16, v31
	v_min_f32_e32 v103, v91, v101
	v_max_f32_e32 v91, v91, v101
	v_max_f32_e32 v14, v14, v33
	v_min_f32_e32 v33, v15, v32
	v_max_f32_e32 v17, v17, v30
	v_add_f32_e32 v30, v83, v4
	v_min_f32_e32 v87, v91, v9
	v_max_f32_e32 v9, v91, v9
	v_max_f32_e32 v12, v12, v95
	v_min_f32_e32 v91, v14, v33
	v_and_or_b32 v30, v30, s0, 49
	v_max_f32_e32 v24, v24, v27
	v_add_f32_e32 v27, v79, v2
	v_max_f32_e32 v13, v13, v99
	v_min_f32_e32 v95, v12, v91
	v_and_or_b32 v27, v27, s0, 64
	v_max_f32_e32 v11, v11, v100
	v_min_f32_e32 v99, v13, v95
	v_max_f32_e32 v16, v16, v31
	v_min_f32_e32 v31, v17, v30
	v_min_f32_e32 v100, v11, v99
	v_max_f32_e32 v15, v15, v32
	v_min_f32_e32 v32, v16, v31
	v_max_f32_e32 v26, v26, v28
	v_min_f32_e32 v28, v24, v27
	v_max3_f32 v10, v10, v102, v103
	v_min_f32_e32 v101, v9, v100
	v_max_f32_e32 v14, v14, v33
	v_min_f32_e32 v33, v15, v32
	v_max_f32_e32 v20, v20, v29
	v_min_f32_e32 v29, v26, v28
	v_max3_f32 v10, v10, v87, v101
	v_max_f32_e32 v12, v12, v91
	v_min_f32_e32 v87, v14, v33
	v_max_f32_e32 v17, v17, v30
	v_min_f32_e32 v30, v20, v29
	v_min_f32_e32 v91, v12, v87
	v_max_f32_e32 v12, v12, v87
	v_add_f32_e32 v87, v83, v7
	v_max_f32_e32 v16, v16, v31
	v_min_f32_e32 v31, v17, v30
	v_and_or_b32 v87, v87, s0, 50
	v_max_f32_e32 v15, v15, v32
	v_min_f32_e32 v32, v16, v31
	v_max_f32_e32 v13, v13, v95
	v_max_f32_e32 v14, v14, v33
	v_min_f32_e32 v33, v15, v32
	v_max_f32_e32 v11, v11, v99
	v_min_f32_e32 v95, v13, v91
	v_max_f32_e32 v13, v13, v91
	v_min_f32_e32 v91, v12, v87
	v_add_f32_e32 v8, v83, v8
	v_max_f32_e32 v12, v12, v87
	v_min_f32_e32 v83, v14, v33
	v_max_f32_e32 v9, v9, v100
	v_min_f32_e32 v99, v11, v95
	v_max_f32_e32 v11, v11, v95
	v_min_f32_e32 v95, v13, v91
	v_max_f32_e32 v13, v13, v91
	v_min_f32_e32 v87, v12, v83
	v_min_f32_e32 v100, v9, v99
	v_max_f32_e32 v9, v9, v99
	v_min_f32_e32 v99, v11, v95
	v_max_f32_e32 v11, v11, v95
	v_min_f32_e32 v91, v13, v87
	v_min_f32_e32 v101, v9, v99
	v_max_f32_e32 v9, v9, v99
	v_min_f32_e32 v95, v11, v91
	v_max3_f32 v10, v10, v100, v101
	v_and_or_b32 v8, v8, s0, 51
	v_min_f32_e32 v99, v9, v95
	v_max3_f32 v8, v10, v8, v99
	v_max_f32_e32 v10, v11, v91
	v_max_f32_e32 v11, v13, v87
	v_max_f32_e32 v13, v14, v33
	v_max_f32_e32 v14, v15, v32
	v_add_f32_e32 v15, v79, v4
	v_and_b32_e32 v15, 0xffffff00, v15
	v_or_b32_e32 v15, 0x41, v15
	v_min_f32_e32 v32, v14, v15
	v_max_f32_e32 v12, v12, v83
	v_min_f32_e32 v33, v13, v32
	v_min_f32_e32 v83, v12, v33
	v_add_f32_e32 v7, v79, v7
	v_min_f32_e32 v87, v11, v83
	v_and_b32_e32 v7, 0xffffff00, v7
	v_max_f32_e32 v9, v9, v95
	v_min_f32_e32 v91, v10, v87
	v_or_b32_e32 v7, 0x42, v7
	v_min_f32_e32 v95, v9, v91
	v_max_f32_e32 v9, v9, v91
	v_min_f32_e32 v79, v9, v7
	v_max_f32_e32 v7, v9, v7
	v_max_f32_e32 v9, v10, v87
	v_max_f32_e32 v10, v11, v83
	v_max_f32_e32 v11, v12, v33
	v_max_f32_e32 v12, v13, v32
	v_max_f32_e32 v13, v14, v15
	v_max_f32_e32 v14, v16, v31
	v_max_f32_e32 v16, v20, v29
	v_add_f32_e32 v20, v75, v2
	v_and_b32_e32 v20, 0xffffff00, v20
	v_or_b32_e32 v20, 0x50, v20
	v_max_f32_e32 v15, v17, v30
	v_max_f32_e32 v17, v26, v28
	v_min_f32_e32 v26, v17, v20
	v_min_f32_e32 v28, v16, v26
	v_max_f32_e32 v16, v16, v26
	v_add_f32_e32 v26, v71, v2
	v_and_b32_e32 v26, 0xffffff00, v26
	v_min_f32_e32 v29, v15, v28
	v_or_b32_e32 v26, 0x60, v26
	v_min_f32_e32 v30, v14, v29
	v_min_f32_e32 v31, v13, v30
	v_max_f32_e32 v15, v15, v28
	v_min_f32_e32 v28, v16, v26
	v_min_f32_e32 v32, v12, v31
	v_max_f32_e32 v14, v14, v29
	v_min_f32_e32 v29, v15, v28
	v_max_f32_e32 v15, v15, v28
	v_add_f32_e32 v28, v63, v2
	v_min_f32_e32 v33, v11, v32
	v_max_f32_e32 v11, v11, v32
	v_add_f32_e32 v32, v75, v4
	v_and_b32_e32 v28, 0xffffff00, v28
	v_and_b32_e32 v32, 0xffffff00, v32
	v_or_b32_e32 v28, 0x70, v28
	v_or_b32_e32 v32, 0x51, v32
	v_max_f32_e32 v13, v13, v30
	v_min_f32_e32 v30, v14, v29
	v_max_f32_e32 v12, v12, v31
	v_min_f32_e32 v31, v13, v30
	v_max_f32_e32 v14, v14, v29
	v_min_f32_e32 v29, v15, v28
	v_max3_f32 v8, v8, v95, v79
	v_min_f32_e32 v79, v10, v33
	v_max_f32_e32 v10, v10, v33
	v_min_f32_e32 v33, v11, v32
	v_max_f32_e32 v11, v11, v32
	v_min_f32_e32 v32, v12, v31
	v_add_f32_e32 v71, v71, v4
	v_max_f32_e32 v13, v13, v30
	v_min_f32_e32 v30, v14, v29
	v_min_f32_e32 v83, v9, v79
	v_max_f32_e32 v9, v9, v79
	v_min_f32_e32 v75, v10, v33
	v_max_f32_e32 v10, v10, v33
	v_min_f32_e32 v33, v11, v32
	v_and_b32_e32 v71, 0xffffff00, v71
	v_max_f32_e32 v12, v12, v31
	v_min_f32_e32 v31, v13, v30
	v_min_f32_e32 v87, v7, v83
	v_max_f32_e32 v7, v7, v83
	v_min_f32_e32 v79, v9, v75
	v_max_f32_e32 v9, v9, v75
	v_min_f32_e32 v75, v10, v33
	v_or_b32_e32 v71, 0x61, v71
	v_max_f32_e32 v11, v11, v32
	v_min_f32_e32 v32, v12, v31
	v_min_f32_e32 v83, v7, v79
	v_max_f32_e32 v7, v7, v79
	v_min_f32_e32 v79, v9, v75
	v_max_f32_e32 v9, v9, v75
	v_max_f32_e32 v10, v10, v33
	v_min_f32_e32 v33, v11, v32
	v_max3_f32 v8, v8, v87, v83
	v_min_f32_e32 v83, v7, v79
	v_max_f32_e32 v7, v7, v79
	v_min_f32_e32 v75, v9, v71
	v_max_f32_e32 v9, v9, v71
	v_min_f32_e32 v71, v10, v33
	v_add_f32_e32 v4, v63, v4
	v_min_f32_e32 v79, v7, v75
	v_max_f32_e32 v7, v7, v75
	v_min_f32_e32 v75, v9, v71
	v_and_b32_e32 v4, 0xffffff00, v4
	v_max3_f32 v8, v8, v83, v79
	v_min_f32_e32 v79, v7, v75
	v_or_b32_e32 v4, 0x71, v4
	v_max3_f32 v4, v8, v79, v4
	v_max_f32_e32 v8, v9, v71
	v_max_f32_e32 v9, v10, v33
	v_max_f32_e32 v10, v11, v32
; DEV void ce(float& a, float& b) { float hi = fmaxf(a, b), lo = fminf(a, b); a = hi; b = lo; }
; DEV void phase_peer_score(const Params& p, int layer, int M, char* smem) {
;     ...
;     for (int i = 0; i < 16; i++)
; #pragma unroll
;       for (int j = 0; j < 16; j++)
;         if ((i + 1) * (j + 1) <= 16) {
;           float v = L0[i] + L1[j];
;           v = __uint_as_float((__float_as_uint(v) & ~255u) | (unsigned)(i * 16 + j));
; #pragma unroll
;           for (int t = 0; t < 16; t++)
;             if (t >= (i + 1) * (j + 1) - 1) ce(R[t], v);
;         }
;     unsigned char* tab = (unsigned char*)smem + 73728 + (w * 16 + l15) * 32;
; #pragma unroll
;     for (int i = 0; i < 16; i++) { tab[i] = (unsigned char)(__float_as_uint(L0[i]) & 127u); tab[16 + i] = (unsigned char)(__float_as_uint(L1[i]) & 127u); }
;     float ev[16]; float sum = 0.f;
; #pragma unroll
;     for (int t = 0; t < 16; t++) { ev[t] = __expf(R[t] - R[0]); sum += ev[t]; }
;     const float inv = 1.f / sum;
;     int eid[16];
; #pragma unroll
;     for (int t = 0; t < 16; t++) {
;       unsigned code = __float_as_uint(R[t]) & 255u;
;       eid[t] = (int)tab[code >> 4] * 128 + (int)tab[16 + (code & 15u)];
	v_max_f32_e32 v11, v12, v31
	v_max_f32_e32 v12, v13, v30
	v_max_f32_e32 v13, v14, v29
	v_add_f32_e32 v14, v67, v2
	v_and_b32_e32 v14, 0xffffff00, v14
	v_or_b32_e32 v14, 0x80, v14
	v_min_f32_e32 v29, v13, v14
	v_min_f32_e32 v30, v12, v29
	v_max_f32_e32 v12, v12, v29
	v_add_f32_e32 v29, v59, v2
	v_and_b32_e32 v29, 0xffffff00, v29
	v_or_b32_e32 v29, 0x90, v29
	v_min_f32_e32 v31, v11, v30
	v_max_f32_e32 v11, v11, v30
	v_min_f32_e32 v30, v12, v29
	v_min_f32_e32 v32, v10, v31
	v_max_f32_e32 v10, v10, v31
	v_min_f32_e32 v31, v11, v30
	v_max_f32_e32 v11, v11, v30
	v_add_f32_e32 v30, v55, v2
	v_and_b32_e32 v30, 0xffffff00, v30
	v_or_b32_e32 v30, 0xa0, v30
	v_min_f32_e32 v33, v9, v32
	v_max_f32_e32 v9, v9, v32
	v_min_f32_e32 v32, v10, v31
	v_max_f32_e32 v10, v10, v31
	v_min_f32_e32 v31, v11, v30
	v_min_f32_e32 v63, v8, v33
	v_max_f32_e32 v8, v8, v33
	v_min_f32_e32 v33, v9, v32
	v_max_f32_e32 v9, v9, v32
	v_min_f32_e32 v32, v10, v31
	v_max_f32_e32 v10, v10, v31
	v_add_f32_e32 v31, v47, v2
	v_and_b32_e32 v31, 0xffffff00, v31
	v_or_b32_e32 v31, 0xb0, v31
	v_min_f32_e32 v59, v8, v33
	v_max_f32_e32 v8, v8, v33
	v_min_f32_e32 v33, v9, v32
	v_max_f32_e32 v9, v9, v32
	v_min_f32_e32 v32, v10, v31
	v_min_f32_e32 v55, v8, v33
	v_max_f32_e32 v8, v8, v33
	v_min_f32_e32 v33, v9, v32
	v_max_f32_e32 v9, v9, v32
	v_add_f32_e32 v32, v51, v2
	v_max_f32_e32 v7, v7, v75
	v_and_b32_e32 v32, 0xffffff00, v32
	v_min_f32_e32 v67, v7, v63
	v_max_f32_e32 v7, v7, v63
	v_or_b32_e32 v32, 0xc0, v32
	v_min_f32_e32 v63, v7, v59
	v_max_f32_e32 v7, v7, v59
	v_min_f32_e32 v59, v7, v55
	v_max_f32_e32 v7, v7, v55
	v_min_f32_e32 v47, v8, v33
	v_max_f32_e32 v8, v8, v33
	v_min_f32_e32 v33, v9, v32
	v_min_f32_e32 v55, v7, v47
	v_max_f32_e32 v7, v7, v47
	v_min_f32_e32 v47, v8, v33
	v_max_f32_e32 v8, v8, v33
	v_add_f32_e32 v33, v39, v2
	v_and_b32_e32 v33, 0xffffff00, v33
	v_or_b32_e32 v33, 0xd0, v33
	v_min_f32_e32 v51, v7, v47
	v_max_f32_e32 v7, v7, v47
	v_min_f32_e32 v39, v8, v33
	v_min_f32_e32 v47, v7, v39
	v_max_f32_e32 v7, v7, v39
	v_add_f32_e32 v39, v43, v2
	v_and_b32_e32 v39, 0xffffff00, v39
	v_max3_f32 v4, v4, v67, v63
	v_or_b32_e32 v39, 0xe0, v39
	v_add_f32_e32 v0, v0, v2
	v_max3_f32 v4, v4, v59, v55
	v_and_b32_e32 v0, 0xffffff00, v0
	v_max3_f32 v4, v4, v51, v47
	v_min_f32_e32 v43, v7, v39
	v_or_b32_e32 v0, 0xf0, v0
	v_max3_f32 v2, v4, v43, v0
	v_max_f32_e32 v13, v13, v14
	v_max_f32_e32 v14, v5, v6
	v_max_f32_e32 v0, 0xff61b1e6, v3
	v_sub_f32_e32 v5, v14, v0
	v_max_f32_e32 v28, v15, v28
	v_max_f32_e32 v15, v21, v23
	v_mul_f32_e32 v5, 0x3fb8aa3b, v5
	v_exp_f32_e32 v101, v5
	v_sub_f32_e32 v5, v15, v0
	v_max_f32_e32 v29, v12, v29
	v_max_f32_e32 v12, v16, v26
	v_max_f32_e32 v16, v22, v25
	v_mul_f32_e32 v5, 0x3fb8aa3b, v5
	v_exp_f32_e32 v104, v5
	v_sub_f32_e32 v5, v16, v0
	v_max_f32_e32 v4, v7, v39
	v_max_f32_e32 v7, v8, v33
	v_max_f32_e32 v8, v9, v32
	v_max_f32_e32 v9, v10, v31
	v_max_f32_e32 v10, v24, v27
	v_mul_f32_e32 v5, 0x3fb8aa3b, v5
	v_exp_f32_e32 v105, v5
	v_sub_f32_e32 v5, v10, v0
	v_max_f32_e32 v30, v11, v30
	v_max_f32_e32 v11, v17, v20
	v_mul_f32_e32 v5, 0x3fb8aa3b, v5
	v_exp_f32_e32 v102, v5
	v_sub_f32_e32 v5, v11, v0
	v_mul_f32_e32 v5, 0x3fb8aa3b, v5
	v_exp_f32_e32 v103, v5
	v_sub_f32_e32 v5, v12, v0
	v_mul_f32_e32 v5, 0x3fb8aa3b, v5
	v_exp_f32_e32 v110, v5
	v_sub_f32_e32 v5, v28, v0
	v_sub_f32_e32 v3, v0, v0
	v_mul_f32_e32 v5, 0x3fb8aa3b, v5
	v_mul_f32_e32 v3, 0x3fb8aa3b, v3
	v_exp_f32_e32 v111, v5
	v_sub_f32_e32 v5, v13, v0
	v_exp_f32_e32 v100, v3
	v_mul_f32_e32 v5, 0x3fb8aa3b, v5
	v_exp_f32_e32 v112, v5
	v_sub_f32_e32 v5, v29, v0
	v_mul_f32_e32 v5, 0x3fb8aa3b, v5
	v_exp_f32_e32 v113, v5
	v_sub_f32_e32 v5, v30, v0
	v_add_f32_e32 v3, 0, v100
	v_mul_f32_e32 v5, 0x3fb8aa3b, v5
	v_add_f32_e32 v3, v3, v101
	v_exp_f32_e32 v114, v5
	v_sub_f32_e32 v5, v9, v0
	v_add_f32_e32 v3, v3, v104
	v_mul_f32_e32 v5, 0x3fb8aa3b, v5
	v_add_f32_e32 v3, v3, v105
	v_exp_f32_e32 v115, v5
	v_sub_f32_e32 v5, v8, v0
	v_add_f32_e32 v3, v3, v102
	v_mul_f32_e32 v5, 0x3fb8aa3b, v5
	v_add_f32_e32 v3, v3, v103
	v_exp_f32_e32 v106, v5
	v_sub_f32_e32 v5, v7, v0
	v_add_f32_e32 v3, v3, v110
	v_mul_f32_e32 v5, 0x3fb8aa3b, v5
	v_add_f32_e32 v3, v3, v111
	v_exp_f32_e32 v107, v5
	v_sub_f32_e32 v5, v4, v0
	v_add_f32_e32 v3, v3, v112
	v_mul_f32_e32 v5, 0x3fb8aa3b, v5
	v_add_f32_e32 v3, v3, v113
	v_exp_f32_e32 v108, v5
	v_sub_f32_e32 v5, v2, v0
	v_add_f32_e32 v3, v3, v114
	v_mul_f32_e32 v5, 0x3fb8aa3b, v5
	v_add_f32_e32 v3, v3, v115
	v_exp_f32_e32 v109, v5
	v_add_f32_e32 v3, v3, v106
	v_add_f32_e32 v3, v3, v107
	v_add_f32_e32 v3, v3, v108
	v_add_f32_e32 v3, v3, v109
	v_div_scale_f32 v5, s[0:1], v3, v3, 1.0
	v_rcp_f32_e32 v6, v5
	v_ashrrev_i32_e32 v19, 31, v18
	s_mov_b32 s0, 0x10000
	v_lshlrev_b64 v[120:121], 9, v[18:19]
	v_fma_f32 v17, -v5, v6, 1.0
	v_fmac_f32_e32 v6, v17, v6
	v_div_scale_f32 v17, vcc, 1.0, v3, 1.0
	v_mul_f32_e32 v20, v17, v6
	v_fma_f32 v21, -v5, v20, v17
	v_fmac_f32_e32 v20, v21, v6
	v_fma_f32 v5, -v5, v20, v17
	v_div_fmas_f32 v5, v5, v6, v20
	v_div_fixup_f32 v116, v5, v3, 1.0
	v_bfe_u32 v3, v2, 4, 4
	v_and_b32_e32 v2, 15, v2
	v_and_b32_e32 v17, 15, v28
	v_add_u32_e32 v3, v138, v3
	v_add_u32_e32 v2, v138, v2
	v_add_u32_e32 v17, v138, v17
	ds_read_u8 v3, v3
	ds_read_u8 v17, v17 offset:16
	ds_read_u8 v2, v2 offset:16
	v_and_b32_e32 v6, 15, v8
	v_add_u32_e32 v6, v138, v6
	ds_read_u8 v6, v6 offset:16
	v_lshl_add_u64 v[18:19], s[8:9], 0, v[120:121]
	s_waitcnt lgkmcnt(1)
	v_lshl_add_u32 v5, v3, 7, v2
	v_bfe_u32 v2, v4, 4, 4
	v_and_b32_e32 v3, 15, v4
	v_add_u32_e32 v2, v138, v2
	v_add_u32_e32 v3, v138, v3
	ds_read_u8 v2, v2
	ds_read_u8 v3, v3 offset:16
	s_lshl_b32 s52, s19, 6
	v_lshl_add_u64 v[118:119], v[18:19], 0, s[52:53]
	v_lshl_add_u64 v[120:121], s[6:7], 0, v[120:121]
	v_lshl_add_u64 v[120:121], v[120:121], 0, s[52:53]
	s_waitcnt lgkmcnt(0)
; DEV void phase_peer_score(const Params& p, int layer, int M, char* smem) {
;     ...
;     int eid[16];
; #pragma unroll
;     for (int t = 0; t < 16; t++) {
;       unsigned code = __float_as_uint(R[t]) & 255u;
;       eid[t] = (int)tab[code >> 4] * 128 + (int)tab[16 + (code & 15u)];
;     }
	v_lshl_add_u32 v4, v2, 7, v3
	v_bfe_u32 v2, v7, 4, 4
	v_and_b32_e32 v3, 15, v7
	v_add_u32_e32 v2, v138, v2
	v_add_u32_e32 v3, v138, v3
	ds_read_u8 v2, v2
	ds_read_u8 v3, v3 offset:16
	v_and_b32_e32 v7, 15, v9
	v_add_u32_e32 v7, v138, v7
	ds_read_u8 v7, v7 offset:16
	s_waitcnt lgkmcnt(1)
	v_lshl_add_u32 v3, v2, 7, v3
	v_bfe_u32 v2, v8, 4, 4
	v_add_u32_e32 v2, v138, v2
	ds_read_u8 v2, v2
	s_waitcnt lgkmcnt(0)
	v_lshl_add_u32 v2, v2, 7, v6
	v_bfe_u32 v6, v9, 4, 4
	v_add_u32_e32 v6, v138, v6
	ds_read_u8 v6, v6
	s_waitcnt lgkmcnt(0)
	v_lshl_add_u32 v9, v6, 7, v7
	v_bfe_u32 v6, v30, 4, 4
	v_and_b32_e32 v7, 15, v30
	v_add_u32_e32 v6, v138, v6
	v_add_u32_e32 v7, v138, v7
	ds_read_u8 v6, v6
	ds_read_u8 v7, v7 offset:16
	s_waitcnt lgkmcnt(0)
	v_lshl_add_u32 v8, v6, 7, v7
	v_bfe_u32 v6, v29, 4, 4
	v_and_b32_e32 v7, 15, v29
	v_add_u32_e32 v6, v138, v6
	v_add_u32_e32 v7, v138, v7
	ds_read_u8 v6, v6
	ds_read_u8 v7, v7 offset:16
	s_waitcnt lgkmcnt(0)
	v_lshl_add_u32 v7, v6, 7, v7
	v_bfe_u32 v6, v13, 4, 4
	v_and_b32_e32 v13, 15, v13
	v_add_u32_e32 v6, v138, v6
	v_add_u32_e32 v13, v138, v13
	ds_read_u8 v6, v6
	ds_read_u8 v13, v13 offset:16
	s_waitcnt lgkmcnt(0)
	v_lshl_add_u32 v6, v6, 7, v13
	v_bfe_u32 v13, v28, 4, 4
	v_add_u32_e32 v13, v138, v13
	ds_read_u8 v13, v13
	s_waitcnt lgkmcnt(0)
	v_lshl_add_u32 v13, v13, 7, v17
	v_bfe_u32 v17, v12, 4, 4
	v_and_b32_e32 v12, 15, v12
	v_add_u32_e32 v17, v138, v17
	v_add_u32_e32 v12, v138, v12
	ds_read_u8 v17, v17
	ds_read_u8 v12, v12 offset:16
	s_waitcnt lgkmcnt(0)
	v_lshl_add_u32 v12, v17, 7, v12
	v_bfe_u32 v17, v11, 4, 4
	v_and_b32_e32 v11, 15, v11
	v_add_u32_e32 v17, v138, v17
	v_add_u32_e32 v11, v138, v11
	ds_read_u8 v17, v17
	ds_read_u8 v11, v11 offset:16
	s_waitcnt lgkmcnt(0)
	v_lshl_add_u32 v11, v17, 7, v11
	v_bfe_u32 v17, v10, 4, 4
	v_and_b32_e32 v10, 15, v10
	v_add_u32_e32 v17, v138, v17
	v_add_u32_e32 v10, v138, v10
	ds_read_u8 v17, v17
	ds_read_u8 v10, v10 offset:16
	s_waitcnt lgkmcnt(0)
	v_lshl_add_u32 v10, v17, 7, v10
	v_bfe_u32 v17, v16, 4, 4
	v_and_b32_e32 v16, 15, v16
	v_add_u32_e32 v17, v138, v17
	v_add_u32_e32 v16, v138, v16
	ds_read_u8 v17, v17
	ds_read_u8 v16, v16 offset:16
	s_waitcnt lgkmcnt(0)
	v_lshl_add_u32 v17, v17, 7, v16
	v_bfe_u32 v16, v15, 4, 4
	v_and_b32_e32 v15, 15, v15
	v_add_u32_e32 v16, v138, v16
	v_add_u32_e32 v15, v138, v15
	ds_read_u8 v16, v16
	ds_read_u8 v15, v15 offset:16
	s_waitcnt lgkmcnt(0)
	v_lshl_add_u32 v16, v16, 7, v15
	v_bfe_u32 v15, v14, 4, 4
	v_and_b32_e32 v14, 15, v14
	v_add_u32_e32 v15, v138, v15
	v_add_u32_e32 v14, v138, v14
	ds_read_u8 v15, v15
	ds_read_u8 v14, v14 offset:16
	s_waitcnt lgkmcnt(0)
	v_lshl_add_u32 v15, v15, 7, v14
	v_bfe_u32 v14, v0, 4, 4
	v_and_b32_e32 v0, 15, v0
	v_add_u32_e32 v14, v138, v14
	v_add_u32_e32 v0, v138, v0
	ds_read_u8 v14, v14
	ds_read_u8 v0, v0 offset:16
	s_waitcnt lgkmcnt(0)
; DEV void phase_peer_score(const Params& p, int layer, int M, char* smem) {
;     ...
;     if (quad == 0) {
;       int* eo = EIDX + (size_t)m * 128 + h * 16;
;       float* go = GATE + (size_t)m * 128 + h * 16;
;       float* uo = go + (size_t)MT * 128;
;       float us[16], vs[16];
; #pragma unroll
;       for (int t = 0; t < 16; t++) { us[t] = USC[eid[t]]; vs[t] = USC[16384 + eid[t]]; }
; #pragma unroll
;       for (int t = 0; t < 16; t += 4) {
;         *(int4*)(eo + t) = make_int4(eid[t], eid[t + 1], eid[t + 2], eid[t + 3]);
;         *(float4*)(go + t) = make_float4(ev[t] * inv * vs[t], ev[t + 1] * inv * vs[t + 1], ev[t + 2] * inv * vs[t + 2], ev[t + 3] * inv * vs[t + 3]);
;         *(float4*)(uo + t) = make_float4(us[t], us[t + 1], us[t + 2], us[t + 3]);
;       }
;     }
	v_lshl_add_u32 v14, v14, 7, v0
	v_lshlrev_b32_e32 v0, 2, v14
	v_lshl_add_u64 v[20:21], s[10:11], 0, v[0:1]
	v_add_co_u32_e32 v20, vcc, s0, v20
	global_load_dword v18, v0, s[10:11]
	s_nop 0
	v_addc_co_u32_e32 v21, vcc, 0, v21, vcc
	global_load_dword v122, v[20:21], off
	v_lshlrev_b32_e32 v0, 2, v15
	v_lshl_add_u64 v[20:21], s[10:11], 0, v[0:1]
	v_add_co_u32_e32 v20, vcc, s0, v20
	global_load_dword v19, v0, s[10:11]
	s_nop 0
	v_addc_co_u32_e32 v21, vcc, 0, v21, vcc
	global_load_dword v123, v[20:21], off
	v_lshlrev_b32_e32 v0, 2, v16
	v_lshl_add_u64 v[22:23], s[10:11], 0, v[0:1]
	v_add_co_u32_e32 v22, vcc, s0, v22
	global_load_dword v20, v0, s[10:11]
	s_nop 0
	v_addc_co_u32_e32 v23, vcc, 0, v23, vcc
	global_load_dword v126, v[22:23], off
	v_lshlrev_b32_e32 v0, 2, v17
	v_lshl_add_u64 v[22:23], s[10:11], 0, v[0:1]
	v_add_co_u32_e32 v22, vcc, s0, v22
	global_load_dword v21, v0, s[10:11]
	s_nop 0
	v_addc_co_u32_e32 v23, vcc, 0, v23, vcc
	global_load_dword v127, v[22:23], off
	v_lshlrev_b32_e32 v0, 2, v10
	v_lshl_add_u64 v[24:25], s[10:11], 0, v[0:1]
	v_add_co_u32_e32 v24, vcc, s0, v24
	global_load_dword v22, v0, s[10:11]
	s_nop 0
	v_addc_co_u32_e32 v25, vcc, 0, v25, vcc
	global_load_dword v124, v[24:25], off
	v_lshlrev_b32_e32 v0, 2, v11
	v_lshl_add_u64 v[24:25], s[10:11], 0, v[0:1]
	v_add_co_u32_e32 v24, vcc, s0, v24
	global_load_dword v23, v0, s[10:11]
	s_nop 0
	v_addc_co_u32_e32 v25, vcc, 0, v25, vcc
	global_load_dword v125, v[24:25], off
	v_lshlrev_b32_e32 v0, 2, v12
	v_lshl_add_u64 v[26:27], s[10:11], 0, v[0:1]
	v_add_co_u32_e32 v26, vcc, s0, v26
	global_load_dword v24, v0, s[10:11]
	s_nop 0
	v_addc_co_u32_e32 v27, vcc, 0, v27, vcc
	global_load_dword v128, v[26:27], off
	v_lshlrev_b32_e32 v0, 2, v13
	v_lshl_add_u64 v[26:27], s[10:11], 0, v[0:1]
	v_add_co_u32_e32 v26, vcc, s0, v26
	global_load_dword v25, v0, s[10:11]
	s_nop 0
	v_addc_co_u32_e32 v27, vcc, 0, v27, vcc
	global_load_dword v129, v[26:27], off
	v_lshlrev_b32_e32 v0, 2, v6
	v_lshl_add_u64 v[28:29], s[10:11], 0, v[0:1]
	v_add_co_u32_e32 v28, vcc, s0, v28
	global_load_dword v26, v0, s[10:11]
	s_nop 0
	v_addc_co_u32_e32 v29, vcc, 0, v29, vcc
	global_load_dword v130, v[28:29], off
	v_lshlrev_b32_e32 v0, 2, v7
	v_lshl_add_u64 v[28:29], s[10:11], 0, v[0:1]
	v_add_co_u32_e32 v28, vcc, s0, v28
	global_load_dword v27, v0, s[10:11]
	s_nop 0
	v_addc_co_u32_e32 v29, vcc, 0, v29, vcc
	global_load_dword v131, v[28:29], off
	v_lshlrev_b32_e32 v0, 2, v8
	v_lshl_add_u64 v[30:31], s[10:11], 0, v[0:1]
	v_add_co_u32_e32 v30, vcc, s0, v30
	global_load_dword v28, v0, s[10:11]
	s_nop 0
	v_addc_co_u32_e32 v31, vcc, 0, v31, vcc
	global_load_dword v132, v[30:31], off
	v_lshlrev_b32_e32 v0, 2, v9
	v_lshl_add_u64 v[30:31], s[10:11], 0, v[0:1]
	v_add_co_u32_e32 v30, vcc, s0, v30
	global_load_dword v29, v0, s[10:11]
	s_nop 0
	v_addc_co_u32_e32 v31, vcc, 0, v31, vcc
	global_load_dword v133, v[30:31], off
	v_lshlrev_b32_e32 v0, 2, v2
	v_lshl_add_u64 v[32:33], s[10:11], 0, v[0:1]
	v_add_co_u32_e32 v32, vcc, s0, v32
	global_load_dword v30, v0, s[10:11]
	s_nop 0
	v_addc_co_u32_e32 v33, vcc, 0, v33, vcc
	global_load_dword v134, v[32:33], off
	v_lshlrev_b32_e32 v0, 2, v3
	v_lshl_add_u64 v[32:33], s[10:11], 0, v[0:1]
	v_add_co_u32_e32 v32, vcc, s0, v32
	global_load_dword v31, v0, s[10:11]
	s_nop 0
	v_addc_co_u32_e32 v33, vcc, 0, v33, vcc
	global_load_dword v135, v[32:33], off
	v_lshlrev_b32_e32 v0, 2, v4
	v_lshl_add_u64 v[136:137], s[10:11], 0, v[0:1]
	v_add_co_u32_e32 v136, vcc, s0, v136
	global_load_dword v32, v0, s[10:11]
	s_nop 0
	v_addc_co_u32_e32 v137, vcc, 0, v137, vcc
	global_load_dword v136, v[136:137], off
	v_lshlrev_b32_e32 v0, 2, v5
	v_lshl_add_u64 v[140:141], s[10:11], 0, v[0:1]
	v_add_co_u32_e32 v140, vcc, s0, v140
	global_load_dword v33, v0, s[10:11]
	s_nop 0
	v_addc_co_u32_e32 v141, vcc, 0, v141, vcc
	global_load_dword v137, v[140:141], off
	s_mov_b32 s0, 0x840000
	global_store_dwordx4 v[120:121], v[14:17], off
	s_nop 1
	v_pk_mul_f32 v[14:15], v[100:101], v[116:117] op_sel_hi:[1,0]
	v_pk_mul_f32 v[16:17], v[104:105], v[116:117] op_sel_hi:[1,0]
	s_waitcnt vmcnt(29)
	v_pk_mul_f32 v[14:15], v[14:15], v[122:123]
	s_waitcnt vmcnt(25)
	v_pk_mul_f32 v[16:17], v[16:17], v[126:127]
	global_store_dwordx4 v[118:119], v[14:17], off
	s_nop 1
	v_add_co_u32_e32 v14, vcc, s0, v118
	s_nop 1
	v_addc_co_u32_e32 v15, vcc, 0, v119, vcc
	global_store_dwordx4 v[14:15], v[18:21], off
	global_store_dwordx4 v[120:121], v[10:13], off offset:16
	s_nop 1
	v_pk_mul_f32 v[10:11], v[102:103], v[116:117] op_sel_hi:[1,0]
	v_pk_mul_f32 v[12:13], v[110:111], v[116:117] op_sel_hi:[1,0]
	s_waitcnt vmcnt(24)
	v_pk_mul_f32 v[10:11], v[10:11], v[124:125]
	s_waitcnt vmcnt(20)
	v_pk_mul_f32 v[12:13], v[12:13], v[128:129]
	global_store_dwordx4 v[118:119], v[10:13], off offset:16
	global_store_dwordx4 v[14:15], v[22:25], off offset:16
	global_store_dwordx4 v[120:121], v[6:9], off offset:32
	s_nop 1
	v_pk_mul_f32 v[6:7], v[112:113], v[116:117] op_sel_hi:[1,0]
	v_pk_mul_f32 v[8:9], v[114:115], v[116:117] op_sel_hi:[1,0]
	s_waitcnt vmcnt(19)
	v_pk_mul_f32 v[6:7], v[6:7], v[130:131]
	s_waitcnt vmcnt(15)
	v_pk_mul_f32 v[8:9], v[8:9], v[132:133]
	global_store_dwordx4 v[118:119], v[6:9], off offset:32
	global_store_dwordx4 v[14:15], v[26:29], off offset:32
	global_store_dwordx4 v[120:121], v[2:5], off offset:48
	s_nop 1
	v_pk_mul_f32 v[2:3], v[106:107], v[116:117] op_sel_hi:[1,0]
	v_pk_mul_f32 v[4:5], v[108:109], v[116:117] op_sel_hi:[1,0]
	s_waitcnt vmcnt(14)
	v_pk_mul_f32 v[2:3], v[2:3], v[134:135]
	s_waitcnt vmcnt(10)
	v_pk_mul_f32 v[4:5], v[4:5], v[136:137]
	global_store_dwordx4 v[118:119], v[2:5], off offset:48
	global_store_dwordx4 v[14:15], v[30:33], off offset:48
	s_branch .LBB0_162

; DEV f32x4 mfma16(bf16x8 a, bf16x8 b, f32x4 c) { return __builtin_amdgcn_mfma_f32_16x16x32_bf16(a, b, c, 0, 0, 0); }
; DEV void peer_top16(const bf16_t* __restrict__ pq, const bf16_t* sk  , float (&l)[16]) {
;     ...
;   f32x4 acc[8];
; #pragma unroll
;   for (int nt = 0; nt < 8; nt++) acc[nt] = (f32x4){0.f, 0.f, 0.f, 0.f};
; #pragma unroll 1
;   for (int ks = 0; ks < 4; ks++) {
;     const bf16x8 bqk = *(const bf16x8*)(pq + ks * 32 + quad * 8);
; #pragma unroll
;     for (int nt = 0; nt < 8; nt++) {
;       bf16x8 ak = *(const bf16x8*)(sk + (nt * 16 + l15) * 144 + ks * 32 + quad * 8);
;       acc[nt] = mfma16(ak, bqk, acc[nt]);
;     }
;   }
;   float hi[16];
; #pragma unroll
;   for (int nt = 0; nt < 4; nt++)
; #pragma unroll
;     for (int r = 0; r < 4; r++) {
;       l[nt * 4 + r] = __uint_as_float((__float_as_uint(acc[nt][r]) & ~127u) | (unsigned)(nt * 16 + quad * 4 + r));
;       hi[nt * 4 + r] = __uint_as_float((__float_as_uint(acc[nt + 4][r]) & ~127u) | (unsigned)((nt + 4) * 16 + quad * 4 + r));
;     }
;   sort16_desc(l);
;   sort16_desc(hi);
.LBB0_633:
	global_load_dwordx4 v[104:107], v[102:103], off
	v_add_u32_e32 v43, s18, v39
	ds_read_b128 v[108:111], v43
	s_add_i32 s18, s18, 64
	v_lshl_add_u64 v[102:103], v[102:103], 0, 64
	s_cmpk_lg_i32 s18, 0x100
	s_waitcnt vmcnt(0) lgkmcnt(0)
	v_mfma_f32_16x16x32_bf16 v[30:33], v[108:111], v[104:107], v[30:33]
	ds_read_b128 v[108:111], v43 offset:4608
	s_waitcnt lgkmcnt(0)
	v_mfma_f32_16x16x32_bf16 v[22:25], v[108:111], v[104:107], v[22:25]
	ds_read_b128 v[108:111], v43 offset:9216
	s_waitcnt lgkmcnt(0)
	v_mfma_f32_16x16x32_bf16 v[14:17], v[108:111], v[104:107], v[14:17]
	ds_read_b128 v[108:111], v43 offset:13824
	s_waitcnt lgkmcnt(0)
	v_mfma_f32_16x16x32_bf16 v[6:9], v[108:111], v[104:107], v[6:9]
	ds_read_b128 v[108:111], v43 offset:18432
	s_waitcnt lgkmcnt(0)
	v_mfma_f32_16x16x32_bf16 v[26:29], v[108:111], v[104:107], v[26:29]
	ds_read_b128 v[108:111], v43 offset:23040
	s_waitcnt lgkmcnt(0)
	v_mfma_f32_16x16x32_bf16 v[18:21], v[108:111], v[104:107], v[18:21]
	ds_read_b128 v[108:111], v43 offset:27648
	s_waitcnt lgkmcnt(0)
	v_mfma_f32_16x16x32_bf16 v[10:13], v[108:111], v[104:107], v[10:13]
	ds_read_b128 v[108:111], v43 offset:32256
	s_waitcnt lgkmcnt(0)
	v_mfma_f32_16x16x32_bf16 v[2:5], v[108:111], v[104:107], v[2:5]
	s_cbranch_scc1 .LBB0_633
	v_lshlrev_b32_e32 v0, 2, v0
	s_movk_i32 s18, 0xff80
	v_and_or_b32 v30, v30, s18, v0
	v_and_b32_e32 v27, 0xffffff80, v27
	s_movk_i32 s18, 0x41
	v_or3_b32 v27, v0, v27, s18
	v_and_b32_e32 v28, 0xffffff80, v28
	s_movk_i32 s18, 0x42
	v_or3_b32 v28, v0, v28, s18
	v_and_b32_e32 v29, 0xffffff80, v29
	s_movk_i32 s18, 0x43
	v_or3_b32 v29, v0, v29, s18
	v_and_b32_e32 v18, 0xffffff80, v18
	s_movk_i32 s18, 0x50
	v_or3_b32 v18, v0, v18, s18
	v_and_b32_e32 v19, 0xffffff80, v19
	s_movk_i32 s18, 0x51
	v_or3_b32 v19, v0, v19, s18
	v_and_b32_e32 v20, 0xffffff80, v20
	s_movk_i32 s18, 0x52
	v_or3_b32 v20, v0, v20, s18
	v_and_b32_e32 v21, 0xffffff80, v21
	s_movk_i32 s18, 0x53
	v_or3_b32 v21, v0, v21, s18
	v_and_b32_e32 v10, 0xffffff80, v10
	s_movk_i32 s18, 0x60
	v_or3_b32 v10, v0, v10, s18
	v_and_b32_e32 v11, 0xffffff80, v11
	s_movk_i32 s18, 0x61
	v_or3_b32 v11, v0, v11, s18
	v_and_b32_e32 v12, 0xffffff80, v12
	s_movk_i32 s18, 0x62
	v_or3_b32 v12, v0, v12, s18
	v_and_b32_e32 v13, 0xffffff80, v13
	s_movk_i32 s18, 0x63
	v_or3_b32 v13, v0, v13, s18
	v_and_b32_e32 v2, 0xffffff80, v2
	s_movk_i32 s18, 0x70
	v_or3_b32 v2, v0, v2, s18
	v_and_b32_e32 v3, 0xffffff80, v3
	s_movk_i32 s18, 0x71
	v_and_b32_e32 v26, 0xffffff80, v26
	v_and_b32_e32 v31, 0xffffff80, v31
	v_or3_b32 v3, v0, v3, s18
	v_and_b32_e32 v4, 0xffffff80, v4
	s_movk_i32 s18, 0x72
	v_or3_b32 v26, v0, v26, 64
	v_or3_b32 v31, v0, v31, 1
	v_and_b32_e32 v32, 0xffffff80, v32
	v_and_b32_e32 v33, 0xffffff80, v33
	v_and_b32_e32 v22, 0xffffff80, v22
	v_and_b32_e32 v23, 0xffffff80, v23
	v_and_b32_e32 v24, 0xffffff80, v24
	v_and_b32_e32 v25, 0xffffff80, v25
	v_and_b32_e32 v14, 0xffffff80, v14
	v_and_b32_e32 v15, 0xffffff80, v15
	v_and_b32_e32 v16, 0xffffff80, v16
	v_and_b32_e32 v17, 0xffffff80, v17
	v_and_b32_e32 v6, 0xffffff80, v6
	v_and_b32_e32 v7, 0xffffff80, v7
	v_and_b32_e32 v8, 0xffffff80, v8
	v_or3_b32 v4, v0, v4, s18
	v_and_b32_e32 v9, 0xffffff80, v9
	v_and_b32_e32 v5, 0xffffff80, v5
	s_movk_i32 s18, 0x73
	v_or3_b32 v32, v0, v32, 2
	v_or3_b32 v33, v0, v33, 3
	v_or3_b32 v22, v0, v22, 16
	v_or3_b32 v23, v0, v23, 17
	v_or3_b32 v24, v0, v24, 18
	v_or3_b32 v25, v0, v25, 19
	v_or3_b32 v14, v0, v14, 32
	v_or3_b32 v15, v0, v15, 33
	v_or3_b32 v16, v0, v16, 34
	v_or3_b32 v17, v0, v17, 35
	v_or3_b32 v6, v0, v6, 48
	v_or3_b32 v7, v0, v7, 49
	v_or3_b32 v8, v0, v8, 50
	v_or3_b32 v9, v0, v9, 51
	v_or3_b32 v0, v0, v5, s18
	v_max_f32_e32 v5, v31, v31
	v_max_f32_e32 v31, v30, v5
	v_min_f32_e32 v5, v30, v5
	v_max_f32_e32 v30, v32, v32
	v_max_f32_e32 v32, v33, v33
	v_max_f32_e32 v67, v26, v27
	v_min_f32_e32 v26, v26, v27
	v_max_f32_e32 v27, v28, v28
	v_max_f32_e32 v28, v29, v29
	v_max_f32_e32 v33, v32, v30
	v_min_f32_e32 v30, v32, v30
	v_max_f32_e32 v32, v22, v23
	v_min_f32_e32 v22, v22, v23
	v_max_f32_e32 v23, v24, v24
	v_max_f32_e32 v24, v25, v25
	v_max_f32_e32 v29, v28, v27
	v_min_f32_e32 v27, v28, v27
	v_max_f32_e32 v28, v18, v19
	v_min_f32_e32 v18, v18, v19
	v_max_f32_e32 v19, v20, v20
	v_max_f32_e32 v20, v21, v21
	v_max_f32_e32 v25, v24, v23
	v_min_f32_e32 v23, v24, v23
	v_max_f32_e32 v24, v14, v15
	v_min_f32_e32 v14, v14, v15
	v_max_f32_e32 v15, v16, v16
	v_max_f32_e32 v16, v17, v17
	v_max_f32_e32 v21, v20, v19
	v_min_f32_e32 v19, v20, v19
	v_max_f32_e32 v20, v10, v11
	v_min_f32_e32 v10, v10, v11
	v_max_f32_e32 v11, v12, v12
	v_max_f32_e32 v12, v13, v13
	v_max_f32_e32 v17, v16, v15
	v_min_f32_e32 v15, v16, v15
	v_max_f32_e32 v16, v6, v7
	v_min_f32_e32 v6, v6, v7
	v_max_f32_e32 v7, v8, v8
	v_max_f32_e32 v8, v9, v9
	v_max_f32_e32 v13, v12, v11
	v_min_f32_e32 v11, v12, v11
	v_max_f32_e32 v12, v2, v3
	v_min_f32_e32 v2, v2, v3
	v_max_f32_e32 v3, v4, v4
	v_max_f32_e32 v9, v8, v7
	v_min_f32_e32 v7, v8, v7
	v_max_f32_e32 v4, v0, v3
	v_min_f32_e32 v0, v0, v3
	v_max_f32_e32 v8, v31, v30
	v_min_f32_e32 v30, v31, v30
	v_max_f32_e32 v31, v5, v33
	v_min_f32_e32 v5, v5, v33
	v_max_f32_e32 v33, v23, v32
	v_min_f32_e32 v23, v23, v32
	v_max_f32_e32 v32, v25, v22
	v_min_f32_e32 v22, v25, v22
	v_max_f32_e32 v25, v24, v15
	v_min_f32_e32 v15, v24, v15
	v_max_f32_e32 v24, v14, v17
	v_min_f32_e32 v14, v14, v17
	v_max_f32_e32 v17, v7, v16
	v_min_f32_e32 v7, v7, v16
	v_max_f32_e32 v16, v9, v6
	v_min_f32_e32 v6, v9, v6
	v_max_f32_e32 v3, v67, v27
	v_min_f32_e32 v27, v67, v27
	v_max_f32_e32 v67, v26, v29
	v_min_f32_e32 v26, v26, v29
	v_max_f32_e32 v29, v19, v28
	v_min_f32_e32 v19, v19, v28
; DEV void ce(float& a, float& b) { float hi = fmaxf(a, b), lo = fminf(a, b); a = hi; b = lo; }
; DEV void sort16_desc(float (&a)[16]) {
; #pragma unroll
;   for (int k = 2; k <= 16; k <<= 1)
; #pragma unroll
;     for (int j = k >> 1; j > 0; j >>= 1)
; #pragma unroll
;       for (int i = 0; i < 16; i++) {
;         const int p = i ^ j;
;         if (p > i) { if ((i & k) == 0) ce(a[i], a[p]); else ce(a[p], a[i]); }
;       }
; }
	v_max_f32_e32 v28, v21, v18
	v_min_f32_e32 v18, v21, v18
	v_max_f32_e32 v21, v20, v11
	v_min_f32_e32 v11, v20, v11
	v_max_f32_e32 v20, v10, v13
	v_min_f32_e32 v10, v10, v13
	v_max_f32_e32 v13, v0, v12
	v_min_f32_e32 v0, v0, v12
	v_max_f32_e32 v12, v4, v2
	v_min_f32_e32 v2, v4, v2
	v_max_f32_e32 v9, v8, v31
	v_min_f32_e32 v8, v8, v31
	v_max_f32_e32 v31, v30, v5
	v_min_f32_e32 v5, v30, v5
	v_max_f32_e32 v30, v22, v23
	v_min_f32_e32 v22, v22, v23
	v_max_f32_e32 v23, v32, v33
	v_min_f32_e32 v32, v32, v33
	v_max_f32_e32 v33, v25, v24
	v_min_f32_e32 v24, v25, v24
	v_max_f32_e32 v25, v15, v14
	v_min_f32_e32 v14, v15, v14
	v_max_f32_e32 v15, v6, v7
	v_min_f32_e32 v6, v6, v7
	v_max_f32_e32 v7, v16, v17
	v_min_f32_e32 v16, v16, v17
	v_max_f32_e32 v4, v3, v67
	v_min_f32_e32 v3, v3, v67
	v_max_f32_e32 v67, v27, v26
	v_min_f32_e32 v26, v27, v26
	v_max_f32_e32 v27, v18, v19
	v_min_f32_e32 v18, v18, v19
	v_max_f32_e32 v19, v28, v29
	v_min_f32_e32 v28, v28, v29
	v_max_f32_e32 v29, v21, v20
	v_min_f32_e32 v20, v21, v20
	v_max_f32_e32 v21, v11, v10
	v_min_f32_e32 v10, v11, v10
	v_max_f32_e32 v11, v2, v0
	v_min_f32_e32 v0, v2, v0
	v_max_f32_e32 v2, v12, v13
	v_min_f32_e32 v12, v12, v13
	v_max_f32_e32 v17, v9, v22
	v_min_f32_e32 v9, v9, v22
	v_max_f32_e32 v22, v8, v30
	v_min_f32_e32 v8, v8, v30
	v_max_f32_e32 v30, v31, v32
	v_min_f32_e32 v31, v31, v32
	v_max_f32_e32 v32, v5, v23
	v_min_f32_e32 v5, v5, v23
	v_max_f32_e32 v23, v6, v33
	v_min_f32_e32 v6, v6, v33
	v_max_f32_e32 v33, v15, v24
	v_min_f32_e32 v15, v15, v24
	v_max_f32_e32 v24, v16, v25
	v_min_f32_e32 v16, v16, v25
	v_max_f32_e32 v25, v7, v14
	v_min_f32_e32 v7, v7, v14
	v_max_f32_e32 v13, v4, v18
	v_min_f32_e32 v4, v4, v18
	v_max_f32_e32 v18, v3, v27
	v_min_f32_e32 v3, v3, v27
	v_max_f32_e32 v27, v67, v28
	v_min_f32_e32 v28, v67, v28
	v_max_f32_e32 v67, v26, v19
	v_min_f32_e32 v19, v26, v19
	v_max_f32_e32 v26, v0, v29
	v_min_f32_e32 v0, v0, v29
	v_max_f32_e32 v29, v11, v20
	v_min_f32_e32 v11, v11, v20
	v_max_f32_e32 v20, v12, v21
	v_min_f32_e32 v12, v12, v21
	v_max_f32_e32 v21, v2, v10
	v_min_f32_e32 v2, v2, v10
	v_max_f32_e32 v14, v17, v30
	v_min_f32_e32 v17, v17, v30
	v_max_f32_e32 v30, v22, v32
	v_min_f32_e32 v22, v22, v32
	v_max_f32_e32 v32, v9, v31
	v_min_f32_e32 v9, v9, v31
	v_max_f32_e32 v31, v8, v5
	v_min_f32_e32 v5, v8, v5
	v_max_f32_e32 v8, v16, v6
	v_min_f32_e32 v6, v16, v6
	v_max_f32_e32 v16, v7, v15
	v_min_f32_e32 v7, v7, v15
	v_max_f32_e32 v15, v24, v23
	v_min_f32_e32 v23, v24, v23
	v_max_f32_e32 v24, v25, v33
	v_min_f32_e32 v25, v25, v33
	v_max_f32_e32 v10, v13, v27
	v_min_f32_e32 v13, v13, v27
	v_max_f32_e32 v27, v18, v67
	v_min_f32_e32 v18, v18, v67
	v_max_f32_e32 v67, v4, v28
	v_min_f32_e32 v4, v4, v28
	v_max_f32_e32 v28, v3, v19
	v_min_f32_e32 v3, v3, v19
	v_max_f32_e32 v19, v12, v0
	v_min_f32_e32 v0, v12, v0
	v_max_f32_e32 v12, v2, v11
	v_min_f32_e32 v2, v2, v11
	v_max_f32_e32 v11, v20, v26
	v_min_f32_e32 v20, v20, v26
	v_max_f32_e32 v26, v21, v29
	v_min_f32_e32 v21, v21, v29
	v_max_f32_e32 v33, v14, v30
	v_min_f32_e32 v14, v14, v30
	v_max_f32_e32 v30, v17, v22
	v_min_f32_e32 v17, v17, v22
	v_max_f32_e32 v22, v32, v31
	v_min_f32_e32 v31, v32, v31
	v_max_f32_e32 v32, v9, v5
	v_min_f32_e32 v5, v9, v5
	v_max_f32_e32 v9, v7, v6
	v_min_f32_e32 v6, v7, v6
	v_max_f32_e32 v7, v16, v8
	v_min_f32_e32 v8, v16, v8
	v_max_f32_e32 v16, v25, v23
	v_min_f32_e32 v23, v25, v23
	v_max_f32_e32 v25, v24, v15
	v_min_f32_e32 v15, v24, v15
	v_max_f32_e32 v29, v10, v27
	v_min_f32_e32 v10, v10, v27
	v_max_f32_e32 v27, v13, v18
	v_min_f32_e32 v13, v13, v18
	v_max_f32_e32 v18, v67, v28
	v_min_f32_e32 v28, v67, v28
	v_max_f32_e32 v67, v4, v3
	v_min_f32_e32 v3, v4, v3
	v_max_f32_e32 v4, v2, v0
	v_min_f32_e32 v0, v2, v0
	v_max_f32_e32 v2, v12, v19
	v_min_f32_e32 v12, v12, v19
	v_max_f32_e32 v19, v21, v20
	v_min_f32_e32 v20, v21, v20
	v_max_f32_e32 v21, v26, v11
	v_min_f32_e32 v11, v26, v11
	v_max_f32_e32 v24, v33, v6
	v_min_f32_e32 v6, v33, v6
	v_max_f32_e32 v33, v14, v9
	v_min_f32_e32 v9, v14, v9
	v_max_f32_e32 v14, v30, v8
	v_min_f32_e32 v8, v30, v8
	v_max_f32_e32 v30, v17, v7
	v_min_f32_e32 v7, v17, v7
	v_max_f32_e32 v17, v22, v23
	v_min_f32_e32 v22, v22, v23
	v_max_f32_e32 v23, v31, v16
	v_min_f32_e32 v16, v31, v16
	v_max_f32_e32 v31, v32, v15
	v_min_f32_e32 v15, v32, v15
	v_max_f32_e32 v32, v5, v25
	v_min_f32_e32 v5, v5, v25
	v_max_f32_e32 v26, v29, v0
	v_min_f32_e32 v0, v29, v0
	v_max_f32_e32 v29, v10, v4
	v_min_f32_e32 v4, v10, v4
	v_max_f32_e32 v10, v27, v12
	v_min_f32_e32 v12, v27, v12
	v_max_f32_e32 v27, v13, v2
	v_min_f32_e32 v2, v13, v2
	v_max_f32_e32 v13, v18, v20
	v_min_f32_e32 v18, v18, v20
	v_max_f32_e32 v20, v28, v19
	v_min_f32_e32 v19, v28, v19
	v_max_f32_e32 v28, v67, v11
	v_min_f32_e32 v11, v67, v11
	v_max_f32_e32 v67, v3, v21
	v_min_f32_e32 v3, v3, v21
	v_max_f32_e32 v25, v24, v17
	v_min_f32_e32 v17, v24, v17
	v_max_f32_e32 v24, v33, v23
	v_min_f32_e32 v23, v33, v23
	v_max_f32_e32 v33, v14, v31
	v_min_f32_e32 v14, v14, v31
	v_max_f32_e32 v31, v30, v32
	v_min_f32_e32 v30, v30, v32
	v_max_f32_e32 v32, v6, v22
	v_min_f32_e32 v6, v6, v22
	v_max_f32_e32 v22, v9, v16
	v_min_f32_e32 v9, v9, v16
	v_max_f32_e32 v16, v8, v15
	v_min_f32_e32 v8, v8, v15
	v_max_f32_e32 v15, v7, v5
	v_min_f32_e32 v5, v7, v5
	v_max_f32_e32 v21, v26, v13
	v_min_f32_e32 v13, v26, v13
	v_max_f32_e32 v26, v29, v20
	v_min_f32_e32 v20, v29, v20
	v_max_f32_e32 v29, v10, v28
	v_min_f32_e32 v10, v10, v28
	v_max_f32_e32 v28, v27, v67
	v_min_f32_e32 v27, v27, v67
	v_max_f32_e32 v67, v0, v18
	v_min_f32_e32 v0, v0, v18
	v_max_f32_e32 v18, v4, v19
	v_min_f32_e32 v4, v4, v19
	v_max_f32_e32 v19, v12, v11
	v_min_f32_e32 v11, v12, v11
; DEV void merge_xor(float (&l)[16], int mask) {
;   float t[16];
; #pragma unroll
;   for (int i = 0; i < 16; i++) t[i] = __shfl_xor(l[15 - i], mask);
; #pragma unroll
;   for (int i = 0; i < 16; i++) l[i] = fmaxf(l[i], t[i]);
;   bitonic16(l);
; DEV void peer_top16(const bf16_t* __restrict__ pq, const bf16_t* sk  , float (&l)[16]) {
;     ...
;   sort16_desc(l);
;   sort16_desc(hi);
; #pragma unroll
;   for (int i = 0; i < 16; i++) l[i] = fmaxf(l[i], hi[15 - i]);
;   bitonic16(l);
;   merge_xor(l, 16);
;   merge_xor(l, 32);
	v_max_f32_e32 v12, v2, v3
	v_min_f32_e32 v2, v2, v3
	v_max_f32_e32 v7, v25, v33
	v_min_f32_e32 v25, v25, v33
	v_max_f32_e32 v33, v24, v31
	v_min_f32_e32 v24, v24, v31
	v_max_f32_e32 v31, v17, v14
	v_min_f32_e32 v14, v17, v14
	v_max_f32_e32 v17, v23, v30
	v_min_f32_e32 v23, v23, v30
	v_max_f32_e32 v30, v32, v16
	v_min_f32_e32 v16, v32, v16
	v_max_f32_e32 v32, v22, v15
	v_min_f32_e32 v15, v22, v15
	v_max_f32_e32 v22, v6, v8
	v_min_f32_e32 v6, v6, v8
	v_max_f32_e32 v8, v9, v5
	v_min_f32_e32 v5, v9, v5
	v_max_f32_e32 v3, v21, v29
	v_min_f32_e32 v21, v21, v29
	v_max_f32_e32 v29, v26, v28
	v_min_f32_e32 v26, v26, v28
	v_max_f32_e32 v28, v13, v10
	v_min_f32_e32 v10, v13, v10
	v_max_f32_e32 v13, v20, v27
	v_min_f32_e32 v20, v20, v27
	v_max_f32_e32 v27, v67, v19
	v_min_f32_e32 v19, v67, v19
	v_max_f32_e32 v67, v18, v12
	v_min_f32_e32 v12, v18, v12
	v_max_f32_e32 v18, v0, v11
	v_min_f32_e32 v0, v0, v11
	v_max_f32_e32 v11, v4, v2
	v_min_f32_e32 v2, v4, v2
	v_min_f32_e32 v9, v7, v33
	v_min_f32_e32 v39, v25, v24
	v_min_f32_e32 v43, v31, v17
	v_min_f32_e32 v47, v14, v23
	v_min_f32_e32 v51, v30, v32
	v_min_f32_e32 v55, v16, v15
	v_min_f32_e32 v59, v22, v8
	v_min_f32_e32 v63, v6, v5
	v_min_f32_e32 v4, v3, v29
	v_min_f32_e32 v71, v21, v26
	v_min_f32_e32 v75, v28, v13
	v_min_f32_e32 v79, v10, v20
	v_min_f32_e32 v83, v27, v67
	v_min_f32_e32 v87, v19, v12
	v_min_f32_e32 v91, v18, v11
	v_min_f32_e32 v95, v0, v2
	v_max3_f32 v7, v7, v33, v95
	v_max3_f32 v0, v9, v0, v2
	v_max3_f32 v2, v25, v24, v91
	v_max3_f32 v9, v39, v18, v11
	v_max3_f32 v11, v31, v17, v87
	v_max3_f32 v12, v43, v19, v12
	v_max3_f32 v14, v14, v23, v83
	v_max3_f32 v17, v47, v27, v67
	v_max3_f32 v18, v30, v32, v79
	v_max3_f32 v10, v51, v10, v20
	v_max3_f32 v15, v16, v15, v75
	v_max3_f32 v13, v55, v28, v13
	v_max3_f32 v8, v22, v8, v71
	v_max3_f32 v16, v59, v21, v26
	v_max3_f32 v4, v6, v5, v4
	v_max3_f32 v3, v63, v3, v29
	v_max_f32_e32 v5, v7, v18
	v_min_f32_e32 v6, v7, v18
	v_max_f32_e32 v7, v0, v10
	v_min_f32_e32 v0, v0, v10
	v_max_f32_e32 v10, v2, v15
	v_min_f32_e32 v2, v2, v15
	v_max_f32_e32 v15, v9, v13
	v_min_f32_e32 v9, v9, v13
	v_max_f32_e32 v13, v11, v8
	v_min_f32_e32 v8, v11, v8
	v_max_f32_e32 v11, v12, v16
	v_min_f32_e32 v12, v12, v16
	v_max_f32_e32 v16, v14, v4
	v_min_f32_e32 v4, v14, v4
	v_max_f32_e32 v14, v17, v3
	v_min_f32_e32 v3, v17, v3
	v_max_f32_e32 v17, v5, v13
	v_min_f32_e32 v5, v5, v13
	v_max_f32_e32 v13, v7, v11
	v_min_f32_e32 v7, v7, v11
	v_max_f32_e32 v11, v10, v16
	v_min_f32_e32 v10, v10, v16
	v_max_f32_e32 v16, v15, v14
	v_min_f32_e32 v14, v15, v14
	v_max_f32_e32 v15, v6, v8
	v_min_f32_e32 v6, v6, v8
	v_max_f32_e32 v8, v0, v12
	v_min_f32_e32 v0, v0, v12
	v_max_f32_e32 v12, v2, v4
	v_min_f32_e32 v2, v2, v4
	v_max_f32_e32 v4, v9, v3
	v_min_f32_e32 v3, v9, v3
	v_max_f32_e32 v9, v17, v11
	v_min_f32_e32 v11, v17, v11
	v_max_f32_e32 v17, v13, v16
	v_min_f32_e32 v13, v13, v16
	v_max_f32_e32 v16, v5, v10
	v_min_f32_e32 v5, v5, v10
	v_max_f32_e32 v10, v7, v14
	v_min_f32_e32 v7, v7, v14
	v_max_f32_e32 v14, v15, v12
	v_min_f32_e32 v12, v15, v12
	v_max_f32_e32 v15, v8, v4
	v_min_f32_e32 v4, v8, v4
	v_max_f32_e32 v8, v6, v2
	v_min_f32_e32 v2, v6, v2
	v_max_f32_e32 v6, v0, v3
	v_min_f32_e32 v0, v0, v3
	v_max_f32_e32 v3, v9, v17
	v_min_f32_e32 v9, v9, v17
	v_max_f32_e32 v17, v11, v13
	v_min_f32_e32 v11, v11, v13
	v_max_f32_e32 v13, v16, v10
	v_min_f32_e32 v10, v16, v10
	v_max_f32_e32 v16, v5, v7
	v_min_f32_e32 v5, v5, v7
	v_max_f32_e32 v7, v14, v15
	v_min_f32_e32 v14, v14, v15
	v_max_f32_e32 v15, v12, v4
	v_min_f32_e32 v4, v12, v4
	v_max_f32_e32 v12, v8, v6
	v_min_f32_e32 v6, v8, v6
	v_max_f32_e32 v8, v2, v0
	v_min_f32_e32 v0, v2, v0
	v_mbcnt_hi_u32_b32 v2, -1, v215
	v_and_b32_e32 v19, 64, v2
	v_xor_b32_e32 v18, 16, v2
	v_add_u32_e32 v19, 64, v19
	v_cmp_lt_i32_e32 vcc, v18, v19
	s_add_u32 s8, s12, s8
	s_addc_u32 s9, s13, s9
	v_cndmask_b32_e32 v18, v2, v18, vcc
	v_lshlrev_b32_e32 v95, 2, v18
	ds_bpermute_b32 v18, v95, v0
	ds_bpermute_b32 v20, v95, v8
	ds_bpermute_b32 v21, v95, v6
	ds_bpermute_b32 v22, v95, v12
	ds_bpermute_b32 v23, v95, v4
	ds_bpermute_b32 v24, v95, v15
	s_waitcnt lgkmcnt(5)
	ds_bpermute_b32 v25, v95, v14
	ds_bpermute_b32 v39, v95, v3
	v_max_f32_e32 v3, v3, v18
	s_waitcnt lgkmcnt(6)
	ds_bpermute_b32 v26, v95, v7
	ds_bpermute_b32 v33, v95, v9
	v_max_f32_e32 v9, v9, v20
	s_waitcnt lgkmcnt(7)
	ds_bpermute_b32 v27, v95, v5
	ds_bpermute_b32 v32, v95, v17
	v_max_f32_e32 v17, v17, v21
	s_waitcnt lgkmcnt(8)
	ds_bpermute_b32 v28, v95, v16
	ds_bpermute_b32 v31, v95, v11
	v_max_f32_e32 v11, v11, v22
	s_waitcnt lgkmcnt(9)
	ds_bpermute_b32 v29, v95, v10
	ds_bpermute_b32 v30, v95, v13
	v_max_f32_e32 v13, v13, v23
	s_waitcnt lgkmcnt(10)
	v_max_f32_e32 v10, v10, v24
	s_waitcnt lgkmcnt(9)
	v_max_f32_e32 v16, v16, v25
	s_waitcnt lgkmcnt(7)
	v_max_f32_e32 v5, v5, v26
	s_waitcnt lgkmcnt(5)
	v_max_f32_e32 v7, v7, v27
	s_waitcnt lgkmcnt(3)
	v_max_f32_e32 v14, v14, v28
	s_waitcnt lgkmcnt(1)
	v_max_f32_e32 v15, v15, v29
	s_waitcnt lgkmcnt(0)
; DEV int tidx() { int t = threadIdx.x; asm volatile("" : "+v"(t)); return t; }
; DEV f32x4 mfma16(bf16x8 a, bf16x8 b, f32x4 c) { return __builtin_amdgcn_mfma_f32_16x16x32_bf16(a, b, c, 0, 0, 0); }
; DEV void merge_xor(float (&l)[16], int mask) {
;   float t[16];
; #pragma unroll
;   for (int i = 0; i < 16; i++) t[i] = __shfl_xor(l[15 - i], mask);
; #pragma unroll
;   for (int i = 0; i < 16; i++) l[i] = fmaxf(l[i], t[i]);
;   bitonic16(l);
; }
; DEV void peer_top16(const bf16_t* __restrict__ pq, const bf16_t* sk  , float (&l)[16]) {
;   const int lane = tidx() & 63, l15 = lane & 15, quad = lane >> 4;
;   f32x4 acc[8];
; #pragma unroll
;   for (int nt = 0; nt < 8; nt++) acc[nt] = (f32x4){0.f, 0.f, 0.f, 0.f};
; #pragma unroll 1
;   for (int ks = 0; ks < 4; ks++) {
;     const bf16x8 bqk = *(const bf16x8*)(pq + ks * 32 + quad * 8);
; #pragma unroll
;     for (int nt = 0; nt < 8; nt++) {
;       bf16x8 ak = *(const bf16x8*)(sk + (nt * 16 + l15) * 144 + ks * 32 + quad * 8);
;       acc[nt] = mfma16(ak, bqk, acc[nt]);
;     }
;   }
	v_max_f32_e32 v4, v4, v30
	v_max_f32_e32 v12, v12, v31
	v_max_f32_e32 v6, v6, v32
	v_max_f32_e32 v8, v8, v33
	v_max_f32_e32 v0, v0, v39
	v_max_f32_e32 v18, v3, v7
	v_min_f32_e32 v3, v3, v7
	v_max_f32_e32 v7, v9, v14
	v_min_f32_e32 v9, v9, v14
	v_max_f32_e32 v14, v17, v15
	v_min_f32_e32 v15, v17, v15
	v_max_f32_e32 v17, v11, v4
	v_min_f32_e32 v4, v11, v4
	v_max_f32_e32 v11, v13, v12
	v_min_f32_e32 v12, v13, v12
	v_max_f32_e32 v13, v10, v6
	v_min_f32_e32 v6, v10, v6
	v_max_f32_e32 v10, v16, v8
	v_min_f32_e32 v8, v16, v8
	v_max_f32_e32 v16, v5, v0
	v_min_f32_e32 v0, v5, v0
	v_max_f32_e32 v5, v18, v11
	v_min_f32_e32 v11, v18, v11
	v_max_f32_e32 v18, v7, v13
	v_min_f32_e32 v7, v7, v13
	v_max_f32_e32 v13, v14, v10
	v_min_f32_e32 v10, v14, v10
	v_max_f32_e32 v14, v17, v16
	v_min_f32_e32 v16, v17, v16
	v_max_f32_e32 v17, v3, v12
	v_min_f32_e32 v3, v3, v12
	v_max_f32_e32 v12, v9, v6
	v_min_f32_e32 v6, v9, v6
	v_max_f32_e32 v9, v15, v8
	v_min_f32_e32 v8, v15, v8
	v_max_f32_e32 v15, v4, v0
	v_min_f32_e32 v0, v4, v0
	v_max_f32_e32 v4, v5, v13
	v_min_f32_e32 v5, v5, v13
	v_max_f32_e32 v13, v18, v14
	v_min_f32_e32 v14, v18, v14
	v_max_f32_e32 v18, v11, v10
	v_min_f32_e32 v10, v11, v10
	v_max_f32_e32 v11, v7, v16
	v_min_f32_e32 v7, v7, v16
	v_max_f32_e32 v16, v17, v9
	v_min_f32_e32 v9, v17, v9
	v_max_f32_e32 v17, v12, v15
	v_min_f32_e32 v12, v12, v15
	v_max_f32_e32 v15, v3, v8
	v_min_f32_e32 v3, v3, v8
	v_max_f32_e32 v8, v6, v0
	v_min_f32_e32 v0, v6, v0
	v_max_f32_e32 v43, v3, v0
	v_min_f32_e32 v39, v3, v0
	v_xor_b32_e32 v0, 32, v2
	v_cmp_lt_i32_e32 vcc, v0, v19
	v_max_f32_e32 v109, v4, v13
	v_min_f32_e32 v107, v4, v13
	v_cndmask_b32_e32 v0, v2, v0, vcc
	v_max_f32_e32 v105, v5, v14
	v_min_f32_e32 v103, v5, v14
	v_max_f32_e32 v87, v18, v11
	v_min_f32_e32 v79, v18, v11
	v_max_f32_e32 v75, v10, v7
	v_min_f32_e32 v71, v10, v7
	v_max_f32_e32 v67, v16, v17
	v_min_f32_e32 v63, v16, v17
	v_max_f32_e32 v59, v9, v12
	v_min_f32_e32 v55, v9, v12
	v_max_f32_e32 v51, v15, v8
	v_min_f32_e32 v47, v15, v8
	v_lshlrev_b32_e32 v99, 2, v0
	v_mov_b32_e32 v0, v195
	ds_bpermute_b32 v121, v99, v39
	ds_bpermute_b32 v120, v99, v43
	ds_bpermute_b32 v119, v99, v47
	ds_bpermute_b32 v118, v99, v51
	ds_bpermute_b32 v116, v99, v55
	ds_bpermute_b32 v115, v99, v59
	ds_bpermute_b32 v114, v99, v63
	ds_bpermute_b32 v113, v99, v67
	ds_bpermute_b32 v112, v99, v71
	ds_bpermute_b32 v111, v99, v75
	ds_bpermute_b32 v110, v99, v79
	ds_bpermute_b32 v108, v99, v87
	ds_bpermute_b32 v106, v99, v103
	ds_bpermute_b32 v104, v99, v105
	ds_bpermute_b32 v91, v99, v107
	ds_bpermute_b32 v83, v99, v109
	s_mov_b32 s18, 0
	v_bfe_u32 v102, v0, 4, 2
	v_and_b32_e32 v2, 15, v0
	v_lshlrev_b32_e32 v0, 4, v102
	v_mad_u32_u24 v122, v2, s20, v0
	v_lshl_add_u64 v[2:3], v[100:101], 0, v[0:1]
	v_lshl_add_u64 v[100:101], s[8:9], 0, v[2:3]
	v_mov_b32_e32 v2, 0
	v_mov_b32_e32 v3, v2
	v_mov_b32_e32 v4, v2
	v_mov_b32_e32 v5, v2
	v_mov_b32_e32 v10, v2
	v_mov_b32_e32 v11, v2
	v_mov_b32_e32 v12, v2
	v_mov_b32_e32 v13, v2
	v_mov_b32_e32 v18, v2
	v_mov_b32_e32 v19, v2
	v_mov_b32_e32 v20, v2
	v_mov_b32_e32 v21, v2
	v_mov_b32_e32 v26, v2
	v_mov_b32_e32 v27, v2
	v_mov_b32_e32 v28, v2
	v_mov_b32_e32 v29, v2
	v_mov_b32_e32 v6, v2
	v_mov_b32_e32 v7, v2
	v_mov_b32_e32 v8, v2
	v_mov_b32_e32 v9, v2
	v_mov_b32_e32 v14, v2
	v_mov_b32_e32 v15, v2
	v_mov_b32_e32 v16, v2
	v_mov_b32_e32 v17, v2
	v_mov_b32_e32 v22, v2
	v_mov_b32_e32 v23, v2
	v_mov_b32_e32 v24, v2
	v_mov_b32_e32 v25, v2
	v_mov_b32_e32 v30, v2
	v_mov_b32_e32 v31, v2
	v_mov_b32_e32 v32, v2
	v_mov_b32_e32 v33, v2
.LBB0_635:
	global_load_dwordx4 v[124:127], v[100:101], off
	v_add_u32_e32 v0, s18, v122
	ds_read_b128 v[128:131], v0 offset:36864
	s_add_i32 s18, s18, 64
	v_lshl_add_u64 v[100:101], v[100:101], 0, 64
	s_cmpk_lg_i32 s18, 0x100
	s_waitcnt vmcnt(0) lgkmcnt(0)
	v_mfma_f32_16x16x32_bf16 v[30:33], v[128:131], v[124:127], v[30:33]
	ds_read_b128 v[128:131], v0 offset:41472
	s_waitcnt lgkmcnt(0)
	v_mfma_f32_16x16x32_bf16 v[22:25], v[128:131], v[124:127], v[22:25]
	ds_read_b128 v[128:131], v0 offset:46080
	s_waitcnt lgkmcnt(0)
	v_mfma_f32_16x16x32_bf16 v[14:17], v[128:131], v[124:127], v[14:17]
	ds_read_b128 v[128:131], v0 offset:50688
	s_waitcnt lgkmcnt(0)
	v_mfma_f32_16x16x32_bf16 v[6:9], v[128:131], v[124:127], v[6:9]
	ds_read_b128 v[128:131], v0 offset:55296
	s_waitcnt lgkmcnt(0)
	v_mfma_f32_16x16x32_bf16 v[26:29], v[128:131], v[124:127], v[26:29]
	ds_read_b128 v[128:131], v0 offset:59904
	s_waitcnt lgkmcnt(0)
	v_mfma_f32_16x16x32_bf16 v[18:21], v[128:131], v[124:127], v[18:21]
	ds_read_b128 v[128:131], v0 offset:64512
	v_add_u32_e32 v0, 0x10e00, v0
	s_waitcnt lgkmcnt(0)
	v_mfma_f32_16x16x32_bf16 v[10:13], v[128:131], v[124:127], v[10:13]
	ds_read_b128 v[128:131], v0
	s_waitcnt lgkmcnt(0)
	v_mfma_f32_16x16x32_bf16 v[2:5], v[128:131], v[124:127], v[2:5]
	s_cbranch_scc1 .LBB0_635
; DEV int tidx() { int t = threadIdx.x; asm volatile("" : "+v"(t)); return t; }
; DEV f32x4 mfma16(bf16x8 a, bf16x8 b, f32x4 c) { return __builtin_amdgcn_mfma_f32_16x16x32_bf16(a, b, c, 0, 0, 0); }
; DEV void merge_xor(float (&l)[16], int mask) {
;   float t[16];
; #pragma unroll
;   for (int i = 0; i < 16; i++) t[i] = __shfl_xor(l[15 - i], mask);
; #pragma unroll
;   for (int i = 0; i < 16; i++) l[i] = fmaxf(l[i], t[i]);
;   bitonic16(l);
; }
; DEV void peer_top16(const bf16_t* __restrict__ pq, const bf16_t* sk  , float (&l)[16]) {
;   const int lane = tidx() & 63, l15 = lane & 15, quad = lane >> 4;
;   f32x4 acc[8];
; #pragma unroll
;   for (int nt = 0; nt < 8; nt++) acc[nt] = (f32x4){0.f, 0.f, 0.f, 0.f};
; #pragma unroll 1
;   for (int ks = 0; ks < 4; ks++) {
;     const bf16x8 bqk = *(const bf16x8*)(pq + ks * 32 + quad * 8);
; #pragma unroll
;     for (int nt = 0; nt < 8; nt++) {
;       bf16x8 ak = *(const bf16x8*)(sk + (nt * 16 + l15) * 144 + ks * 32 + quad * 8);
;       acc[nt] = mfma16(ak, bqk, acc[nt]);
;     }
;   }
;   float hi[16];
; #pragma unroll
;   for (int nt = 0; nt < 4; nt++)
; #pragma unroll
;     for (int r = 0; r < 4; r++) {
;       l[nt * 4 + r] = __uint_as_float((__float_as_uint(acc[nt][r]) & ~127u) | (unsigned)(nt * 16 + quad * 4 + r));
;       hi[nt * 4 + r] = __uint_as_float((__float_as_uint(acc[nt + 4][r]) & ~127u) | (unsigned)((nt + 4) * 16 + quad * 4 + r));
;     }
;   sort16_desc(l);
;   sort16_desc(hi);
	v_max_f32_e32 v0, v109, v121
	v_max_f32_e32 v100, v107, v120
	v_max_f32_e32 v101, v105, v119
	v_max_f32_e32 v103, v103, v118
	v_max_f32_e32 v87, v87, v116
	v_max_f32_e32 v79, v79, v115
	v_max_f32_e32 v75, v75, v114
	v_max_f32_e32 v71, v71, v113
	v_max_f32_e32 v67, v67, v112
	v_max_f32_e32 v63, v63, v111
	v_max_f32_e32 v59, v59, v110
	v_max_f32_e32 v55, v55, v108
	v_max_f32_e32 v51, v51, v106
	v_max_f32_e32 v47, v47, v104
	v_max_f32_e32 v43, v43, v91
	v_max_f32_e32 v39, v39, v83
	v_max_f32_e32 v83, v0, v67
	v_min_f32_e32 v0, v0, v67
	v_max_f32_e32 v67, v100, v63
	v_min_f32_e32 v63, v100, v63
	v_max_f32_e32 v91, v101, v59
	v_min_f32_e32 v59, v101, v59
	v_max_f32_e32 v100, v103, v55
	v_min_f32_e32 v55, v103, v55
	v_max_f32_e32 v101, v87, v51
	v_min_f32_e32 v51, v87, v51
	v_max_f32_e32 v87, v79, v47
	v_min_f32_e32 v47, v79, v47
	v_max_f32_e32 v79, v75, v43
	v_min_f32_e32 v43, v75, v43
	v_max_f32_e32 v75, v71, v39
	v_min_f32_e32 v39, v71, v39
	v_max_f32_e32 v71, v83, v101
	v_min_f32_e32 v101, v83, v101
	v_max_f32_e32 v103, v67, v87
	v_min_f32_e32 v67, v67, v87
	v_max_f32_e32 v87, v91, v79
	v_min_f32_e32 v79, v91, v79
	v_max_f32_e32 v91, v100, v75
	v_min_f32_e32 v75, v100, v75
	v_max_f32_e32 v100, v0, v51
	v_min_f32_e32 v0, v0, v51
	v_max_f32_e32 v51, v63, v47
	v_max_f32_e32 v105, v59, v43
	v_min_f32_e32 v43, v59, v43
	v_max_f32_e32 v59, v55, v39
	v_min_f32_e32 v107, v101, v79
	v_min_f32_e32 v108, v67, v75
	v_min_f32_e32 v110, v51, v59
	v_max_f32_e32 v79, v101, v79
	v_max_f32_e32 v67, v67, v75
	v_max_f32_e32 v101, v100, v105
	v_max_f32_e32 v51, v51, v59
	v_min_f32_e32 v75, v79, v67
	v_min_f32_e32 v59, v101, v51
	v_max_f32_e32 v79, v79, v67
	v_max_f32_e32 v67, v101, v51
	v_lshlrev_b32_e32 v101, 2, v102
	s_movk_i32 s8, 0xff80
	v_and_or_b32 v30, v30, s8, v101
	v_and_b32_e32 v27, 0xffffff80, v27
	s_movk_i32 s8, 0x41
	v_or3_b32 v27, v101, v27, s8
	v_and_b32_e32 v28, 0xffffff80, v28
	s_movk_i32 s8, 0x42
	v_or3_b32 v28, v101, v28, s8
	v_and_b32_e32 v29, 0xffffff80, v29
	s_movk_i32 s8, 0x43
	v_or3_b32 v29, v101, v29, s8
	v_and_b32_e32 v18, 0xffffff80, v18
	s_movk_i32 s8, 0x50
	v_or3_b32 v18, v101, v18, s8
	v_and_b32_e32 v19, 0xffffff80, v19
	s_movk_i32 s8, 0x51
	v_or3_b32 v19, v101, v19, s8
	v_and_b32_e32 v20, 0xffffff80, v20
	s_movk_i32 s8, 0x52
	v_or3_b32 v20, v101, v20, s8
	v_and_b32_e32 v21, 0xffffff80, v21
	s_movk_i32 s8, 0x53
	v_or3_b32 v21, v101, v21, s8
	v_and_b32_e32 v10, 0xffffff80, v10
	s_movk_i32 s8, 0x60
	v_or3_b32 v10, v101, v10, s8
	v_and_b32_e32 v11, 0xffffff80, v11
	s_movk_i32 s8, 0x61
	v_or3_b32 v11, v101, v11, s8
	v_and_b32_e32 v12, 0xffffff80, v12
	s_movk_i32 s8, 0x62
	v_or3_b32 v12, v101, v12, s8
	v_and_b32_e32 v13, 0xffffff80, v13
	s_movk_i32 s8, 0x63
	v_or3_b32 v13, v101, v13, s8
	v_and_b32_e32 v2, 0xffffff80, v2
	s_movk_i32 s8, 0x70
	v_and_b32_e32 v26, 0xffffff80, v26
	v_and_b32_e32 v31, 0xffffff80, v31
	v_or3_b32 v2, v101, v2, s8
	v_and_b32_e32 v3, 0xffffff80, v3
	s_movk_i32 s8, 0x71
	v_or3_b32 v26, v101, v26, 64
	v_or3_b32 v31, v101, v31, 1
	v_and_b32_e32 v32, 0xffffff80, v32
	v_and_b32_e32 v33, 0xffffff80, v33
	v_and_b32_e32 v22, 0xffffff80, v22
	v_and_b32_e32 v23, 0xffffff80, v23
	v_or3_b32 v3, v101, v3, s8
	v_and_b32_e32 v4, 0xffffff80, v4
	s_movk_i32 s8, 0x72
	v_min_f32_e32 v39, v55, v39
	v_min_f32_e32 v55, v71, v87
	v_min_f32_e32 v106, v103, v91
	v_min_f32_e32 v109, v100, v105
	v_max_f32_e32 v71, v71, v87
	v_max_f32_e32 v87, v103, v91
	v_or3_b32 v32, v101, v32, 2
	v_or3_b32 v33, v101, v33, 3
	v_or3_b32 v22, v101, v22, 16
	v_or3_b32 v23, v101, v23, 17
	v_and_b32_e32 v24, 0xffffff80, v24
	v_and_b32_e32 v25, 0xffffff80, v25
	v_and_b32_e32 v14, 0xffffff80, v14
	v_and_b32_e32 v15, 0xffffff80, v15
	v_and_b32_e32 v16, 0xffffff80, v16
	v_and_b32_e32 v17, 0xffffff80, v17
	v_and_b32_e32 v6, 0xffffff80, v6
	v_and_b32_e32 v7, 0xffffff80, v7
	v_and_b32_e32 v8, 0xffffff80, v8
	v_or3_b32 v4, v101, v4, s8
	v_and_b32_e32 v9, 0xffffff80, v9
	v_and_b32_e32 v5, 0xffffff80, v5
	s_movk_i32 s8, 0x73
	v_min_f32_e32 v104, v63, v47
	v_min_f32_e32 v83, v55, v106
	v_min_f32_e32 v47, v109, v110
	v_min_f32_e32 v91, v71, v87
	v_max_f32_e32 v100, v71, v87
	v_max_f32_e32 v87, v55, v106
	v_max_f32_e32 v55, v109, v110
	v_or3_b32 v24, v101, v24, 18
	v_or3_b32 v25, v101, v25, 19
	v_or3_b32 v14, v101, v14, 32
	v_or3_b32 v15, v101, v15, 33
	v_or3_b32 v16, v101, v16, 34
	v_or3_b32 v17, v101, v17, 35
	v_or3_b32 v6, v101, v6, 48
	v_or3_b32 v7, v101, v7, 49
	v_or3_b32 v8, v101, v8, 50
	v_or3_b32 v9, v101, v9, 51
	v_or3_b32 v5, v101, v5, s8
	v_max_f32_e32 v101, v30, v31
	v_min_f32_e32 v30, v30, v31
	v_max_f32_e32 v31, v32, v32
	v_max_f32_e32 v32, v33, v33
	v_max_f32_e32 v109, v26, v27
	v_min_f32_e32 v26, v26, v27
	v_max_f32_e32 v27, v28, v28
	v_max_f32_e32 v28, v29, v29
	v_max_f32_e32 v33, v32, v31
	v_min_f32_e32 v31, v32, v31
	v_max_f32_e32 v32, v22, v23
	v_min_f32_e32 v22, v22, v23
	v_max_f32_e32 v23, v24, v24
	v_max_f32_e32 v24, v25, v25
	v_max_f32_e32 v29, v28, v27
	v_min_f32_e32 v27, v28, v27
	v_max_f32_e32 v28, v18, v19
	v_min_f32_e32 v18, v18, v19
	v_max_f32_e32 v19, v20, v20
	v_max_f32_e32 v20, v21, v21
	v_max_f32_e32 v25, v24, v23
	v_min_f32_e32 v23, v24, v23
	v_max_f32_e32 v24, v14, v15
	v_min_f32_e32 v14, v14, v15
	v_max_f32_e32 v15, v16, v16
	v_max_f32_e32 v16, v17, v17
	v_max_f32_e32 v21, v20, v19
	v_min_f32_e32 v19, v20, v19
	v_max_f32_e32 v20, v10, v11
	v_min_f32_e32 v10, v10, v11
	v_max_f32_e32 v11, v12, v12
	v_max_f32_e32 v12, v13, v13
	v_max_f32_e32 v17, v16, v15
	v_min_f32_e32 v15, v16, v15
	v_max_f32_e32 v16, v6, v7
	v_min_f32_e32 v6, v6, v7
	v_max_f32_e32 v7, v8, v8
	v_max_f32_e32 v8, v9, v9
	v_max_f32_e32 v13, v12, v11
	v_min_f32_e32 v11, v12, v11
; DEV void ce(float& a, float& b) { float hi = fmaxf(a, b), lo = fminf(a, b); a = hi; b = lo; }
; DEV void sort16_desc(float (&a)[16]) {
; #pragma unroll
;   for (int k = 2; k <= 16; k <<= 1)
; #pragma unroll
;     for (int j = k >> 1; j > 0; j >>= 1)
; #pragma unroll
;       for (int i = 0; i < 16; i++) {
;         const int p = i ^ j;
;         if (p > i) { if ((i & k) == 0) ce(a[i], a[p]); else ce(a[p], a[i]); }
;       }
; }
	v_max_f32_e32 v12, v2, v3
	v_min_f32_e32 v2, v2, v3
	v_max_f32_e32 v3, v4, v4
	v_max_f32_e32 v4, v5, v5
	v_max_f32_e32 v9, v8, v7
	v_min_f32_e32 v7, v8, v7
	v_max_f32_e32 v5, v4, v3
	v_min_f32_e32 v3, v4, v3
	v_max_f32_e32 v8, v101, v31
	v_min_f32_e32 v31, v101, v31
	v_max_f32_e32 v101, v30, v33
	v_min_f32_e32 v30, v30, v33
	v_max_f32_e32 v33, v23, v32
	v_min_f32_e32 v23, v23, v32
	v_max_f32_e32 v32, v25, v22
	v_min_f32_e32 v22, v25, v22
	v_max_f32_e32 v25, v24, v15
	v_min_f32_e32 v15, v24, v15
	v_max_f32_e32 v24, v14, v17
	v_min_f32_e32 v14, v14, v17
	v_max_f32_e32 v17, v7, v16
	v_min_f32_e32 v7, v7, v16
	v_max_f32_e32 v16, v9, v6
	v_min_f32_e32 v6, v9, v6
	v_max_f32_e32 v4, v109, v27
	v_min_f32_e32 v27, v109, v27
	v_max_f32_e32 v109, v26, v29
	v_min_f32_e32 v26, v26, v29
	v_max_f32_e32 v29, v19, v28
	v_min_f32_e32 v19, v19, v28
	v_max_f32_e32 v28, v21, v18
	v_min_f32_e32 v18, v21, v18
	v_max_f32_e32 v21, v20, v11
	v_min_f32_e32 v11, v20, v11
	v_max_f32_e32 v20, v10, v13
	v_min_f32_e32 v10, v10, v13
	v_max_f32_e32 v13, v3, v12
	v_min_f32_e32 v3, v3, v12
	v_max_f32_e32 v12, v5, v2
	v_min_f32_e32 v2, v5, v2
	v_max_f32_e32 v9, v8, v101
	v_min_f32_e32 v8, v8, v101
	v_max_f32_e32 v101, v31, v30
	v_min_f32_e32 v30, v31, v30
	v_max_f32_e32 v31, v22, v23
	v_min_f32_e32 v22, v22, v23
	v_max_f32_e32 v23, v32, v33
	v_min_f32_e32 v32, v32, v33
	v_max_f32_e32 v33, v25, v24
	v_min_f32_e32 v24, v25, v24
	v_max_f32_e32 v25, v15, v14
	v_min_f32_e32 v14, v15, v14
	v_max_f32_e32 v15, v6, v7
	v_min_f32_e32 v6, v6, v7
	v_max_f32_e32 v7, v16, v17
	v_min_f32_e32 v16, v16, v17
	v_max_f32_e32 v5, v4, v109
	v_min_f32_e32 v4, v4, v109
	v_max_f32_e32 v109, v27, v26
	v_min_f32_e32 v26, v27, v26
	v_max_f32_e32 v27, v18, v19
	v_min_f32_e32 v18, v18, v19
	v_max_f32_e32 v19, v28, v29
	v_min_f32_e32 v28, v28, v29
	v_max_f32_e32 v29, v21, v20
	v_min_f32_e32 v20, v21, v20
	v_max_f32_e32 v21, v11, v10
	v_min_f32_e32 v10, v11, v10
	v_max_f32_e32 v11, v2, v3
	v_min_f32_e32 v2, v2, v3
	v_max_f32_e32 v3, v12, v13
	v_min_f32_e32 v12, v12, v13
	v_max_f32_e32 v17, v9, v22
	v_min_f32_e32 v9, v9, v22
	v_max_f32_e32 v22, v8, v31
	v_min_f32_e32 v8, v8, v31
	v_max_f32_e32 v31, v101, v32
	v_min_f32_e32 v32, v101, v32
	v_max_f32_e32 v101, v30, v23
	v_min_f32_e32 v23, v30, v23
	v_max_f32_e32 v30, v6, v33
	v_min_f32_e32 v6, v6, v33
	v_max_f32_e32 v33, v15, v24
	v_min_f32_e32 v15, v15, v24
	v_max_f32_e32 v24, v16, v25
	v_min_f32_e32 v16, v16, v25
	v_max_f32_e32 v25, v7, v14
	v_min_f32_e32 v7, v7, v14
	v_max_f32_e32 v13, v5, v18
	v_min_f32_e32 v5, v5, v18
	v_max_f32_e32 v18, v4, v27
	v_min_f32_e32 v4, v4, v27
	v_max_f32_e32 v27, v109, v28
	v_min_f32_e32 v28, v109, v28
	v_max_f32_e32 v109, v26, v19
	v_min_f32_e32 v19, v26, v19
	v_max_f32_e32 v26, v2, v29
	v_min_f32_e32 v2, v2, v29
	v_max_f32_e32 v29, v11, v20
	v_min_f32_e32 v11, v11, v20
	v_max_f32_e32 v20, v12, v21
	v_min_f32_e32 v12, v12, v21
	v_max_f32_e32 v21, v3, v10
	v_min_f32_e32 v3, v3, v10
	v_max_f32_e32 v14, v17, v31
	v_min_f32_e32 v17, v17, v31
	v_max_f32_e32 v31, v22, v101
	v_min_f32_e32 v22, v22, v101
	v_max_f32_e32 v101, v9, v32
	v_min_f32_e32 v9, v9, v32
	v_max_f32_e32 v32, v8, v23
	v_min_f32_e32 v8, v8, v23
	v_max_f32_e32 v23, v16, v6
	v_min_f32_e32 v6, v16, v6
	v_max_f32_e32 v16, v7, v15
	v_min_f32_e32 v7, v7, v15
	v_max_f32_e32 v15, v24, v30
	v_min_f32_e32 v24, v24, v30
	v_max_f32_e32 v30, v25, v33
	v_min_f32_e32 v25, v25, v33
	v_max_f32_e32 v10, v13, v27
	v_min_f32_e32 v13, v13, v27
	v_max_f32_e32 v27, v18, v109
	v_min_f32_e32 v18, v18, v109
	v_max_f32_e32 v109, v5, v28
	v_min_f32_e32 v5, v5, v28
	v_max_f32_e32 v28, v4, v19
	v_min_f32_e32 v4, v4, v19
	v_max_f32_e32 v19, v12, v2
	v_min_f32_e32 v2, v12, v2
	v_max_f32_e32 v12, v3, v11
	v_min_f32_e32 v3, v3, v11
	v_max_f32_e32 v11, v20, v26
	v_min_f32_e32 v20, v20, v26
	v_max_f32_e32 v26, v21, v29
	v_min_f32_e32 v21, v21, v29
	v_max_f32_e32 v33, v14, v31
	v_min_f32_e32 v14, v14, v31
	v_max_f32_e32 v31, v17, v22
	v_min_f32_e32 v17, v17, v22
	v_max_f32_e32 v22, v101, v32
	v_min_f32_e32 v32, v101, v32
	v_max_f32_e32 v101, v9, v8
	v_min_f32_e32 v8, v9, v8
	v_max_f32_e32 v9, v7, v6
	v_min_f32_e32 v6, v7, v6
	v_max_f32_e32 v7, v16, v23
	v_min_f32_e32 v16, v16, v23
	v_max_f32_e32 v23, v25, v24
	v_min_f32_e32 v24, v25, v24
	v_max_f32_e32 v25, v30, v15
	v_min_f32_e32 v15, v30, v15
	v_max_f32_e32 v29, v10, v27
	v_min_f32_e32 v10, v10, v27
	v_max_f32_e32 v27, v13, v18
	v_min_f32_e32 v13, v13, v18
	v_max_f32_e32 v18, v109, v28
	v_min_f32_e32 v28, v109, v28
	v_max_f32_e32 v109, v5, v4
	v_min_f32_e32 v4, v5, v4
	v_max_f32_e32 v5, v3, v2
	v_min_f32_e32 v2, v3, v2
	v_max_f32_e32 v3, v12, v19
	v_min_f32_e32 v12, v12, v19
	v_max_f32_e32 v19, v21, v20
	v_min_f32_e32 v20, v21, v20
	v_max_f32_e32 v21, v26, v11
	v_min_f32_e32 v11, v26, v11
	v_max_f32_e32 v30, v33, v6
	v_min_f32_e32 v6, v33, v6
	v_max_f32_e32 v33, v14, v9
	v_min_f32_e32 v9, v14, v9
	v_max_f32_e32 v14, v31, v16
	v_min_f32_e32 v16, v31, v16
	v_max_f32_e32 v31, v17, v7
	v_min_f32_e32 v7, v17, v7
	v_max_f32_e32 v17, v22, v24
	v_min_f32_e32 v22, v22, v24
	v_max_f32_e32 v24, v32, v23
	v_min_f32_e32 v23, v32, v23
	v_max_f32_e32 v32, v101, v15
	v_min_f32_e32 v15, v101, v15
	v_max_f32_e32 v101, v8, v25
	v_min_f32_e32 v8, v8, v25
	v_max_f32_e32 v26, v29, v2
	v_min_f32_e32 v2, v29, v2
	v_max_f32_e32 v29, v10, v5
	v_min_f32_e32 v5, v10, v5
	v_max_f32_e32 v10, v27, v12
	v_min_f32_e32 v12, v27, v12
	v_max_f32_e32 v27, v13, v3
	v_min_f32_e32 v3, v13, v3
	v_max_f32_e32 v13, v18, v20
	v_min_f32_e32 v18, v18, v20
	v_max_f32_e32 v20, v28, v19
	v_min_f32_e32 v19, v28, v19
	v_max_f32_e32 v28, v109, v11
	v_min_f32_e32 v11, v109, v11
	v_max_f32_e32 v109, v4, v21
; DEV void ce(float& a, float& b) { float hi = fmaxf(a, b), lo = fminf(a, b); a = hi; b = lo; }
; DEV void bitonic16(float (&l)[16]) {
; #pragma unroll
;   for (int s = 8; s > 0; s >>= 1)
; #pragma unroll
;     for (int i = 0; i < 16; i++)
;       if (!(i & s)) ce(l[i], l[i + s]);
; }
; DEV void sort16_desc(float (&a)[16]) {
; #pragma unroll
;   for (int k = 2; k <= 16; k <<= 1)
; #pragma unroll
;     for (int j = k >> 1; j > 0; j >>= 1)
; #pragma unroll
;       for (int i = 0; i < 16; i++) {
;         const int p = i ^ j;
;         if (p > i) { if ((i & k) == 0) ce(a[i], a[p]); else ce(a[p], a[i]); }
;       }
; }
; DEV void merge_xor(float (&l)[16], int mask) {
;   float t[16];
; #pragma unroll
;   for (int i = 0; i < 16; i++) t[i] = __shfl_xor(l[15 - i], mask);
; #pragma unroll
;   for (int i = 0; i < 16; i++) l[i] = fmaxf(l[i], t[i]);
;   bitonic16(l);
	v_min_f32_e32 v4, v4, v21
	v_max_f32_e32 v25, v30, v17
	v_min_f32_e32 v17, v30, v17
	v_max_f32_e32 v30, v33, v24
	v_min_f32_e32 v24, v33, v24
	v_max_f32_e32 v33, v14, v32
	v_min_f32_e32 v14, v14, v32
	v_max_f32_e32 v32, v31, v101
	v_min_f32_e32 v31, v31, v101
	v_max_f32_e32 v101, v6, v22
	v_min_f32_e32 v6, v6, v22
	v_max_f32_e32 v22, v9, v23
	v_min_f32_e32 v9, v9, v23
	v_max_f32_e32 v23, v16, v15
	v_min_f32_e32 v15, v16, v15
	v_max_f32_e32 v16, v7, v8
	v_min_f32_e32 v7, v7, v8
	v_max_f32_e32 v21, v26, v13
	v_min_f32_e32 v13, v26, v13
	v_max_f32_e32 v26, v29, v20
	v_min_f32_e32 v20, v29, v20
	v_max_f32_e32 v29, v10, v28
	v_min_f32_e32 v10, v10, v28
	v_max_f32_e32 v28, v27, v109
	v_min_f32_e32 v27, v27, v109
	v_max_f32_e32 v109, v2, v18
	v_min_f32_e32 v2, v2, v18
	v_max_f32_e32 v18, v5, v19
	v_min_f32_e32 v5, v5, v19
	v_max_f32_e32 v19, v12, v11
	v_min_f32_e32 v11, v12, v11
	v_max_f32_e32 v12, v3, v4
	v_min_f32_e32 v3, v3, v4
	v_max_f32_e32 v111, v0, v43
	v_min_f32_e32 v112, v104, v39
	v_max_f32_e32 v103, v104, v39
	v_min_f32_e32 v0, v0, v43
	v_max_f32_e32 v8, v25, v33
	v_min_f32_e32 v25, v25, v33
	v_max_f32_e32 v33, v30, v32
	v_min_f32_e32 v30, v30, v32
	v_max_f32_e32 v32, v17, v14
	v_min_f32_e32 v14, v17, v14
	v_max_f32_e32 v17, v24, v31
	v_min_f32_e32 v24, v24, v31
	v_max_f32_e32 v31, v101, v23
	v_min_f32_e32 v23, v101, v23
	v_max_f32_e32 v101, v22, v16
	v_min_f32_e32 v16, v22, v16
	v_max_f32_e32 v22, v6, v15
	v_min_f32_e32 v6, v6, v15
	v_max_f32_e32 v15, v9, v7
	v_min_f32_e32 v7, v9, v7
	v_max_f32_e32 v4, v21, v29
	v_min_f32_e32 v21, v21, v29
	v_max_f32_e32 v29, v26, v28
	v_min_f32_e32 v26, v26, v28
	v_max_f32_e32 v28, v13, v10
	v_min_f32_e32 v10, v13, v10
	v_max_f32_e32 v13, v20, v27
	v_min_f32_e32 v20, v20, v27
	v_max_f32_e32 v27, v109, v19
	v_min_f32_e32 v19, v109, v19
	v_max_f32_e32 v109, v18, v12
	v_min_f32_e32 v12, v18, v12
	v_max_f32_e32 v18, v2, v11
	v_min_f32_e32 v2, v2, v11
	v_max_f32_e32 v11, v5, v3
	v_min_f32_e32 v3, v5, v3
	v_min_f32_e32 v63, v107, v108
	v_min_f32_e32 v39, v111, v103
	v_max_f32_e32 v71, v107, v108
	v_max_f32_e32 v51, v111, v103
	v_max_f32_e32 v43, v0, v112
	v_min_f32_e32 v0, v0, v112
	v_min_f32_e32 v9, v8, v33
	v_min_f32_e32 v102, v25, v30
	v_min_f32_e32 v103, v32, v17
	v_min_f32_e32 v104, v14, v24
	v_min_f32_e32 v105, v31, v101
	v_min_f32_e32 v106, v23, v16
	v_min_f32_e32 v107, v22, v15
	v_min_f32_e32 v108, v6, v7
	v_min_f32_e32 v5, v4, v29
	v_min_f32_e32 v110, v21, v26
	v_min_f32_e32 v111, v28, v13
	v_min_f32_e32 v112, v10, v20
	v_min_f32_e32 v113, v27, v109
	v_min_f32_e32 v114, v19, v12
	v_min_f32_e32 v115, v18, v11
	v_min_f32_e32 v116, v2, v3
	v_max3_f32 v8, v8, v33, v116
	v_max3_f32 v2, v9, v2, v3
	v_max3_f32 v3, v25, v30, v115
	v_max3_f32 v9, v102, v18, v11
	v_max3_f32 v11, v32, v17, v114
	v_max3_f32 v12, v103, v19, v12
	v_max3_f32 v14, v14, v24, v113
	v_max3_f32 v17, v104, v27, v109
	v_max3_f32 v18, v31, v101, v112
	v_max3_f32 v10, v105, v10, v20
	v_max3_f32 v16, v23, v16, v111
	v_max3_f32 v13, v106, v28, v13
	v_max3_f32 v15, v22, v15, v110
	v_max3_f32 v19, v107, v21, v26
	v_max3_f32 v5, v6, v7, v5
	v_max3_f32 v4, v108, v4, v29
	v_max_f32_e32 v6, v8, v18
	v_min_f32_e32 v7, v8, v18
	v_max_f32_e32 v8, v2, v10
	v_min_f32_e32 v2, v2, v10
	v_max_f32_e32 v10, v3, v16
	v_min_f32_e32 v3, v3, v16
	v_max_f32_e32 v16, v9, v13
	v_min_f32_e32 v9, v9, v13
	v_max_f32_e32 v13, v11, v15
	v_min_f32_e32 v11, v11, v15
	v_max_f32_e32 v15, v12, v19
	v_min_f32_e32 v12, v12, v19
	v_max_f32_e32 v18, v14, v5
	v_min_f32_e32 v5, v14, v5
	v_max_f32_e32 v14, v17, v4
	v_min_f32_e32 v4, v17, v4
	v_max_f32_e32 v17, v6, v13
	v_min_f32_e32 v6, v6, v13
	v_max_f32_e32 v13, v8, v15
	v_min_f32_e32 v8, v8, v15
	v_max_f32_e32 v15, v10, v18
	v_min_f32_e32 v10, v10, v18
	v_max_f32_e32 v18, v16, v14
	v_min_f32_e32 v14, v16, v14
	v_max_f32_e32 v16, v7, v11
	v_min_f32_e32 v7, v7, v11
	v_max_f32_e32 v11, v2, v12
	v_min_f32_e32 v2, v2, v12
	v_max_f32_e32 v12, v3, v5
	v_min_f32_e32 v3, v3, v5
	v_max_f32_e32 v5, v9, v4
	v_min_f32_e32 v4, v9, v4
	v_max_f32_e32 v9, v17, v15
	v_min_f32_e32 v15, v17, v15
	v_max_f32_e32 v17, v13, v18
	v_min_f32_e32 v13, v13, v18
	v_max_f32_e32 v18, v6, v10
	v_min_f32_e32 v6, v6, v10
	v_max_f32_e32 v10, v8, v14
	v_min_f32_e32 v8, v8, v14
	v_max_f32_e32 v14, v16, v12
	v_min_f32_e32 v12, v16, v12
	v_max_f32_e32 v16, v11, v5
	v_min_f32_e32 v5, v11, v5
	v_max_f32_e32 v11, v7, v3
	v_min_f32_e32 v3, v7, v3
	v_max_f32_e32 v7, v2, v4
	v_min_f32_e32 v2, v2, v4
	v_max_f32_e32 v4, v9, v17
	v_min_f32_e32 v9, v9, v17
	v_max_f32_e32 v17, v15, v13
	v_min_f32_e32 v13, v15, v13
	v_max_f32_e32 v15, v18, v10
	v_min_f32_e32 v10, v18, v10
	v_max_f32_e32 v18, v6, v8
	v_min_f32_e32 v6, v6, v8
	v_max_f32_e32 v8, v14, v16
	v_min_f32_e32 v14, v14, v16
	v_max_f32_e32 v16, v12, v5
	v_min_f32_e32 v5, v12, v5
	v_max_f32_e32 v12, v11, v7
	v_min_f32_e32 v7, v11, v7
	v_max_f32_e32 v11, v3, v2
	v_min_f32_e32 v2, v3, v2
	ds_bpermute_b32 v3, v95, v2
	ds_bpermute_b32 v19, v95, v11
	ds_bpermute_b32 v20, v95, v7
	ds_bpermute_b32 v21, v95, v12
	ds_bpermute_b32 v22, v95, v5
	ds_bpermute_b32 v23, v95, v16
	s_waitcnt lgkmcnt(5)
	ds_bpermute_b32 v24, v95, v14
	ds_bpermute_b32 v33, v95, v4
	v_max_f32_e32 v3, v4, v3
	s_waitcnt lgkmcnt(6)
	ds_bpermute_b32 v25, v95, v8
	ds_bpermute_b32 v32, v95, v9
	v_max_f32_e32 v4, v9, v19
	s_waitcnt lgkmcnt(7)
	ds_bpermute_b32 v26, v95, v6
	ds_bpermute_b32 v31, v95, v17
	v_max_f32_e32 v9, v17, v20
	s_waitcnt lgkmcnt(8)
	ds_bpermute_b32 v27, v95, v18
	ds_bpermute_b32 v30, v95, v13
	v_max_f32_e32 v13, v13, v21
	s_waitcnt lgkmcnt(9)
	ds_bpermute_b32 v28, v95, v10
	ds_bpermute_b32 v29, v95, v15
	v_max_f32_e32 v15, v15, v22
	s_waitcnt lgkmcnt(10)
; DEV void merge_xor(float (&l)[16], int mask) {
;   float t[16];
; #pragma unroll
;   for (int i = 0; i < 16; i++) t[i] = __shfl_xor(l[15 - i], mask);
; #pragma unroll
;   for (int i = 0; i < 16; i++) l[i] = fmaxf(l[i], t[i]);
;   bitonic16(l);
; }
; DEV void phase_peer_score(const Params& p, int layer, int M, char* smem) {
;     ...
;     unsigned char* tab = (unsigned char*)smem + 73728 + (w * 16 + l15) * 32;
; #pragma unroll
;     for (int i = 0; i < 16; i++) { tab[i] = (unsigned char)(__float_as_uint(L0[i]) & 127u); tab[16 + i] = (unsigned char)(__float_as_uint(L1[i]) & 127u); }
	v_max_f32_e32 v10, v10, v23
	s_waitcnt lgkmcnt(9)
	v_max_f32_e32 v17, v18, v24
	s_waitcnt lgkmcnt(7)
	v_max_f32_e32 v6, v6, v25
	s_waitcnt lgkmcnt(5)
	v_max_f32_e32 v8, v8, v26
	s_waitcnt lgkmcnt(3)
	v_max_f32_e32 v14, v14, v27
	s_waitcnt lgkmcnt(1)
	v_max_f32_e32 v16, v16, v28
	s_waitcnt lgkmcnt(0)
	v_max_f32_e32 v5, v5, v29
	v_max_f32_e32 v12, v12, v30
	v_max_f32_e32 v7, v7, v31
	v_max_f32_e32 v11, v11, v32
	v_max_f32_e32 v2, v2, v33
	v_max_f32_e32 v18, v3, v8
	v_min_f32_e32 v3, v3, v8
	v_max_f32_e32 v8, v4, v14
	v_min_f32_e32 v4, v4, v14
	v_max_f32_e32 v14, v9, v16
	v_min_f32_e32 v9, v9, v16
	v_max_f32_e32 v16, v13, v5
	v_min_f32_e32 v5, v13, v5
	v_max_f32_e32 v13, v15, v12
	v_min_f32_e32 v12, v15, v12
	v_max_f32_e32 v15, v10, v7
	v_min_f32_e32 v7, v10, v7
	v_max_f32_e32 v10, v17, v11
	v_min_f32_e32 v11, v17, v11
	v_max_f32_e32 v17, v6, v2
	v_min_f32_e32 v2, v6, v2
	v_max_f32_e32 v6, v18, v13
	v_min_f32_e32 v13, v18, v13
	v_max_f32_e32 v18, v8, v15
	v_min_f32_e32 v8, v8, v15
	v_max_f32_e32 v15, v14, v10
	v_min_f32_e32 v10, v14, v10
	v_max_f32_e32 v14, v16, v17
	v_min_f32_e32 v16, v16, v17
	v_max_f32_e32 v17, v3, v12
	v_min_f32_e32 v3, v3, v12
	v_max_f32_e32 v12, v4, v7
	v_min_f32_e32 v4, v4, v7
	v_max_f32_e32 v7, v9, v11
	v_min_f32_e32 v9, v9, v11
	v_max_f32_e32 v11, v5, v2
	v_min_f32_e32 v2, v5, v2
	v_max_f32_e32 v5, v6, v15
	v_min_f32_e32 v6, v6, v15
	v_max_f32_e32 v15, v18, v14
	v_min_f32_e32 v14, v18, v14
	v_max_f32_e32 v18, v13, v10
	v_min_f32_e32 v10, v13, v10
	v_max_f32_e32 v13, v8, v16
	v_min_f32_e32 v8, v8, v16
	v_max_f32_e32 v16, v17, v7
	v_min_f32_e32 v7, v17, v7
	v_max_f32_e32 v17, v12, v11
	v_min_f32_e32 v11, v12, v11
	v_max_f32_e32 v12, v3, v9
	v_min_f32_e32 v3, v3, v9
	v_max_f32_e32 v9, v4, v2
	v_min_f32_e32 v2, v4, v2
	v_max_f32_e32 v4, v5, v15
	v_min_f32_e32 v5, v5, v15
	v_max_f32_e32 v15, v6, v14
	v_min_f32_e32 v6, v6, v14
	v_max_f32_e32 v14, v18, v13
	v_min_f32_e32 v13, v18, v13
	v_max_f32_e32 v18, v10, v8
	v_min_f32_e32 v8, v10, v8
	v_max_f32_e32 v10, v16, v17
	v_min_f32_e32 v16, v16, v17
	v_max_f32_e32 v17, v7, v11
	v_min_f32_e32 v7, v7, v11
	v_max_f32_e32 v11, v12, v9
	v_min_f32_e32 v9, v12, v9
	v_max_f32_e32 v12, v3, v2
	v_min_f32_e32 v2, v3, v2
	ds_bpermute_b32 v3, v99, v2
	ds_bpermute_b32 v19, v99, v12
	ds_bpermute_b32 v20, v99, v9
	ds_bpermute_b32 v21, v99, v11
	ds_bpermute_b32 v22, v99, v7
	ds_bpermute_b32 v23, v99, v17
	s_waitcnt lgkmcnt(5)
	ds_bpermute_b32 v24, v99, v16
	ds_bpermute_b32 v33, v99, v4
	v_max_f32_e32 v3, v4, v3
	s_waitcnt lgkmcnt(6)
	ds_bpermute_b32 v25, v99, v10
	ds_bpermute_b32 v32, v99, v5
	v_max_f32_e32 v4, v5, v19
	s_waitcnt lgkmcnt(7)
	ds_bpermute_b32 v26, v99, v8
	ds_bpermute_b32 v31, v99, v15
	v_max_f32_e32 v5, v15, v20
	s_waitcnt lgkmcnt(8)
	ds_bpermute_b32 v27, v99, v18
	ds_bpermute_b32 v30, v99, v6
	v_max_f32_e32 v6, v6, v21
	s_waitcnt lgkmcnt(9)
	ds_bpermute_b32 v28, v99, v13
	ds_bpermute_b32 v29, v99, v14
	v_max_f32_e32 v14, v14, v22
	s_waitcnt lgkmcnt(10)
	v_max_f32_e32 v13, v13, v23
	s_waitcnt lgkmcnt(9)
	v_max_f32_e32 v15, v18, v24
	s_waitcnt lgkmcnt(7)
	v_max_f32_e32 v8, v8, v25
	s_waitcnt lgkmcnt(5)
	v_max_f32_e32 v10, v10, v26
	s_waitcnt lgkmcnt(3)
	v_max_f32_e32 v16, v16, v27
	s_waitcnt lgkmcnt(1)
	v_max_f32_e32 v17, v17, v28
	s_waitcnt lgkmcnt(0)
	v_max_f32_e32 v7, v7, v29
	v_max_f32_e32 v11, v11, v30
	v_max_f32_e32 v9, v9, v31
	v_max_f32_e32 v12, v12, v32
	v_max_f32_e32 v2, v2, v33
	v_max_f32_e32 v18, v3, v10
	v_min_f32_e32 v3, v3, v10
	v_max_f32_e32 v10, v4, v16
	v_min_f32_e32 v4, v4, v16
	v_max_f32_e32 v16, v5, v17
	v_min_f32_e32 v5, v5, v17
	v_max_f32_e32 v17, v6, v7
	v_min_f32_e32 v6, v6, v7
	v_max_f32_e32 v7, v14, v11
	v_min_f32_e32 v11, v14, v11
	v_max_f32_e32 v14, v13, v9
	v_min_f32_e32 v9, v13, v9
	v_max_f32_e32 v13, v15, v12
	v_min_f32_e32 v12, v15, v12
	v_max_f32_e32 v15, v8, v2
	v_min_f32_e32 v2, v8, v2
	v_max_f32_e32 v8, v18, v7
	v_min_f32_e32 v7, v18, v7
	v_max_f32_e32 v18, v10, v14
	v_min_f32_e32 v10, v10, v14
	v_max_f32_e32 v14, v16, v13
	v_min_f32_e32 v13, v16, v13
	v_max_f32_e32 v16, v17, v15
	v_min_f32_e32 v15, v17, v15
	v_max_f32_e32 v17, v3, v11
	v_min_f32_e32 v3, v3, v11
	v_max_f32_e32 v11, v4, v9
	v_min_f32_e32 v4, v4, v9
	v_max_f32_e32 v9, v5, v12
	v_min_f32_e32 v5, v5, v12
	v_max_f32_e32 v12, v6, v2
	v_min_f32_e32 v2, v6, v2
	v_max_f32_e32 v6, v8, v14
	v_min_f32_e32 v8, v8, v14
	v_max_f32_e32 v14, v18, v16
	v_min_f32_e32 v16, v18, v16
	v_max_f32_e32 v18, v7, v13
	v_max_f32_e32 v19, v10, v15
	s_movk_i32 s8, 0x7f
	v_min_f32_e32 v13, v7, v13
	v_min_f32_e32 v10, v10, v15
	v_max_f32_e32 v15, v17, v9
	v_min_f32_e32 v21, v17, v9
	v_max_f32_e32 v17, v11, v12
	v_min_f32_e32 v22, v11, v12
	v_max_f32_e32 v23, v3, v5
	v_min_f32_e32 v3, v3, v5
	v_max_f32_e32 v5, v4, v2
	v_min_f32_e32 v24, v4, v2
	v_max_f32_e32 v9, v18, v19
	v_min_f32_e32 v12, v18, v19
	v_and_b32_sdwa v18, v63, s8 dst_sel:BYTE_1 dst_unused:UNUSED_PAD src0_sel:DWORD src1_sel:DWORD
	v_max_f32_e32 v2, v6, v14
	v_min_f32_e32 v4, v6, v14
	v_max_f32_e32 v11, v13, v10
	v_min_f32_e32 v10, v13, v10
	v_max_f32_e32 v14, v23, v5
	v_min_f32_e32 v13, v23, v5
	v_max_f32_e32 v6, v3, v24
	v_min_f32_e32 v5, v3, v24
	v_and_b32_sdwa v3, v75, s8 dst_sel:BYTE_1 dst_unused:UNUSED_PAD src0_sel:DWORD src1_sel:DWORD
	v_bitop3_b16 v18, v71, v18, s8 bitop3:0xec
	v_bitop3_b16 v3, v79, v3, s8 bitop3:0xec
	v_lshlrev_b32_e32 v18, 16, v18
	v_or_b32_sdwa v23, v3, v18 dst_sel:DWORD dst_unused:UNUSED_PAD src0_sel:WORD_0 src1_sel:DWORD
	v_and_b32_sdwa v18, v83, s8 dst_sel:BYTE_1 dst_unused:UNUSED_PAD src0_sel:DWORD src1_sel:DWORD
	v_and_b32_sdwa v3, v91, s8 dst_sel:BYTE_1 dst_unused:UNUSED_PAD src0_sel:DWORD src1_sel:DWORD
; DEV void ce(float& a, float& b) { float hi = fmaxf(a, b), lo = fminf(a, b); a = hi; b = lo; }
; DEV void phase_peer_score(const Params& p, int layer, int M, char* smem) {
;     ...
;     for (int i = 0; i < 16; i++)
; #pragma unroll
;       for (int j = 0; j < 16; j++)
;         if ((i + 1) * (j + 1) <= 16) {
;           float v = L0[i] + L1[j];
;           v = __uint_as_float((__float_as_uint(v) & ~255u) | (unsigned)(i * 16 + j));
; #pragma unroll
;           for (int t = 0; t < 16; t++)
;             if (t >= (i + 1) * (j + 1) - 1) ce(R[t], v);
;         }
;     unsigned char* tab = (unsigned char*)smem + 73728 + (w * 16 + l15) * 32;
; #pragma unroll
;     for (int i = 0; i < 16; i++) { tab[i] = (unsigned char)(__float_as_uint(L0[i]) & 127u); tab[16 + i] = (unsigned char)(__float_as_uint(L1[i]) & 127u); }
	v_bitop3_b16 v18, v87, v18, s8 bitop3:0xec
	v_bitop3_b16 v3, v100, v3, s8 bitop3:0xec
	v_lshlrev_b32_e32 v18, 16, v18
	v_max_f32_e32 v7, v8, v16
	v_min_f32_e32 v8, v8, v16
	v_max_f32_e32 v20, v15, v17
	v_min_f32_e32 v17, v15, v17
	v_max_f32_e32 v16, v21, v22
	v_min_f32_e32 v15, v21, v22
	v_or_b32_sdwa v22, v3, v18 dst_sel:DWORD dst_unused:UNUSED_PAD src0_sel:WORD_0 src1_sel:DWORD
	v_and_b32_sdwa v18, v10, s8 dst_sel:BYTE_1 dst_unused:UNUSED_PAD src0_sel:DWORD src1_sel:DWORD
	v_and_b32_sdwa v3, v12, s8 dst_sel:BYTE_1 dst_unused:UNUSED_PAD src0_sel:DWORD src1_sel:DWORD
	v_bitop3_b16 v18, v11, v18, s8 bitop3:0xec
	v_bitop3_b16 v3, v9, v3, s8 bitop3:0xec
	v_lshlrev_b32_e32 v18, 16, v18
	v_or_b32_sdwa v27, v3, v18 dst_sel:DWORD dst_unused:UNUSED_PAD src0_sel:WORD_0 src1_sel:DWORD
	v_and_b32_sdwa v18, v8, s8 dst_sel:BYTE_1 dst_unused:UNUSED_PAD src0_sel:DWORD src1_sel:DWORD
	v_and_b32_sdwa v3, v4, s8 dst_sel:BYTE_1 dst_unused:UNUSED_PAD src0_sel:DWORD src1_sel:DWORD
	v_bitop3_b16 v18, v7, v18, s8 bitop3:0xec
	v_bitop3_b16 v3, v2, v3, s8 bitop3:0xec
	v_lshlrev_b32_e32 v18, 16, v18
	v_or_b32_sdwa v26, v3, v18 dst_sel:DWORD dst_unused:UNUSED_PAD src0_sel:WORD_0 src1_sel:DWORD
	v_and_b32_sdwa v18, v0, s8 dst_sel:BYTE_1 dst_unused:UNUSED_PAD src0_sel:DWORD src1_sel:DWORD
	v_and_b32_sdwa v3, v39, s8 dst_sel:BYTE_1 dst_unused:UNUSED_PAD src0_sel:DWORD src1_sel:DWORD
	v_bitop3_b16 v18, v43, v18, s8 bitop3:0xec
	v_bitop3_b16 v3, v51, v3, s8 bitop3:0xec
	v_lshlrev_b32_e32 v18, 16, v18
	v_or_b32_sdwa v25, v3, v18 dst_sel:DWORD dst_unused:UNUSED_PAD src0_sel:WORD_0 src1_sel:DWORD
	v_and_b32_sdwa v18, v47, s8 dst_sel:BYTE_1 dst_unused:UNUSED_PAD src0_sel:DWORD src1_sel:DWORD
	v_and_b32_sdwa v3, v59, s8 dst_sel:BYTE_1 dst_unused:UNUSED_PAD src0_sel:DWORD src1_sel:DWORD
	v_bitop3_b16 v18, v55, v18, s8 bitop3:0xec
	v_bitop3_b16 v3, v67, v3, s8 bitop3:0xec
	v_lshlrev_b32_e32 v18, 16, v18
	v_or_b32_sdwa v24, v3, v18 dst_sel:DWORD dst_unused:UNUSED_PAD src0_sel:WORD_0 src1_sel:DWORD
	v_and_b32_sdwa v18, v5, s8 dst_sel:BYTE_1 dst_unused:UNUSED_PAD src0_sel:DWORD src1_sel:DWORD
	v_and_b32_sdwa v3, v13, s8 dst_sel:BYTE_1 dst_unused:UNUSED_PAD src0_sel:DWORD src1_sel:DWORD
	v_bitop3_b16 v18, v6, v18, s8 bitop3:0xec
	v_bitop3_b16 v3, v14, v3, s8 bitop3:0xec
	v_lshlrev_b32_e32 v18, 16, v18
	v_or_b32_sdwa v29, v3, v18 dst_sel:DWORD dst_unused:UNUSED_PAD src0_sel:WORD_0 src1_sel:DWORD
	v_and_b32_sdwa v18, v15, s8 dst_sel:BYTE_1 dst_unused:UNUSED_PAD src0_sel:DWORD src1_sel:DWORD
	v_and_b32_sdwa v3, v17, s8 dst_sel:BYTE_1 dst_unused:UNUSED_PAD src0_sel:DWORD src1_sel:DWORD
	v_bitop3_b16 v18, v16, v18, s8 bitop3:0xec
	v_bitop3_b16 v3, v20, v3, s8 bitop3:0xec
	v_lshlrev_b32_e32 v18, 16, v18
	v_or_b32_sdwa v28, v3, v18 dst_sel:DWORD dst_unused:UNUSED_PAD src0_sel:WORD_0 src1_sel:DWORD
	ds_write_b128 v138, v[22:25]
	ds_write_b128 v138, v[26:29] offset:16
	s_and_saveexec_b64 s[8:9], s[38:39]
	s_cbranch_execz .LBB0_627
	s_lshl_b32 s18, s16, 3
	v_add_f32_e32 v3, v100, v2
	s_andn2_b32 s18, s18, 63
	v_and_b32_e32 v3, 0xffffff00, v3
	v_add_u32_e32 v18, s18, v117
	v_add_f32_e32 v22, v100, v4
	s_movk_i32 s18, 0xff00
	v_min_f32_e32 v21, 0xff61b1e6, v3
	v_and_or_b32 v22, v22, s18, 1
	v_max_f32_e32 v21, 0xff61b1e6, v21
	v_add_f32_e32 v24, v100, v7
	v_min_f32_e32 v23, v21, v22
	v_and_or_b32 v24, v24, s18, 2
	v_max_f32_e32 v23, v21, v23
	v_add_f32_e32 v26, v100, v8
	v_min_f32_e32 v25, v23, v24
	v_and_or_b32 v26, v26, s18, 3
	v_max_f32_e32 v25, v23, v25
	v_add_f32_e32 v28, v100, v9
	v_min_f32_e32 v27, v25, v26
	v_and_or_b32 v28, v28, s18, 4
	v_max_f32_e32 v27, v25, v27
	v_add_f32_e32 v30, v100, v12
	v_min_f32_e32 v29, v27, v28
	v_and_or_b32 v30, v30, s18, 5
	v_max_f32_e32 v29, v27, v29
	v_add_f32_e32 v32, v100, v11
	v_min_f32_e32 v31, v29, v30
	v_and_or_b32 v32, v32, s18, 6
	v_max_f32_e32 v31, v29, v31
	v_add_f32_e32 v95, v100, v10
	v_min_f32_e32 v33, v31, v32
	v_and_or_b32 v95, v95, s18, 7
	v_max_f32_e32 v33, v31, v33
	v_add_f32_e32 v20, v100, v20
	v_min_f32_e32 v99, v33, v95
	v_and_or_b32 v20, v20, s18, 8
	v_max_f32_e32 v99, v33, v99
	v_add_f32_e32 v17, v100, v17
	v_min_f32_e32 v101, v99, v20
	v_and_or_b32 v17, v17, s18, 9
	v_max_f32_e32 v101, v99, v101
	v_add_f32_e32 v16, v100, v16
	v_min_f32_e32 v102, v101, v17
	v_and_or_b32 v16, v16, s18, 10
	v_max_f32_e32 v102, v101, v102
	v_add_f32_e32 v15, v100, v15
	v_min_f32_e32 v103, v102, v16
	v_and_or_b32 v15, v15, s18, 11
	v_max_f32_e32 v103, v102, v103
	v_add_f32_e32 v14, v100, v14
	v_min_f32_e32 v104, v103, v15
	v_and_or_b32 v14, v14, s18, 12
	v_max_f32_e32 v104, v103, v104
	v_add_f32_e32 v13, v100, v13
	v_min_f32_e32 v105, v104, v14
	v_and_or_b32 v13, v13, s18, 13
	v_max_f32_e32 v105, v104, v105
	v_add_f32_e32 v6, v100, v6
	v_min_f32_e32 v106, v105, v13
	v_and_or_b32 v6, v6, s18, 14
	v_max_f32_e32 v106, v105, v106
	v_add_f32_e32 v5, v100, v5
	v_min_f32_e32 v107, v106, v6
	v_and_or_b32 v5, v5, s18, 15
	v_max3_f32 v100, v106, v107, v5
	v_max_f32_e32 v106, v106, v6
	v_add_f32_e32 v6, v91, v2
	v_and_or_b32 v6, v6, s18, 16
	v_max_f32_e32 v5, v21, v22
	v_max_f32_e32 v23, v23, v24
	v_min_f32_e32 v21, v5, v6
	v_max_f32_e32 v25, v25, v26
	v_min_f32_e32 v22, v23, v21
	v_min_f32_e32 v24, v25, v22
	v_max_f32_e32 v22, v25, v22
	v_add_f32_e32 v25, v91, v4
	v_and_or_b32 v25, v25, s18, 17
	v_max_f32_e32 v27, v27, v28
	v_max_f32_e32 v29, v29, v30
	v_min_f32_e32 v26, v27, v24
	v_max_f32_e32 v24, v27, v24
	v_min_f32_e32 v27, v22, v25
	v_max_f32_e32 v31, v31, v32
	v_min_f32_e32 v28, v29, v26
	v_max_f32_e32 v26, v29, v26
	v_min_f32_e32 v29, v24, v27
	v_min_f32_e32 v30, v31, v28
	v_max_f32_e32 v28, v31, v28
	v_min_f32_e32 v31, v26, v29
	v_max_f32_e32 v26, v26, v29
; DEV void ce(float& a, float& b) { float hi = fmaxf(a, b), lo = fminf(a, b); a = hi; b = lo; }
; DEV void phase_peer_score(const Params& p, int layer, int M, char* smem) {
;     ...
;     for (int i = 0; i < 16; i++)
; #pragma unroll
;       for (int j = 0; j < 16; j++)
;         if ((i + 1) * (j + 1) <= 16) {
;           float v = L0[i] + L1[j];
;           v = __uint_as_float((__float_as_uint(v) & ~255u) | (unsigned)(i * 16 + j));
; #pragma unroll
;           for (int t = 0; t < 16; t++)
;             if (t >= (i + 1) * (j + 1) - 1) ce(R[t], v);
;         }
	v_add_f32_e32 v29, v91, v7
	v_max_f32_e32 v33, v33, v95
	v_and_or_b32 v29, v29, s18, 18
	v_max_f32_e32 v20, v99, v20
	v_min_f32_e32 v32, v33, v30
	v_min_f32_e32 v95, v20, v32
	v_max_f32_e32 v20, v20, v32
	v_max_f32_e32 v30, v33, v30
	v_min_f32_e32 v32, v28, v31
	v_max_f32_e32 v28, v28, v31
	v_min_f32_e32 v31, v26, v29
	v_max_f32_e32 v17, v101, v17
	v_min_f32_e32 v33, v30, v32
	v_max_f32_e32 v30, v30, v32
	v_min_f32_e32 v32, v28, v31
	v_min_f32_e32 v99, v17, v95
	v_max_f32_e32 v17, v17, v95
	v_min_f32_e32 v95, v20, v33
	v_max_f32_e32 v20, v20, v33
	v_min_f32_e32 v33, v30, v32
	v_max_f32_e32 v30, v30, v32
	v_add_f32_e32 v32, v91, v8
	v_and_or_b32 v32, v32, s18, 19
	v_max_f32_e32 v16, v102, v16
	v_max_f32_e32 v15, v103, v15
	v_min_f32_e32 v101, v16, v99
	v_max_f32_e32 v16, v16, v99
	v_min_f32_e32 v99, v17, v95
	v_max_f32_e32 v17, v17, v95
	v_min_f32_e32 v95, v20, v33
	v_max_f32_e32 v20, v20, v33
	v_min_f32_e32 v33, v30, v32
	v_max_f32_e32 v14, v104, v14
	v_min_f32_e32 v102, v15, v101
	v_max_f32_e32 v15, v15, v101
	v_min_f32_e32 v101, v16, v99
	v_max_f32_e32 v16, v16, v99
	v_min_f32_e32 v99, v17, v95
	v_max_f32_e32 v17, v17, v95
	v_min_f32_e32 v95, v20, v33
	v_min_f32_e32 v103, v14, v102
	v_max_f32_e32 v14, v14, v102
	v_min_f32_e32 v102, v15, v101
	v_max_f32_e32 v15, v15, v101
	v_min_f32_e32 v101, v16, v99
	v_max_f32_e32 v16, v16, v99
	v_min_f32_e32 v99, v17, v95
	v_max_f32_e32 v17, v17, v95
	v_add_f32_e32 v95, v91, v9
	v_max_f32_e32 v13, v105, v13
	v_and_or_b32 v95, v95, s18, 20
	v_min_f32_e32 v104, v13, v103
	v_max_f32_e32 v13, v13, v103
	v_min_f32_e32 v103, v14, v102
	v_min_f32_e32 v105, v106, v104
	v_max_f32_e32 v104, v106, v104
	v_min_f32_e32 v106, v13, v103
	v_max_f32_e32 v14, v14, v102
	v_min_f32_e32 v102, v15, v101
	v_max_f32_e32 v15, v15, v101
	v_min_f32_e32 v101, v16, v99
	v_max_f32_e32 v16, v16, v99
	v_min_f32_e32 v99, v17, v95
	v_add_f32_e32 v12, v91, v12
	v_min_f32_e32 v107, v104, v106
	v_max_f32_e32 v13, v13, v103
	v_min_f32_e32 v103, v14, v102
	v_max_f32_e32 v14, v14, v102
	v_min_f32_e32 v102, v15, v101
	v_max_f32_e32 v15, v15, v101
	v_min_f32_e32 v101, v16, v99
	v_and_or_b32 v12, v12, s18, 21
	v_max_f32_e32 v21, v23, v21
	v_add_f32_e32 v23, v87, v2
	v_max3_f32 v100, v100, v105, v107
	v_max_f32_e32 v104, v104, v106
	v_min_f32_e32 v105, v13, v103
	v_max_f32_e32 v13, v13, v103
	v_min_f32_e32 v103, v14, v102
	v_max_f32_e32 v14, v14, v102
	v_min_f32_e32 v102, v15, v101
	v_max_f32_e32 v15, v15, v101
	v_and_or_b32 v23, v23, s18, 32
	v_min_f32_e32 v106, v104, v105
	v_max_f32_e32 v104, v104, v105
	v_min_f32_e32 v105, v13, v103
	v_max_f32_e32 v13, v13, v103
	v_min_f32_e32 v103, v14, v102
	v_max_f32_e32 v14, v14, v102
	v_min_f32_e32 v101, v15, v12
	v_add_f32_e32 v11, v91, v11
	v_min_f32_e32 v107, v104, v105
	v_max_f32_e32 v104, v104, v105
	v_min_f32_e32 v105, v13, v103
	v_max_f32_e32 v13, v13, v103
	v_min_f32_e32 v102, v14, v101
	v_and_or_b32 v11, v11, s18, 22
	v_max_f32_e32 v22, v22, v25
	v_min_f32_e32 v25, v21, v23
	v_min_f32_e32 v103, v13, v102
	v_max_f32_e32 v13, v13, v102
	v_max_f32_e32 v24, v24, v27
	v_min_f32_e32 v27, v22, v25
	v_min_f32_e32 v102, v13, v11
	v_max_f32_e32 v11, v13, v11
	v_max_f32_e32 v13, v14, v101
	v_max_f32_e32 v14, v16, v99
	v_max_f32_e32 v16, v20, v33
	v_max_f32_e32 v20, v28, v31
	v_max_f32_e32 v26, v26, v29
	v_min_f32_e32 v28, v24, v27
	v_min_f32_e32 v29, v26, v28
	v_max_f32_e32 v26, v26, v28
	v_add_f32_e32 v28, v87, v4
	v_and_or_b32 v28, v28, s18, 33
	v_max_f32_e32 v12, v15, v12
	v_max_f32_e32 v15, v17, v95
	v_max_f32_e32 v17, v30, v32
	v_min_f32_e32 v30, v20, v29
	v_max_f32_e32 v20, v20, v29
	v_min_f32_e32 v29, v26, v28
	v_min_f32_e32 v31, v17, v30
	v_max_f32_e32 v17, v17, v30
	v_min_f32_e32 v30, v20, v29
	v_min_f32_e32 v32, v16, v31
	v_max_f32_e32 v16, v16, v31
	v_min_f32_e32 v31, v17, v30
	v_min_f32_e32 v33, v15, v32
	v_max_f32_e32 v15, v15, v32
	v_min_f32_e32 v32, v16, v31
	v_max_f32_e32 v16, v16, v31
	v_add_f32_e32 v31, v87, v7
	v_and_or_b32 v31, v31, s18, 34
	v_max3_f32 v100, v100, v106, v107
	v_min_f32_e32 v106, v104, v105
	v_max_f32_e32 v104, v104, v105
	v_min_f32_e32 v105, v104, v103
	v_max_f32_e32 v103, v104, v103
	v_add_f32_e32 v10, v91, v10
	v_min_f32_e32 v95, v14, v33
	v_max_f32_e32 v14, v14, v33
	v_min_f32_e32 v33, v15, v32
	v_max_f32_e32 v15, v15, v32
	v_min_f32_e32 v32, v16, v31
	v_max_f32_e32 v22, v22, v25
	v_add_f32_e32 v25, v83, v2
	v_max3_f32 v100, v100, v106, v105
	v_min_f32_e32 v104, v103, v102
	v_and_or_b32 v10, v10, s18, 23
	v_min_f32_e32 v99, v12, v95
	v_max_f32_e32 v12, v12, v95
	v_min_f32_e32 v95, v14, v33
	v_max_f32_e32 v14, v14, v33
	v_min_f32_e32 v33, v15, v32
	v_and_or_b32 v25, v25, s18, 48
	v_max3_f32 v10, v100, v104, v10
	v_min_f32_e32 v100, v13, v99
	v_max_f32_e32 v13, v13, v99
	v_min_f32_e32 v99, v12, v95
	v_max_f32_e32 v12, v12, v95
	v_min_f32_e32 v95, v14, v33
	v_min_f32_e32 v101, v11, v100
	v_max_f32_e32 v11, v11, v100
	v_min_f32_e32 v100, v13, v99
	v_max_f32_e32 v13, v13, v99
	v_min_f32_e32 v99, v12, v95
	v_max_f32_e32 v12, v12, v95
	v_add_f32_e32 v95, v87, v8
	v_max_f32_e32 v24, v24, v27
	v_min_f32_e32 v27, v22, v25
	v_and_or_b32 v95, v95, s18, 35
	v_max_f32_e32 v26, v26, v28
	v_min_f32_e32 v28, v24, v27
	v_max_f32_e32 v91, v103, v102
	v_max_f32_e32 v20, v20, v29
	v_min_f32_e32 v29, v26, v28
	v_min_f32_e32 v102, v91, v101
	v_max_f32_e32 v91, v91, v101
	v_min_f32_e32 v101, v11, v100
	v_max_f32_e32 v11, v11, v100
	v_min_f32_e32 v100, v13, v99
	v_max_f32_e32 v13, v13, v99
	v_min_f32_e32 v99, v12, v95
	v_max_f32_e32 v17, v17, v30
	v_min_f32_e32 v30, v20, v29
	v_min_f32_e32 v103, v91, v101
	v_max_f32_e32 v91, v91, v101
	v_min_f32_e32 v101, v11, v100
	v_max_f32_e32 v11, v11, v100
; DEV void ce(float& a, float& b) { float hi = fmaxf(a, b), lo = fminf(a, b); a = hi; b = lo; }
; DEV void phase_peer_score(const Params& p, int layer, int M, char* smem) {
;     ...
;     for (int i = 0; i < 16; i++)
; #pragma unroll
;       for (int j = 0; j < 16; j++)
;         if ((i + 1) * (j + 1) <= 16) {
;           float v = L0[i] + L1[j];
;           v = __uint_as_float((__float_as_uint(v) & ~255u) | (unsigned)(i * 16 + j));
; #pragma unroll
;           for (int t = 0; t < 16; t++)
;             if (t >= (i + 1) * (j + 1) - 1) ce(R[t], v);
;         }
	v_min_f32_e32 v100, v13, v99
	v_add_f32_e32 v9, v87, v9
	v_max_f32_e32 v16, v16, v31
	v_min_f32_e32 v31, v17, v30
	v_max3_f32 v10, v10, v102, v103
	v_min_f32_e32 v102, v91, v101
	v_max_f32_e32 v91, v91, v101
	v_min_f32_e32 v101, v11, v100
	v_and_or_b32 v9, v9, s18, 36
	v_max_f32_e32 v15, v15, v32
	v_min_f32_e32 v32, v16, v31
	v_min_f32_e32 v103, v91, v101
	v_max_f32_e32 v91, v91, v101
	v_max_f32_e32 v14, v14, v33
	v_min_f32_e32 v33, v15, v32
	v_max_f32_e32 v17, v17, v30
	v_add_f32_e32 v30, v83, v4
	v_min_f32_e32 v87, v91, v9
	v_max_f32_e32 v9, v91, v9
	v_max_f32_e32 v12, v12, v95
	v_min_f32_e32 v91, v14, v33
	v_and_or_b32 v30, v30, s18, 49
	v_max_f32_e32 v24, v24, v27
	v_add_f32_e32 v27, v79, v2
	v_max_f32_e32 v13, v13, v99
	v_min_f32_e32 v95, v12, v91
	v_and_or_b32 v27, v27, s18, 64
	v_max_f32_e32 v11, v11, v100
	v_min_f32_e32 v99, v13, v95
	v_max_f32_e32 v16, v16, v31
	v_min_f32_e32 v31, v17, v30
	v_min_f32_e32 v100, v11, v99
	v_max_f32_e32 v15, v15, v32
	v_min_f32_e32 v32, v16, v31
	v_max_f32_e32 v26, v26, v28
	v_min_f32_e32 v28, v24, v27
	v_max3_f32 v10, v10, v102, v103
	v_min_f32_e32 v101, v9, v100
	v_max_f32_e32 v14, v14, v33
	v_min_f32_e32 v33, v15, v32
	v_max_f32_e32 v20, v20, v29
	v_min_f32_e32 v29, v26, v28
	v_max3_f32 v10, v10, v87, v101
	v_max_f32_e32 v12, v12, v91
	v_min_f32_e32 v87, v14, v33
	v_max_f32_e32 v17, v17, v30
	v_min_f32_e32 v30, v20, v29
	v_min_f32_e32 v91, v12, v87
	v_max_f32_e32 v12, v12, v87
	v_add_f32_e32 v87, v83, v7
	v_max_f32_e32 v16, v16, v31
	v_min_f32_e32 v31, v17, v30
	v_and_or_b32 v87, v87, s18, 50
	v_max_f32_e32 v15, v15, v32
	v_min_f32_e32 v32, v16, v31
	v_max_f32_e32 v13, v13, v95
	v_max_f32_e32 v14, v14, v33
	v_min_f32_e32 v33, v15, v32
	v_max_f32_e32 v11, v11, v99
	v_min_f32_e32 v95, v13, v91
	v_max_f32_e32 v13, v13, v91
	v_min_f32_e32 v91, v12, v87
	v_add_f32_e32 v8, v83, v8
	v_max_f32_e32 v12, v12, v87
	v_min_f32_e32 v83, v14, v33
	v_max_f32_e32 v9, v9, v100
	v_min_f32_e32 v99, v11, v95
	v_max_f32_e32 v11, v11, v95
	v_min_f32_e32 v95, v13, v91
	v_max_f32_e32 v13, v13, v91
	v_min_f32_e32 v87, v12, v83
	v_min_f32_e32 v100, v9, v99
	v_max_f32_e32 v9, v9, v99
	v_min_f32_e32 v99, v11, v95
	v_max_f32_e32 v11, v11, v95
	v_min_f32_e32 v91, v13, v87
	v_min_f32_e32 v101, v9, v99
	v_max_f32_e32 v9, v9, v99
	v_min_f32_e32 v95, v11, v91
	v_max3_f32 v10, v10, v100, v101
	v_and_or_b32 v8, v8, s18, 51
	v_min_f32_e32 v99, v9, v95
	v_max3_f32 v8, v10, v8, v99
	v_max_f32_e32 v10, v11, v91
	v_max_f32_e32 v11, v13, v87
	v_max_f32_e32 v13, v14, v33
	v_max_f32_e32 v14, v15, v32
	v_add_f32_e32 v15, v79, v4
	v_and_b32_e32 v15, 0xffffff00, v15
	v_or_b32_e32 v15, 0x41, v15
	v_min_f32_e32 v32, v14, v15
	v_max_f32_e32 v12, v12, v83
	v_min_f32_e32 v33, v13, v32
	v_min_f32_e32 v83, v12, v33
	v_add_f32_e32 v7, v79, v7
	v_min_f32_e32 v87, v11, v83
	v_and_b32_e32 v7, 0xffffff00, v7
	v_max_f32_e32 v9, v9, v95
	v_min_f32_e32 v91, v10, v87
	v_or_b32_e32 v7, 0x42, v7
	v_min_f32_e32 v95, v9, v91
	v_max_f32_e32 v9, v9, v91
	v_min_f32_e32 v79, v9, v7
	v_max_f32_e32 v7, v9, v7
	v_max_f32_e32 v9, v10, v87
	v_max_f32_e32 v10, v11, v83
	v_max_f32_e32 v11, v12, v33
	v_max_f32_e32 v12, v13, v32
	v_max_f32_e32 v13, v14, v15
	v_max_f32_e32 v14, v16, v31
	v_max_f32_e32 v16, v20, v29
	v_add_f32_e32 v20, v75, v2
	v_and_b32_e32 v20, 0xffffff00, v20
	v_or_b32_e32 v20, 0x50, v20
	v_max_f32_e32 v15, v17, v30
	v_max_f32_e32 v17, v26, v28
	v_min_f32_e32 v26, v17, v20
	v_min_f32_e32 v28, v16, v26
	v_max_f32_e32 v16, v16, v26
	v_add_f32_e32 v26, v71, v2
	v_and_b32_e32 v26, 0xffffff00, v26
	v_min_f32_e32 v29, v15, v28
	v_or_b32_e32 v26, 0x60, v26
	v_min_f32_e32 v30, v14, v29
	v_min_f32_e32 v31, v13, v30
	v_max_f32_e32 v15, v15, v28
	v_min_f32_e32 v28, v16, v26
	v_min_f32_e32 v32, v12, v31
	v_max_f32_e32 v14, v14, v29
	v_min_f32_e32 v29, v15, v28
	v_max_f32_e32 v15, v15, v28
	v_add_f32_e32 v28, v63, v2
	v_min_f32_e32 v33, v11, v32
	v_max_f32_e32 v11, v11, v32
	v_add_f32_e32 v32, v75, v4
	v_and_b32_e32 v28, 0xffffff00, v28
	v_and_b32_e32 v32, 0xffffff00, v32
	v_or_b32_e32 v28, 0x70, v28
	v_or_b32_e32 v32, 0x51, v32
	v_max_f32_e32 v13, v13, v30
	v_min_f32_e32 v30, v14, v29
	v_max_f32_e32 v12, v12, v31
	v_min_f32_e32 v31, v13, v30
	v_max_f32_e32 v14, v14, v29
	v_min_f32_e32 v29, v15, v28
	v_max3_f32 v8, v8, v95, v79
	v_min_f32_e32 v79, v10, v33
	v_max_f32_e32 v10, v10, v33
	v_min_f32_e32 v33, v11, v32
	v_max_f32_e32 v11, v11, v32
	v_min_f32_e32 v32, v12, v31
	v_add_f32_e32 v71, v71, v4
	v_max_f32_e32 v13, v13, v30
	v_min_f32_e32 v30, v14, v29
	v_min_f32_e32 v83, v9, v79
	v_max_f32_e32 v9, v9, v79
	v_min_f32_e32 v75, v10, v33
	v_max_f32_e32 v10, v10, v33
	v_min_f32_e32 v33, v11, v32
	v_and_b32_e32 v71, 0xffffff00, v71
	v_max_f32_e32 v12, v12, v31
	v_min_f32_e32 v31, v13, v30
	v_min_f32_e32 v87, v7, v83
	v_max_f32_e32 v7, v7, v83
	v_min_f32_e32 v79, v9, v75
	v_max_f32_e32 v9, v9, v75
	v_min_f32_e32 v75, v10, v33
	v_or_b32_e32 v71, 0x61, v71
	v_max_f32_e32 v11, v11, v32
	v_min_f32_e32 v32, v12, v31
	v_min_f32_e32 v83, v7, v79
	v_max_f32_e32 v7, v7, v79
	v_min_f32_e32 v79, v9, v75
	v_max_f32_e32 v9, v9, v75
	v_max_f32_e32 v10, v10, v33
	v_min_f32_e32 v33, v11, v32
	v_max3_f32 v8, v8, v87, v83
	v_min_f32_e32 v83, v7, v79
	v_max_f32_e32 v7, v7, v79
	v_min_f32_e32 v75, v9, v71
	v_max_f32_e32 v9, v9, v71
	v_min_f32_e32 v71, v10, v33
	v_add_f32_e32 v4, v63, v4
	v_min_f32_e32 v79, v7, v75
	v_max_f32_e32 v7, v7, v75
	v_min_f32_e32 v75, v9, v71
	v_and_b32_e32 v4, 0xffffff00, v4
	v_max3_f32 v8, v8, v83, v79
	v_min_f32_e32 v79, v7, v75
	v_or_b32_e32 v4, 0x71, v4
	v_max3_f32 v4, v8, v79, v4
	v_max_f32_e32 v8, v9, v71
	v_max_f32_e32 v9, v10, v33
	v_max_f32_e32 v10, v11, v32
; DEV void ce(float& a, float& b) { float hi = fmaxf(a, b), lo = fminf(a, b); a = hi; b = lo; }
; DEV void phase_peer_score(const Params& p, int layer, int M, char* smem) {
;     ...
;     for (int i = 0; i < 16; i++)
; #pragma unroll
;       for (int j = 0; j < 16; j++)
;         if ((i + 1) * (j + 1) <= 16) {
;           float v = L0[i] + L1[j];
;           v = __uint_as_float((__float_as_uint(v) & ~255u) | (unsigned)(i * 16 + j));
; #pragma unroll
;           for (int t = 0; t < 16; t++)
;             if (t >= (i + 1) * (j + 1) - 1) ce(R[t], v);
;         }
;     unsigned char* tab = (unsigned char*)smem + 73728 + (w * 16 + l15) * 32;
; #pragma unroll
;     for (int i = 0; i < 16; i++) { tab[i] = (unsigned char)(__float_as_uint(L0[i]) & 127u); tab[16 + i] = (unsigned char)(__float_as_uint(L1[i]) & 127u); }
;     float ev[16]; float sum = 0.f;
; #pragma unroll
;     for (int t = 0; t < 16; t++) { ev[t] = __expf(R[t] - R[0]); sum += ev[t]; }
;     const float inv = 1.f / sum;
;     int eid[16];
; #pragma unroll
;     for (int t = 0; t < 16; t++) {
;       unsigned code = __float_as_uint(R[t]) & 255u;
;       eid[t] = (int)tab[code >> 4] * 128 + (int)tab[16 + (code & 15u)];
	v_max_f32_e32 v11, v12, v31
	v_max_f32_e32 v12, v13, v30
	v_max_f32_e32 v13, v14, v29
	v_add_f32_e32 v14, v67, v2
	v_and_b32_e32 v14, 0xffffff00, v14
	v_or_b32_e32 v14, 0x80, v14
	v_min_f32_e32 v29, v13, v14
	v_min_f32_e32 v30, v12, v29
	v_max_f32_e32 v12, v12, v29
	v_add_f32_e32 v29, v59, v2
	v_and_b32_e32 v29, 0xffffff00, v29
	v_or_b32_e32 v29, 0x90, v29
	v_min_f32_e32 v31, v11, v30
	v_max_f32_e32 v11, v11, v30
	v_min_f32_e32 v30, v12, v29
	v_min_f32_e32 v32, v10, v31
	v_max_f32_e32 v10, v10, v31
	v_min_f32_e32 v31, v11, v30
	v_max_f32_e32 v11, v11, v30
	v_add_f32_e32 v30, v55, v2
	v_and_b32_e32 v30, 0xffffff00, v30
	v_or_b32_e32 v30, 0xa0, v30
	v_min_f32_e32 v33, v9, v32
	v_max_f32_e32 v9, v9, v32
	v_min_f32_e32 v32, v10, v31
	v_max_f32_e32 v10, v10, v31
	v_min_f32_e32 v31, v11, v30
	v_min_f32_e32 v63, v8, v33
	v_max_f32_e32 v8, v8, v33
	v_min_f32_e32 v33, v9, v32
	v_max_f32_e32 v9, v9, v32
	v_min_f32_e32 v32, v10, v31
	v_max_f32_e32 v10, v10, v31
	v_add_f32_e32 v31, v47, v2
	v_and_b32_e32 v31, 0xffffff00, v31
	v_or_b32_e32 v31, 0xb0, v31
	v_min_f32_e32 v59, v8, v33
	v_max_f32_e32 v8, v8, v33
	v_min_f32_e32 v33, v9, v32
	v_max_f32_e32 v9, v9, v32
	v_min_f32_e32 v32, v10, v31
	v_min_f32_e32 v55, v8, v33
	v_max_f32_e32 v8, v8, v33
	v_min_f32_e32 v33, v9, v32
	v_max_f32_e32 v9, v9, v32
	v_add_f32_e32 v32, v51, v2
	v_max_f32_e32 v7, v7, v75
	v_and_b32_e32 v32, 0xffffff00, v32
	v_min_f32_e32 v67, v7, v63
	v_max_f32_e32 v7, v7, v63
	v_or_b32_e32 v32, 0xc0, v32
	v_min_f32_e32 v63, v7, v59
	v_max_f32_e32 v7, v7, v59
	v_min_f32_e32 v59, v7, v55
	v_max_f32_e32 v7, v7, v55
	v_min_f32_e32 v47, v8, v33
	v_max_f32_e32 v8, v8, v33
	v_min_f32_e32 v33, v9, v32
	v_min_f32_e32 v55, v7, v47
	v_max_f32_e32 v7, v7, v47
	v_min_f32_e32 v47, v8, v33
	v_max_f32_e32 v8, v8, v33
	v_add_f32_e32 v33, v39, v2
	v_and_b32_e32 v33, 0xffffff00, v33
	v_or_b32_e32 v33, 0xd0, v33
	v_min_f32_e32 v51, v7, v47
	v_max_f32_e32 v7, v7, v47
	v_min_f32_e32 v39, v8, v33
	v_min_f32_e32 v47, v7, v39
	v_max_f32_e32 v7, v7, v39
	v_add_f32_e32 v39, v43, v2
	v_and_b32_e32 v39, 0xffffff00, v39
	v_max3_f32 v4, v4, v67, v63
	v_or_b32_e32 v39, 0xe0, v39
	v_add_f32_e32 v0, v0, v2
	v_max3_f32 v4, v4, v59, v55
	v_and_b32_e32 v0, 0xffffff00, v0
	v_max3_f32 v4, v4, v51, v47
	v_min_f32_e32 v43, v7, v39
	v_or_b32_e32 v0, 0xf0, v0
	v_max3_f32 v2, v4, v43, v0
	v_max_f32_e32 v13, v13, v14
	v_max_f32_e32 v14, v5, v6
	v_max_f32_e32 v0, 0xff61b1e6, v3
	v_sub_f32_e32 v5, v14, v0
	v_max_f32_e32 v28, v15, v28
	v_max_f32_e32 v15, v21, v23
	v_mul_f32_e32 v5, 0x3fb8aa3b, v5
	v_exp_f32_e32 v101, v5
	v_sub_f32_e32 v5, v15, v0
	v_max_f32_e32 v29, v12, v29
	v_max_f32_e32 v12, v16, v26
	v_max_f32_e32 v16, v22, v25
	v_mul_f32_e32 v5, 0x3fb8aa3b, v5
	v_exp_f32_e32 v104, v5
	v_sub_f32_e32 v5, v16, v0
	v_max_f32_e32 v4, v7, v39
	v_max_f32_e32 v7, v8, v33
	v_max_f32_e32 v8, v9, v32
	v_max_f32_e32 v9, v10, v31
	v_max_f32_e32 v10, v24, v27
	v_mul_f32_e32 v5, 0x3fb8aa3b, v5
	v_exp_f32_e32 v105, v5
	v_sub_f32_e32 v5, v10, v0
	v_max_f32_e32 v30, v11, v30
	v_max_f32_e32 v11, v17, v20
	v_mul_f32_e32 v5, 0x3fb8aa3b, v5
	v_exp_f32_e32 v102, v5
	v_sub_f32_e32 v5, v11, v0
	v_mul_f32_e32 v5, 0x3fb8aa3b, v5
	v_exp_f32_e32 v103, v5
	v_sub_f32_e32 v5, v12, v0
	v_mul_f32_e32 v5, 0x3fb8aa3b, v5
	v_exp_f32_e32 v110, v5
	v_sub_f32_e32 v5, v28, v0
	v_sub_f32_e32 v3, v0, v0
	v_mul_f32_e32 v5, 0x3fb8aa3b, v5
	v_mul_f32_e32 v3, 0x3fb8aa3b, v3
	v_exp_f32_e32 v111, v5
	v_sub_f32_e32 v5, v13, v0
	v_exp_f32_e32 v100, v3
	v_mul_f32_e32 v5, 0x3fb8aa3b, v5
	v_exp_f32_e32 v112, v5
	v_sub_f32_e32 v5, v29, v0
	v_mul_f32_e32 v5, 0x3fb8aa3b, v5
	v_exp_f32_e32 v113, v5
	v_sub_f32_e32 v5, v30, v0
	v_add_f32_e32 v3, 0, v100
	v_mul_f32_e32 v5, 0x3fb8aa3b, v5
	v_add_f32_e32 v3, v3, v101
	v_exp_f32_e32 v114, v5
	v_sub_f32_e32 v5, v9, v0
	v_add_f32_e32 v3, v3, v104
	v_mul_f32_e32 v5, 0x3fb8aa3b, v5
	v_add_f32_e32 v3, v3, v105
	v_exp_f32_e32 v115, v5
	v_sub_f32_e32 v5, v8, v0
	v_add_f32_e32 v3, v3, v102
	v_mul_f32_e32 v5, 0x3fb8aa3b, v5
	v_add_f32_e32 v3, v3, v103
	v_exp_f32_e32 v106, v5
	v_sub_f32_e32 v5, v7, v0
	v_add_f32_e32 v3, v3, v110
	v_mul_f32_e32 v5, 0x3fb8aa3b, v5
	v_add_f32_e32 v3, v3, v111
	v_exp_f32_e32 v107, v5
	v_sub_f32_e32 v5, v4, v0
	v_add_f32_e32 v3, v3, v112
	v_mul_f32_e32 v5, 0x3fb8aa3b, v5
	v_add_f32_e32 v3, v3, v113
	v_exp_f32_e32 v108, v5
	v_sub_f32_e32 v5, v2, v0
	v_add_f32_e32 v3, v3, v114
	v_mul_f32_e32 v5, 0x3fb8aa3b, v5
	v_add_f32_e32 v3, v3, v115
	v_exp_f32_e32 v109, v5
	v_add_f32_e32 v3, v3, v106
	v_add_f32_e32 v3, v3, v107
	v_add_f32_e32 v3, v3, v108
	v_add_f32_e32 v3, v3, v109
	v_div_scale_f32 v5, s[18:19], v3, v3, 1.0
	v_rcp_f32_e32 v6, v5
	v_ashrrev_i32_e32 v19, 31, v18
	s_lshl_b32 s52, s17, 6
	s_mov_b32 s17, 0x10000
	v_fma_f32 v17, -v5, v6, 1.0
	v_fmac_f32_e32 v6, v17, v6
	v_div_scale_f32 v17, vcc, 1.0, v3, 1.0
	v_mul_f32_e32 v20, v17, v6
	v_fma_f32 v21, -v5, v20, v17
	v_fmac_f32_e32 v20, v21, v6
	v_fma_f32 v5, -v5, v20, v17
	v_div_fmas_f32 v5, v5, v6, v20
	v_div_fixup_f32 v116, v5, v3, 1.0
	v_bfe_u32 v3, v2, 4, 4
	v_and_b32_e32 v2, 15, v2
	v_and_b32_e32 v17, 15, v28
	v_add_u32_e32 v3, v138, v3
	v_add_u32_e32 v2, v138, v2
	v_add_u32_e32 v17, v138, v17
	ds_read_u8 v3, v3
	ds_read_u8 v17, v17 offset:16
	ds_read_u8 v2, v2 offset:16
	v_and_b32_e32 v6, 15, v8
	v_add_u32_e32 v6, v138, v6
	ds_read_u8 v6, v6 offset:16
	v_lshlrev_b64 v[120:121], 9, v[18:19]
	s_waitcnt lgkmcnt(1)
	v_lshl_add_u32 v5, v3, 7, v2
	v_bfe_u32 v2, v4, 4, 4
	v_and_b32_e32 v3, 15, v4
	v_add_u32_e32 v2, v138, v2
	v_add_u32_e32 v3, v138, v3
	ds_read_u8 v2, v2
	ds_read_u8 v3, v3 offset:16
	v_lshl_add_u64 v[18:19], s[2:3], 0, v[120:121]
	v_lshl_add_u64 v[118:119], v[18:19], 0, s[52:53]
	v_lshl_add_u64 v[120:121], s[0:1], 0, v[120:121]
	v_lshl_add_u64 v[120:121], v[120:121], 0, s[52:53]
	s_waitcnt lgkmcnt(0)
; DEV void phase_peer_score(const Params& p, int layer, int M, char* smem) {
;     ...
;     int eid[16];
; #pragma unroll
;     for (int t = 0; t < 16; t++) {
;       unsigned code = __float_as_uint(R[t]) & 255u;
;       eid[t] = (int)tab[code >> 4] * 128 + (int)tab[16 + (code & 15u)];
;     }
	v_lshl_add_u32 v4, v2, 7, v3
	v_bfe_u32 v2, v7, 4, 4
	v_and_b32_e32 v3, 15, v7
	v_add_u32_e32 v2, v138, v2
	v_add_u32_e32 v3, v138, v3
	ds_read_u8 v2, v2
	ds_read_u8 v3, v3 offset:16
	v_and_b32_e32 v7, 15, v9
	v_add_u32_e32 v7, v138, v7
	ds_read_u8 v7, v7 offset:16
	s_waitcnt lgkmcnt(1)
	v_lshl_add_u32 v3, v2, 7, v3
	v_bfe_u32 v2, v8, 4, 4
	v_add_u32_e32 v2, v138, v2
	ds_read_u8 v2, v2
	s_waitcnt lgkmcnt(0)
	v_lshl_add_u32 v2, v2, 7, v6
	v_bfe_u32 v6, v9, 4, 4
	v_add_u32_e32 v6, v138, v6
	ds_read_u8 v6, v6
	s_waitcnt lgkmcnt(0)
	v_lshl_add_u32 v9, v6, 7, v7
	v_bfe_u32 v6, v30, 4, 4
	v_and_b32_e32 v7, 15, v30
	v_add_u32_e32 v6, v138, v6
	v_add_u32_e32 v7, v138, v7
	ds_read_u8 v6, v6
	ds_read_u8 v7, v7 offset:16
	s_waitcnt lgkmcnt(0)
	v_lshl_add_u32 v8, v6, 7, v7
	v_bfe_u32 v6, v29, 4, 4
	v_and_b32_e32 v7, 15, v29
	v_add_u32_e32 v6, v138, v6
	v_add_u32_e32 v7, v138, v7
	ds_read_u8 v6, v6
	ds_read_u8 v7, v7 offset:16
	s_waitcnt lgkmcnt(0)
	v_lshl_add_u32 v7, v6, 7, v7
	v_bfe_u32 v6, v13, 4, 4
	v_and_b32_e32 v13, 15, v13
	v_add_u32_e32 v6, v138, v6
	v_add_u32_e32 v13, v138, v13
	ds_read_u8 v6, v6
	ds_read_u8 v13, v13 offset:16
	s_waitcnt lgkmcnt(0)
	v_lshl_add_u32 v6, v6, 7, v13
	v_bfe_u32 v13, v28, 4, 4
	v_add_u32_e32 v13, v138, v13
	ds_read_u8 v13, v13
	s_waitcnt lgkmcnt(0)
	v_lshl_add_u32 v13, v13, 7, v17
	v_bfe_u32 v17, v12, 4, 4
	v_and_b32_e32 v12, 15, v12
	v_add_u32_e32 v17, v138, v17
	v_add_u32_e32 v12, v138, v12
	ds_read_u8 v17, v17
	ds_read_u8 v12, v12 offset:16
	s_waitcnt lgkmcnt(0)
	v_lshl_add_u32 v12, v17, 7, v12
	v_bfe_u32 v17, v11, 4, 4
	v_and_b32_e32 v11, 15, v11
	v_add_u32_e32 v17, v138, v17
	v_add_u32_e32 v11, v138, v11
	ds_read_u8 v17, v17
	ds_read_u8 v11, v11 offset:16
	s_waitcnt lgkmcnt(0)
	v_lshl_add_u32 v11, v17, 7, v11
	v_bfe_u32 v17, v10, 4, 4
	v_and_b32_e32 v10, 15, v10
	v_add_u32_e32 v17, v138, v17
	v_add_u32_e32 v10, v138, v10
	ds_read_u8 v17, v17
	ds_read_u8 v10, v10 offset:16
	s_waitcnt lgkmcnt(0)
	v_lshl_add_u32 v10, v17, 7, v10
	v_bfe_u32 v17, v16, 4, 4
	v_and_b32_e32 v16, 15, v16
	v_add_u32_e32 v17, v138, v17
	v_add_u32_e32 v16, v138, v16
	ds_read_u8 v17, v17
	ds_read_u8 v16, v16 offset:16
	s_waitcnt lgkmcnt(0)
	v_lshl_add_u32 v17, v17, 7, v16
	v_bfe_u32 v16, v15, 4, 4
	v_and_b32_e32 v15, 15, v15
	v_add_u32_e32 v16, v138, v16
	v_add_u32_e32 v15, v138, v15
	ds_read_u8 v16, v16
	ds_read_u8 v15, v15 offset:16
	s_waitcnt lgkmcnt(0)
	v_lshl_add_u32 v16, v16, 7, v15
	v_bfe_u32 v15, v14, 4, 4
	v_and_b32_e32 v14, 15, v14
	v_add_u32_e32 v15, v138, v15
	v_add_u32_e32 v14, v138, v14
	ds_read_u8 v15, v15
	ds_read_u8 v14, v14 offset:16
	s_waitcnt lgkmcnt(0)
	v_lshl_add_u32 v15, v15, 7, v14
	v_bfe_u32 v14, v0, 4, 4
	v_and_b32_e32 v0, 15, v0
	v_add_u32_e32 v14, v138, v14
	v_add_u32_e32 v0, v138, v0
	ds_read_u8 v14, v14
	ds_read_u8 v0, v0 offset:16
	s_waitcnt lgkmcnt(0)
; DEV void phase_peer_score(const Params& p, int layer, int M, char* smem) {
;     ...
;     if (quad == 0) {
;       int* eo = EIDX + (size_t)m * 128 + h * 16;
;       float* go = GATE + (size_t)m * 128 + h * 16;
;       float* uo = go + (size_t)MT * 128;
;       float us[16], vs[16];
; #pragma unroll
;       for (int t = 0; t < 16; t++) { us[t] = USC[eid[t]]; vs[t] = USC[16384 + eid[t]]; }
; #pragma unroll
;       for (int t = 0; t < 16; t += 4) {
;         *(int4*)(eo + t) = make_int4(eid[t], eid[t + 1], eid[t + 2], eid[t + 3]);
;         *(float4*)(go + t) = make_float4(ev[t] * inv * vs[t], ev[t + 1] * inv * vs[t + 1], ev[t + 2] * inv * vs[t + 2], ev[t + 3] * inv * vs[t + 3]);
;         *(float4*)(uo + t) = make_float4(us[t], us[t + 1], us[t + 2], us[t + 3]);
;       }
;     }
	v_lshl_add_u32 v14, v14, 7, v0
	v_lshlrev_b32_e32 v0, 2, v14
	v_lshl_add_u64 v[20:21], s[6:7], 0, v[0:1]
	v_add_co_u32_e32 v20, vcc, s17, v20
	global_load_dword v18, v0, s[6:7]
	s_nop 0
	v_addc_co_u32_e32 v21, vcc, 0, v21, vcc
	global_load_dword v122, v[20:21], off
	v_lshlrev_b32_e32 v0, 2, v15
	v_lshl_add_u64 v[20:21], s[6:7], 0, v[0:1]
	v_add_co_u32_e32 v20, vcc, s17, v20
	global_load_dword v19, v0, s[6:7]
	s_nop 0
	v_addc_co_u32_e32 v21, vcc, 0, v21, vcc
	global_load_dword v123, v[20:21], off
	v_lshlrev_b32_e32 v0, 2, v16
	v_lshl_add_u64 v[22:23], s[6:7], 0, v[0:1]
	v_add_co_u32_e32 v22, vcc, s17, v22
	global_load_dword v20, v0, s[6:7]
	s_nop 0
	v_addc_co_u32_e32 v23, vcc, 0, v23, vcc
	global_load_dword v126, v[22:23], off
	v_lshlrev_b32_e32 v0, 2, v17
	v_lshl_add_u64 v[22:23], s[6:7], 0, v[0:1]
	v_add_co_u32_e32 v22, vcc, s17, v22
	global_load_dword v21, v0, s[6:7]
	s_nop 0
	v_addc_co_u32_e32 v23, vcc, 0, v23, vcc
	global_load_dword v127, v[22:23], off
	v_lshlrev_b32_e32 v0, 2, v10
	v_lshl_add_u64 v[24:25], s[6:7], 0, v[0:1]
	v_add_co_u32_e32 v24, vcc, s17, v24
	global_load_dword v22, v0, s[6:7]
	s_nop 0
	v_addc_co_u32_e32 v25, vcc, 0, v25, vcc
	global_load_dword v124, v[24:25], off
	v_lshlrev_b32_e32 v0, 2, v11
	v_lshl_add_u64 v[24:25], s[6:7], 0, v[0:1]
	v_add_co_u32_e32 v24, vcc, s17, v24
	global_load_dword v23, v0, s[6:7]
	s_nop 0
	v_addc_co_u32_e32 v25, vcc, 0, v25, vcc
	global_load_dword v125, v[24:25], off
	v_lshlrev_b32_e32 v0, 2, v12
	v_lshl_add_u64 v[26:27], s[6:7], 0, v[0:1]
	v_add_co_u32_e32 v26, vcc, s17, v26
	global_load_dword v24, v0, s[6:7]
	s_nop 0
	v_addc_co_u32_e32 v27, vcc, 0, v27, vcc
	global_load_dword v128, v[26:27], off
	v_lshlrev_b32_e32 v0, 2, v13
	v_lshl_add_u64 v[26:27], s[6:7], 0, v[0:1]
	v_add_co_u32_e32 v26, vcc, s17, v26
	global_load_dword v25, v0, s[6:7]
	s_nop 0
	v_addc_co_u32_e32 v27, vcc, 0, v27, vcc
	global_load_dword v129, v[26:27], off
	v_lshlrev_b32_e32 v0, 2, v6
	v_lshl_add_u64 v[28:29], s[6:7], 0, v[0:1]
	v_add_co_u32_e32 v28, vcc, s17, v28
	global_load_dword v26, v0, s[6:7]
	s_nop 0
	v_addc_co_u32_e32 v29, vcc, 0, v29, vcc
	global_load_dword v130, v[28:29], off
	v_lshlrev_b32_e32 v0, 2, v7
	v_lshl_add_u64 v[28:29], s[6:7], 0, v[0:1]
	v_add_co_u32_e32 v28, vcc, s17, v28
	global_load_dword v27, v0, s[6:7]
	s_nop 0
	v_addc_co_u32_e32 v29, vcc, 0, v29, vcc
	global_load_dword v131, v[28:29], off
	v_lshlrev_b32_e32 v0, 2, v8
	v_lshl_add_u64 v[30:31], s[6:7], 0, v[0:1]
	v_add_co_u32_e32 v30, vcc, s17, v30
	global_load_dword v28, v0, s[6:7]
	s_nop 0
	v_addc_co_u32_e32 v31, vcc, 0, v31, vcc
	global_load_dword v132, v[30:31], off
	v_lshlrev_b32_e32 v0, 2, v9
	v_lshl_add_u64 v[30:31], s[6:7], 0, v[0:1]
	v_add_co_u32_e32 v30, vcc, s17, v30
	global_load_dword v29, v0, s[6:7]
	s_nop 0
	v_addc_co_u32_e32 v31, vcc, 0, v31, vcc
	global_load_dword v133, v[30:31], off
	v_lshlrev_b32_e32 v0, 2, v2
	v_lshl_add_u64 v[32:33], s[6:7], 0, v[0:1]
	v_add_co_u32_e32 v32, vcc, s17, v32
	global_load_dword v30, v0, s[6:7]
	s_nop 0
	v_addc_co_u32_e32 v33, vcc, 0, v33, vcc
	global_load_dword v134, v[32:33], off
	v_lshlrev_b32_e32 v0, 2, v3
	v_lshl_add_u64 v[32:33], s[6:7], 0, v[0:1]
	v_add_co_u32_e32 v32, vcc, s17, v32
	global_load_dword v31, v0, s[6:7]
	s_nop 0
	v_addc_co_u32_e32 v33, vcc, 0, v33, vcc
	global_load_dword v135, v[32:33], off
	v_lshlrev_b32_e32 v0, 2, v4
	v_lshl_add_u64 v[136:137], s[6:7], 0, v[0:1]
	v_add_co_u32_e32 v136, vcc, s17, v136
	global_load_dword v32, v0, s[6:7]
	s_nop 0
	v_addc_co_u32_e32 v137, vcc, 0, v137, vcc
	global_load_dword v136, v[136:137], off
	v_lshlrev_b32_e32 v0, 2, v5
	v_lshl_add_u64 v[140:141], s[6:7], 0, v[0:1]
	v_add_co_u32_e32 v140, vcc, s17, v140
	global_load_dword v33, v0, s[6:7]
	s_nop 0
	v_addc_co_u32_e32 v141, vcc, 0, v141, vcc
	global_load_dword v137, v[140:141], off
	s_mov_b32 s17, 0x840000
	global_store_dwordx4 v[120:121], v[14:17], off
	s_nop 1
	v_pk_mul_f32 v[14:15], v[100:101], v[116:117] op_sel_hi:[1,0]
	v_pk_mul_f32 v[16:17], v[104:105], v[116:117] op_sel_hi:[1,0]
	s_waitcnt vmcnt(29)
	v_pk_mul_f32 v[14:15], v[14:15], v[122:123]
	s_waitcnt vmcnt(25)
	v_pk_mul_f32 v[16:17], v[16:17], v[126:127]
	global_store_dwordx4 v[118:119], v[14:17], off
	s_nop 1
	v_add_co_u32_e32 v14, vcc, s17, v118
	s_nop 1
	v_addc_co_u32_e32 v15, vcc, 0, v119, vcc
	global_store_dwordx4 v[14:15], v[18:21], off
	global_store_dwordx4 v[120:121], v[10:13], off offset:16
	s_nop 1
	v_pk_mul_f32 v[10:11], v[102:103], v[116:117] op_sel_hi:[1,0]
	v_pk_mul_f32 v[12:13], v[110:111], v[116:117] op_sel_hi:[1,0]
	s_waitcnt vmcnt(24)
	v_pk_mul_f32 v[10:11], v[10:11], v[124:125]
	s_waitcnt vmcnt(20)
	v_pk_mul_f32 v[12:13], v[12:13], v[128:129]
	global_store_dwordx4 v[118:119], v[10:13], off offset:16
	global_store_dwordx4 v[14:15], v[22:25], off offset:16
	global_store_dwordx4 v[120:121], v[6:9], off offset:32
	s_nop 1
	v_pk_mul_f32 v[6:7], v[112:113], v[116:117] op_sel_hi:[1,0]
	v_pk_mul_f32 v[8:9], v[114:115], v[116:117] op_sel_hi:[1,0]
	s_waitcnt vmcnt(19)
	v_pk_mul_f32 v[6:7], v[6:7], v[130:131]
	s_waitcnt vmcnt(15)
	v_pk_mul_f32 v[8:9], v[8:9], v[132:133]
	global_store_dwordx4 v[118:119], v[6:9], off offset:32
	global_store_dwordx4 v[14:15], v[26:29], off offset:32
	global_store_dwordx4 v[120:121], v[2:5], off offset:48
	s_nop 1
	v_pk_mul_f32 v[2:3], v[106:107], v[116:117] op_sel_hi:[1,0]
	v_pk_mul_f32 v[4:5], v[108:109], v[116:117] op_sel_hi:[1,0]
	s_waitcnt vmcnt(14)
	v_pk_mul_f32 v[2:3], v[2:3], v[134:135]
	s_waitcnt vmcnt(10)
	v_pk_mul_f32 v[4:5], v[4:5], v[136:137]
	global_store_dwordx4 v[118:119], v[2:5], off offset:48
	global_store_dwordx4 v[14:15], v[30:33], off offset:48
	s_branch .LBB0_627

; DEV void attn_item(const Params& p, int item, char* smem) {
;     ...
;   float mrun[2] = {-1e30f, -1e30f}, lrun[2] = {0.f, 0.f};
;   u32x4 rk0, rk1, rv0;
;   const int k0row = tid / 12, k0cc = tid - k0row * 12;
;   const int k1id = 256 + (tid & 127), k1row = k1id / 12, k1cc = k1id - k1row * 12;
;   const bool has_k1 = tid < 128;
;   const int vrow = tid >> 2, vcc = tid & 3;
;   const int ntile = nkeys >> 5;
;   __syncthreads();
;   rk0 = *(const u32x4*)(Kb + (size_t)k0row * 96 + k0cc * 8);
;   rk1 = *(const u32x4*)(Kb + (size_t)k1row * 96 + k1cc * 8);
;   rv0 = *(const u32x4*)(Vb + (size_t)vrow * 8448 + vcc * 8);
;   *(u32x4*)(Ks + k0row * ASTR + k0cc * 8) = rk0;
;   if (has_k1) *(u32x4*)(Ks + k1row * ASTR + k1cc * 8) = rk1;
;   *(uint2*)(Vs + vrow * VSTR + vcc * 8) = make_uint2(rv0[0], rv0[1]);
;   *(uint2*)(Vs + vrow * VSTR + vcc * 8 + 4) = make_uint2(rv0[2], rv0[3]);
;   __syncthreads();
;   if (ntile > 1) {
;     rk0 = *(const u32x4*)(Kb + (size_t)(32 + k0row) * 96 + k0cc * 8);
;     rk1 = *(const u32x4*)(Kb + (size_t)(32 + k1row) * 96 + k1cc * 8);
;     rv0 = *(const u32x4*)(Vb + (size_t)vrow * 8448 + 32 + vcc * 8);
;   }
.LBB0_751:
	s_or_b64 exec, exec, s[14:15]
	s_movk_i32 s15, 0x58
	v_mul_lo_u32 v15, v12, s15
	v_lshl_add_u32 v186, v14, 1, v15
	v_add_u32_e32 v14, 0x3400, v186
	s_waitcnt vmcnt(0)
	ds_write2_b64 v14, v[2:3], v[4:5] offset1:1
	v_lshlrev_b64 v[2:3], 1, v[174:175]
	v_lshl_add_u64 v[4:5], v[8:9], 0, v[2:3]
	s_movk_i32 s14, 0x1000
	v_add_co_u32_e32 v4, vcc, s14, v4
	s_waitcnt lgkmcnt(0)
	s_nop 0
	v_addc_co_u32_e32 v5, vcc, 0, v5, vcc
	s_barrier
	global_load_dwordx4 v[160:163], v[6:7], off offset:64
	global_load_dwordx4 v[164:167], v[4:5], off offset:2048
	v_add_u32_e32 v6, 32, v11
	v_mov_b64_e32 v[4:5], s[12:13]
	s_movk_i32 s14, 0xc0
	v_mad_i64_i32 v[4:5], s[12:13], v6, s14, v[4:5]
	v_lshlrev_b64 v[6:7], 1, v[176:177]
	v_lshl_add_u64 v[4:5], v[4:5], 0, v[6:7]
	global_load_dwordx4 v[168:171], v[4:5], off
	v_mad_i64_i32 v[4:5], s[12:13], v11, s14, 0
	s_movk_i32 s12, 0x4200
	s_nop 0
	v_mad_i64_i32 v[8:9], s[12:13], v12, s12, 0
	v_and_b32_e32 v173, 31, v172
	s_movk_i32 s13, 0xd0
	v_mad_u32_u24 v187, v173, s13, v0
	v_lshlrev_b32_e32 v0, 3, v10
	v_mad_u32_u24 v177, v173, s15, v0
	v_and_b32_e32 v0, 3, v172
	v_lshl_add_u64 v[8:9], s[10:11], 0, v[8:9]
	v_lshlrev_b32_e32 v0, 4, v0
	v_lshl_add_u64 v[8:9], v[8:9], 0, v[0:1]
	s_mov_b32 s10, 0x15555556
	v_lshl_add_u64 v[178:179], s[0:1], 0, v[8:9]
	v_mul_hi_u32 v0, v13, s10
	v_mov_b64_e32 v[8:9], s[8:9]
	v_mad_u64_u32 v[8:9], s[10:11], v0, s14, v[8:9]
	v_lshl_add_u64 v[2:3], v[8:9], 0, v[2:3]
	v_lshl_add_u64 v[180:181], s[2:3], 0, v[2:3]
	v_lshl_add_u64 v[2:3], s[8:9], 0, v[4:5]
	v_lshl_add_u64 v[2:3], v[2:3], 0, v[6:7]
	v_mov_b32_e32 v14, v1
	v_mov_b32_e32 v15, v1
	v_lshlrev_b32_e32 v189, 2, v10
	v_lshl_add_u64 v[182:183], s[2:3], 0, v[2:3]
	v_mov_b32_e32 v0, v1
	v_mov_b32_e32 v2, v1
	v_mov_b32_e32 v3, v1
	v_mov_b32_e32 v4, v1
	v_mov_b32_e32 v5, v1
	v_mov_b32_e32 v6, v1
	v_mov_b32_e32 v7, v1
	v_mov_b32_e32 v8, v1
	v_mov_b32_e32 v9, v1
	v_mov_b32_e32 v10, v1
	v_mov_b32_e32 v11, v1
	v_mov_b32_e32 v12, v1
	v_mov_b32_e32 v13, v1
	v_mov_b64_e32 v[62:63], v[14:15]
	v_mov_b64_e32 v[30:31], v[14:15]
	v_mov_b64_e32 v[78:79], v[14:15]
	v_mov_b64_e32 v[46:47], v[14:15]
	s_mov_b32 s12, 0
	v_mul_u32_u24_e32 v190, 0x58, v173
	s_add_i32 s13, s31, 1
	v_mov_b32_e32 v184, 0
	v_mov_b32_e32 v175, 0xf149f2ca
	v_mov_b64_e32 v[60:61], v[12:13]
	v_mov_b64_e32 v[58:59], v[10:11]
	v_mov_b64_e32 v[56:57], v[8:9]
	v_mov_b64_e32 v[54:55], v[6:7]
	v_mov_b64_e32 v[52:53], v[4:5]
	v_mov_b64_e32 v[50:51], v[2:3]
	v_mov_b64_e32 v[48:49], v[0:1]
	v_mov_b64_e32 v[28:29], v[12:13]
	v_mov_b64_e32 v[26:27], v[10:11]
	v_mov_b64_e32 v[24:25], v[8:9]
	v_mov_b64_e32 v[22:23], v[6:7]
	v_mov_b64_e32 v[20:21], v[4:5]
	v_mov_b64_e32 v[18:19], v[2:3]
	v_mov_b64_e32 v[16:17], v[0:1]
	v_mov_b64_e32 v[76:77], v[12:13]
	v_mov_b64_e32 v[74:75], v[10:11]
	v_mov_b64_e32 v[72:73], v[8:9]
	v_mov_b64_e32 v[70:71], v[6:7]
	v_mov_b64_e32 v[68:69], v[4:5]
	v_mov_b64_e32 v[66:67], v[2:3]
	v_mov_b64_e32 v[64:65], v[0:1]
	v_mov_b64_e32 v[44:45], v[12:13]
	v_mov_b64_e32 v[42:43], v[10:11]
	v_mov_b64_e32 v[40:41], v[8:9]
	v_mov_b64_e32 v[38:39], v[6:7]
	v_mov_b64_e32 v[36:37], v[4:5]
	v_mov_b64_e32 v[34:35], v[2:3]
	v_mov_b64_e32 v[32:33], v[0:1]
	v_mov_b32_e32 v185, 0xf149f2ca
	v_mov_b32_e32 v14, 0
	v_mov_b32_e32 v232, 0xf149f2ca
	v_mov_b32_e32 v234, 0xf149f2ca
	s_branch .LBB0_753

; DEV f32x16 mfma32(bf16x8 a, bf16x8 b, f32x16 c) { return __builtin_amdgcn_mfma_f32_32x32x16_bf16(a, b, c, 0, 0, 0); }
; DEV void attn_item(const Params& p, int item, char* smem) {
;     ...
;   for (int kt = 0; kt < ntile; kt++) {
;     const bf16_t* Kc = Ks + (kt & 1) * (32 * ASTR);
;     const bf16_t* Vc = Vs + (kt & 1) * (64 * VSTR);
;     f32x16 s[2];
; #pragma unroll
;     for (int jt = 0; jt < 2; jt++) {
; #pragma unroll
;       for (int r = 0; r < 16; r++) s[jt][r] = 0.f;
; #pragma unroll
;       for (int ks = 0; ks < 6; ks++) {
;         bf16x8 kf = *(const bf16x8*)(Kc + c31 * ASTR + ks * 16 + hf * 8);
;         s[jt] = mfma32(kf, qf[jt][ks], s[jt]);
;       }
;     }
; #pragma unroll
;     for (int jt = 0; jt < 2; jt++) {
;       float m0 = fmaxf(fmaxf(s[jt][0], s[jt][1]), fmaxf(s[jt][2], s[jt][3]));
;       float m1 = fmaxf(fmaxf(s[jt][4], s[jt][5]), fmaxf(s[jt][6], s[jt][7]));
;       float m2 = fmaxf(fmaxf(s[jt][8], s[jt][9]), fmaxf(s[jt][10], s[jt][11]));
;       float m3 = fmaxf(fmaxf(s[jt][12], s[jt][13]), fmaxf(s[jt][14], s[jt][15]));
;       const float mx = fmaxf(fmaxf(m0, m1), fmaxf(m2, m3));
;       if (__any(mx > mrun[jt])) {
;         const float mxa = fmaxf(mx, __shfl_xor(mx, 32));
;         const float mnew = fmaxf(mrun[jt], mxa);
;         const float alpha = __builtin_amdgcn_exp2f(mrun[jt] - mnew);
;         mrun[jt] = mnew;
;         lrun[jt] *= alpha;
; #pragma unroll
;         for (int dt = 0; dt < 2; dt++)
; #pragma unroll
;           for (int r = 0; r < 16; r++) o[dt][jt][r] *= alpha;
;       }
.LBB0_753:
	s_and_b32 s11, s12, 1
	s_mul_i32 s10, s11, 0x1a00
	v_add_u32_e32 v0, s10, v187
	ds_read_b128 v[2:5], v0
	ds_read_b128 v[6:9], v0 offset:32
	ds_read_b128 v[10:13], v0 offset:64
	ds_read_b128 v[240:243], v0 offset:96
	ds_read_b128 v[244:247], v0 offset:128
	ds_read_b128 v[236:239], v0 offset:160
	s_waitcnt lgkmcnt(5)
	v_mfma_f32_32x32x16_bf16 v[96:111], v[2:5], v[156:159], 0
	s_waitcnt lgkmcnt(4)
	v_mfma_f32_32x32x16_bf16 v[96:111], v[6:9], v[152:155], v[96:111]
	v_mfma_f32_32x32x16_bf16 v[80:95], v[2:5], v[132:135], 0
	s_waitcnt lgkmcnt(3)
	v_mfma_f32_32x32x16_bf16 v[96:111], v[10:13], v[148:151], v[96:111]
	v_mfma_f32_32x32x16_bf16 v[80:95], v[6:9], v[128:131], v[80:95]
	s_waitcnt lgkmcnt(2)
	v_mfma_f32_32x32x16_bf16 v[96:111], v[240:243], v[144:147], v[96:111]
	v_mfma_f32_32x32x16_bf16 v[80:95], v[10:13], v[112:115], v[80:95]
	s_waitcnt lgkmcnt(1)
	v_mfma_f32_32x32x16_bf16 v[96:111], v[244:247], v[140:143], v[96:111]
	v_mfma_f32_32x32x16_bf16 v[80:95], v[240:243], v[116:119], v[80:95]
	s_waitcnt lgkmcnt(0)
	v_mfma_f32_32x32x16_bf16 v[96:111], v[236:239], v[136:139], v[96:111]
	v_mfma_f32_32x32x16_bf16 v[80:95], v[244:247], v[120:123], v[80:95]
	s_nop 10
	v_max3_f32 v0, v96, v97, v98
	v_max3_f32 v2, v99, v100, v101
	v_max3_f32 v3, v102, v103, v104
	v_max3_f32 v4, v105, v106, v107
	v_mfma_f32_32x32x16_bf16 v[80:95], v[236:239], v[124:127], v[80:95]
	v_max3_f32 v5, v108, v109, v110
	v_max3_f32 v0, v0, v2, v111
	v_max3_f32 v3, v3, v4, v5
	v_max_f32_e32 v0, v0, v3
	v_cmp_gt_f32_e32 vcc, v0, v232
	s_cbranch_vccz .LBB0_755
	v_mbcnt_hi_u32_b32 v2, -1, v215
	v_and_b32_e32 v4, 64, v2
	v_xor_b32_e32 v3, 32, v2
	v_add_u32_e32 v4, 64, v4
	v_cmp_lt_i32_e32 vcc, v3, v4
	s_nop 1
	v_cndmask_b32_e32 v2, v2, v3, vcc
	v_lshlrev_b32_e32 v2, 2, v2
	ds_bpermute_b32 v2, v2, v0
	s_waitcnt lgkmcnt(0)
	v_max3_f32 v2, v185, v0, v2
	v_sub_f32_e32 v0, v185, v2
	v_exp_f32_e32 v0, v0
	v_mov_b32_e32 v185, v2
	v_add_f32_e32 v232, 0x41000000, v2
	v_mul_f32_e32 v14, v14, v0
	v_pk_mul_f32 v[46:47], v[46:47], v[0:1] op_sel_hi:[1,0]
	v_pk_mul_f32 v[44:45], v[44:45], v[0:1] op_sel_hi:[1,0]
	v_pk_mul_f32 v[42:43], v[42:43], v[0:1] op_sel_hi:[1,0]
	v_pk_mul_f32 v[40:41], v[40:41], v[0:1] op_sel_hi:[1,0]
	v_pk_mul_f32 v[38:39], v[38:39], v[0:1] op_sel_hi:[1,0]
	v_pk_mul_f32 v[36:37], v[36:37], v[0:1] op_sel_hi:[1,0]
	v_pk_mul_f32 v[34:35], v[34:35], v[0:1] op_sel_hi:[1,0]
	v_pk_mul_f32 v[32:33], v[32:33], v[0:1] op_sel_hi:[1,0]
	v_pk_mul_f32 v[30:31], v[30:31], v[0:1] op_sel_hi:[1,0]
	v_pk_mul_f32 v[28:29], v[28:29], v[0:1] op_sel_hi:[1,0]
	v_pk_mul_f32 v[26:27], v[26:27], v[0:1] op_sel_hi:[1,0]
	v_pk_mul_f32 v[24:25], v[24:25], v[0:1] op_sel_hi:[1,0]
	v_pk_mul_f32 v[22:23], v[22:23], v[0:1] op_sel_hi:[1,0]
	v_pk_mul_f32 v[20:21], v[20:21], v[0:1] op_sel_hi:[1,0]
	v_pk_mul_f32 v[18:19], v[18:19], v[0:1] op_sel_hi:[1,0]
	v_pk_mul_f32 v[16:17], v[16:17], v[0:1] op_sel_hi:[1,0]
.LBB0_755:
	v_sub_f32_e32 v2, v97, v185
	v_exp_f32_e32 v193, v2
	v_sub_f32_e32 v2, v98, v185
	v_exp_f32_e32 v194, v2
	v_sub_f32_e32 v2, v99, v185
	v_exp_f32_e32 v239, v2
	v_sub_f32_e32 v2, v100, v185
	v_exp_f32_e32 v100, v2
	v_sub_f32_e32 v2, v101, v185
	v_exp_f32_e32 v101, v2
	v_sub_f32_e32 v2, v102, v185
	v_exp_f32_e32 v102, v2
	v_sub_f32_e32 v2, v103, v185
	v_exp_f32_e32 v240, v2
	v_sub_f32_e32 v2, v104, v185
	v_exp_f32_e32 v103, v2
	v_sub_f32_e32 v2, v105, v185
	v_exp_f32_e32 v104, v2
	v_sub_f32_e32 v2, v106, v185
	v_exp_f32_e32 v105, v2
	v_sub_f32_e32 v2, v107, v185
	v_exp_f32_e32 v106, v2
	v_sub_f32_e32 v2, v108, v185
	s_mulk_i32 s11, 0x1600
	v_exp_f32_e32 v107, v2
	v_sub_f32_e32 v2, v109, v185
	v_exp_f32_e32 v108, v2
	v_sub_f32_e32 v2, v110, v185
	v_add_u32_e32 v10, s11, v177
	v_exp_f32_e32 v109, v2
	v_sub_f32_e32 v2, v111, v185
	v_add_u32_e32 v6, 0x3000, v10
	v_add_u32_e32 v15, 0x3800, v10
	v_exp_f32_e32 v110, v2
	ds_read2_b64 v[2:5], v6 offset0:128 offset1:130
	ds_read2_b64 v[6:9], v6 offset0:132 offset1:134
	ds_read2_b64 v[10:13], v15 offset0:224 offset1:226
	v_sub_f32_e32 v0, v96, v185
	v_exp_f32_e32 v0, v0
	v_cvt_pk_bf16_f32 v97, v194, v239
	v_cvt_pk_bf16_f32 v98, v100, v101
	v_cvt_pk_bf16_f32 v99, v102, v240
	v_cvt_pk_bf16_f32 v96, v0, v193
	v_max3_f32 v111, v80, v81, v82
	v_cvt_pk_bf16_f32 v242, v103, v104
	s_waitcnt lgkmcnt(2)
	v_mfma_f32_32x32x16_bf16 v[32:47], v[2:5], v[96:99], v[32:47]
	v_cvt_pk_bf16_f32 v243, v105, v106
	v_cvt_pk_bf16_f32 v244, v107, v108
	v_cvt_pk_bf16_f32 v245, v109, v110
	v_max3_f32 v192, v83, v84, v85
	v_max3_f32 v236, v86, v87, v88
	v_max3_f32 v237, v89, v90, v91
	v_max3_f32 v238, v92, v93, v94
	s_waitcnt lgkmcnt(0)
	v_mfma_f32_32x32x16_bf16 v[16:31], v[10:13], v[96:99], v[16:31]
	ds_read2_b64 v[96:99], v15 offset0:228 offset1:230
	v_max3_f32 v15, v111, v192, v95
	v_max3_f32 v236, v236, v237, v238
	v_mfma_f32_32x32x16_bf16 v[32:47], v[6:9], v[242:245], v[32:47]
	s_nop 1
	v_max_f32_e32 v15, v15, v236
	s_waitcnt lgkmcnt(0)
	v_mfma_f32_32x32x16_bf16 v[16:31], v[96:99], v[242:245], v[16:31]
	v_cmp_gt_f32_e32 vcc, v15, v234
	s_cbranch_vccz .LBB0_757
	v_mbcnt_hi_u32_b32 v111, -1, v215
	v_and_b32_e32 v236, 64, v111
	v_xor_b32_e32 v192, 32, v111
	v_add_u32_e32 v236, 64, v236
	v_cmp_lt_i32_e32 vcc, v192, v236
	s_nop 1
	v_cndmask_b32_e32 v111, v111, v192, vcc
	v_lshlrev_b32_e32 v111, 2, v111
	ds_bpermute_b32 v111, v111, v15
	s_waitcnt lgkmcnt(0)
	v_max3_f32 v15, v175, v15, v111
	v_sub_f32_e32 v111, v175, v15
	v_exp_f32_e32 v192, v111
	v_mov_b32_e32 v175, v15
	v_add_f32_e32 v234, 0x41000000, v15
	v_mul_f32_e32 v184, v184, v192
	v_pk_mul_f32 v[78:79], v[78:79], v[192:193] op_sel_hi:[1,0]
	v_pk_mul_f32 v[76:77], v[76:77], v[192:193] op_sel_hi:[1,0]
	v_pk_mul_f32 v[74:75], v[74:75], v[192:193] op_sel_hi:[1,0]
	v_pk_mul_f32 v[72:73], v[72:73], v[192:193] op_sel_hi:[1,0]
	v_pk_mul_f32 v[70:71], v[70:71], v[192:193] op_sel_hi:[1,0]
	v_pk_mul_f32 v[68:69], v[68:69], v[192:193] op_sel_hi:[1,0]
	v_pk_mul_f32 v[66:67], v[66:67], v[192:193] op_sel_hi:[1,0]
	v_pk_mul_f32 v[64:65], v[64:65], v[192:193] op_sel_hi:[1,0]
	v_pk_mul_f32 v[62:63], v[62:63], v[192:193] op_sel_hi:[1,0]
	v_pk_mul_f32 v[60:61], v[60:61], v[192:193] op_sel_hi:[1,0]
	v_pk_mul_f32 v[58:59], v[58:59], v[192:193] op_sel_hi:[1,0]
	v_pk_mul_f32 v[56:57], v[56:57], v[192:193] op_sel_hi:[1,0]
	v_pk_mul_f32 v[54:55], v[54:55], v[192:193] op_sel_hi:[1,0]
	v_pk_mul_f32 v[52:53], v[52:53], v[192:193] op_sel_hi:[1,0]
	v_pk_mul_f32 v[50:51], v[50:51], v[192:193] op_sel_hi:[1,0]
	v_pk_mul_f32 v[48:49], v[48:49], v[192:193] op_sel_hi:[1,0]
